# GEMM K-loops: per-segment s_setprio toggles replaced by one static priority raise for the wave half that runs the extra ALIGN barrier
# speedup vs baseline: 1.0190x; 1.0050x over previous
; #define PG8_STAGE(bufoff, gbase, voff) do { _Pragma("unroll") for (int _i = 0; _i < 2; ++_i) \
;         __builtin_amdgcn_global_load_lds((const unsigned*)((const char*)(gbase) + (voff)[_i]), (PG8_LAS unsigned*)(lds + (bufoff) + ldsw + _i * 8192), 16, 0, 0); } while (0)
; #define PG8_LDA(dst, b, h) do { _Pragma("unroll") for (int m = 0; m < 4; ++m) _Pragma("unroll") for (int k = 0; k < 2; ++k) dst[m][k] = *(const PG8_LAS bf16x8*)(lds + PG8_SA(b, h) + aoff + m * 2048 + k * 1024); } while (0)
; #define PG8_LDB(dst, b, h) do { _Pragma("unroll") for (int n = 0; n < 2; ++n) _Pragma("unroll") for (int k = 0; k < 2; ++k) dst[n][k] = *(const PG8_LAS bf16x8*)(lds + PG8_SB(b, h) + boff + n * 2048 + k * 1024); } while (0)
; #define PG8_MMA(ai, bj, At, Bt) do { __builtin_amdgcn_s_setprio(1); _Pragma("unroll") for (int m = 0; m < 4; ++m) _Pragma("unroll") for (int n = 0; n < 2; ++n) _Pragma("unroll") for (int k = 0; k < 2; ++k) \
;         acc[ai][bj][m][n] = __builtin_amdgcn_mfma_f32_16x16x32_bf16(Bt[n][k], At[m][k], acc[ai][bj][m][n], 0, 0, 0); __builtin_amdgcn_s_setprio(0); } while (0)
; #define PG8_WAIT_V(n) asm volatile("s_waitcnt vmcnt(" #n ")" ::: "memory")
; #define PG8_WAIT_L(n) asm volatile("s_waitcnt lgkmcnt(" #n ")" ::: "memory")
; template <class Epi, class Sched, bool ALIGN_EPI = false, bool SP2 = false>
; __device__ __forceinline__ void gemm_phase(PG8_LAS unsigned char* lds, const Gemm g, const Sched& S, const Epi& E, const int tid) {
;     ...
;             const bool last = (t == nt - 2);
;             const char* a1 = cA + (size_t)(t + 1) * kstep;
;             const char* a2 = last ? nA : cA + (size_t)(t + 2) * kstep; const char* b2 = last ? nB : cB + (size_t)(t + 2) * kstep;
;             const char* a3 = a2 + kstep; const char* b3 = b2 + kstep;
;             if (last && has_next) S.a_ready(nxt);
;             if constexpr (SP2) {
;             PG8_LDB(B0, 0, 0); PG8_LDB(B1, 0, 1); PG8_SCHED; PG8_LDA(At, 0, 0); PG8_STAGE(PG8_SA(1, 1), a1 + hstepA, voffA);
;             PG8_WAIT_V(8); PG8_WAIT_L(0); PG8_BAR; PG8_MMA(0, 0, At, B0); PG8_MMA(0, 1, At, B1); PG8_BAR; PG8_SCHED;
;             PG8_LDA(At, 0, 1); PG8_STAGE(PG8_SB(0, 0), b2, voffB); PG8_STAGE(PG8_SB(0, 1), b2 + hstep, voffB); PG8_STAGE(PG8_SA(0, 0), a2, voffA);
;             PG8_WAIT_V(8); PG8_WAIT_L(0); PG8_BAR; PG8_MMA(1, 0, At, B0); PG8_MMA(1, 1, At, B1); PG8_BAR; PG8_SCHED;
.LBB0_279:
	s_cmp_lg_u64 s[12:13], 0
	s_cbranch_scc0 .Lsp_0
	s_setprio 1
.Lsp_0:
	ds_read_b128 v[144:147], v154
	ds_read_b128 v[148:151], v154 offset:1024
	ds_read_b128 v[160:163], v154 offset:2048
	ds_read_b128 v[164:167], v154 offset:3072
	ds_read_b128 v[168:171], v155
	ds_read_b128 v[172:175], v155 offset:1024
	ds_read_b128 v[176:179], v155 offset:2048
	ds_read_b128 v[180:183], v155 offset:3072
	s_add_u32 s26, s24, 0xfffc0080
	s_addc_u32 s27, s25, -1
	s_cmp_eq_u32 s58, 12
	s_cselect_b32 s29, s17, s27
	s_cselect_b32 s28, s54, s26
	s_cselect_b32 s27, s15, s57
	s_cselect_b32 s26, s55, s56
	v_lshl_add_u64 v[196:197], s[24:25], 0, v[136:137]
	s_add_i32 m0, s39, 0xc000
	ds_read_b128 v[184:187], v156
	ds_read_b128 v[188:191], v156 offset:1024
	ds_read_b128 v[192:195], v156 offset:2048
	ds_read_b128 v[200:203], v156 offset:3072
	ds_read_b128 v[204:207], v156 offset:4096
	ds_read_b128 v[208:211], v156 offset:5120
	ds_read_b128 v[212:215], v156 offset:6144
	ds_read_b128 v[216:219], v156 offset:7168
	global_load_lds_dwordx4 v[196:197], off
	v_lshl_add_u64 v[196:197], s[24:25], 0, v[138:139]
	s_add_i32 m0, s39, 0xe000
	s_nop 0
	global_load_lds_dwordx4 v[196:197], off
	s_waitcnt vmcnt(8)
	s_waitcnt lgkmcnt(0)
	s_barrier
	s_waitcnt lgkmcnt(0)
	v_mfma_f32_16x16x32_bf16 v[124:127], v[144:147], v[184:187], v[124:127]
	v_mfma_f32_16x16x32_bf16 v[120:123], v[160:163], v[184:187], v[120:123]
	v_mfma_f32_16x16x32_bf16 v[108:111], v[144:147], v[192:195], v[108:111]
	v_mfma_f32_16x16x32_bf16 v[104:107], v[160:163], v[192:195], v[104:107]
	v_mfma_f32_16x16x32_bf16 v[92:95], v[144:147], v[204:207], v[92:95]
	v_mfma_f32_16x16x32_bf16 v[88:91], v[160:163], v[204:207], v[88:91]
	v_mfma_f32_16x16x32_bf16 v[76:79], v[144:147], v[212:215], v[76:79]
	v_mfma_f32_16x16x32_bf16 v[72:75], v[160:163], v[212:215], v[72:75]
	v_mfma_f32_16x16x32_bf16 v[124:127], v[148:151], v[188:191], v[124:127]
	v_mfma_f32_16x16x32_bf16 v[120:123], v[164:167], v[188:191], v[120:123]
	v_mfma_f32_16x16x32_bf16 v[108:111], v[148:151], v[200:203], v[108:111]
	v_mfma_f32_16x16x32_bf16 v[104:107], v[164:167], v[200:203], v[104:107]
	v_mfma_f32_16x16x32_bf16 v[92:95], v[148:151], v[208:211], v[92:95]
	v_mfma_f32_16x16x32_bf16 v[88:91], v[164:167], v[208:211], v[88:91]
	v_mfma_f32_16x16x32_bf16 v[76:79], v[148:151], v[216:219], v[76:79]
	v_mfma_f32_16x16x32_bf16 v[72:75], v[164:167], v[216:219], v[72:75]
	v_mfma_f32_16x16x32_bf16 v[116:119], v[168:171], v[184:187], v[116:119]
	v_mfma_f32_16x16x32_bf16 v[112:115], v[176:179], v[184:187], v[112:115]
	v_mfma_f32_16x16x32_bf16 v[100:103], v[168:171], v[192:195], v[100:103]
	v_mfma_f32_16x16x32_bf16 v[96:99], v[176:179], v[192:195], v[96:99]
	v_mfma_f32_16x16x32_bf16 v[84:87], v[168:171], v[204:207], v[84:87]
	v_mfma_f32_16x16x32_bf16 v[80:83], v[176:179], v[204:207], v[80:83]
	v_mfma_f32_16x16x32_bf16 v[68:71], v[168:171], v[212:215], v[68:71]
	v_mfma_f32_16x16x32_bf16 v[64:67], v[176:179], v[212:215], v[64:67]
	v_mfma_f32_16x16x32_bf16 v[116:119], v[172:175], v[188:191], v[116:119]
	v_mfma_f32_16x16x32_bf16 v[112:115], v[180:183], v[188:191], v[112:115]
	v_mfma_f32_16x16x32_bf16 v[100:103], v[172:175], v[200:203], v[100:103]
	v_mfma_f32_16x16x32_bf16 v[96:99], v[180:183], v[200:203], v[96:99]
	v_mfma_f32_16x16x32_bf16 v[84:87], v[172:175], v[208:211], v[84:87]
	v_mfma_f32_16x16x32_bf16 v[80:83], v[180:183], v[208:211], v[80:83]
	v_mfma_f32_16x16x32_bf16 v[68:71], v[172:175], v[216:219], v[68:71]
	v_mfma_f32_16x16x32_bf16 v[64:67], v[180:183], v[216:219], v[64:67]
	s_barrier
	s_mov_b32 m0, s23
	v_lshl_add_u64 v[196:197], s[26:27], 0, v[132:133]
	s_add_u32 s60, s26, 0x40000
	ds_read_b128 v[184:187], v156 offset:16384
	ds_read_b128 v[188:191], v156 offset:17408
	ds_read_b128 v[192:195], v156 offset:18432
	ds_read_b128 v[200:203], v156 offset:19456
	ds_read_b128 v[204:207], v156 offset:20480
	ds_read_b128 v[208:211], v156 offset:21504
	ds_read_b128 v[212:215], v156 offset:22528
	ds_read_b128 v[216:219], v156 offset:23552
	global_load_lds_dwordx4 v[196:197], off
	v_lshl_add_u64 v[220:221], s[26:27], 0, v[128:129]
	s_mov_b32 m0, s36
	s_addc_u32 s61, s27, 0
	global_load_lds_dwordx4 v[220:221], off
	v_lshl_add_u64 v[222:223], s[60:61], 0, v[132:133]
	s_mov_b32 m0, s37
	v_lshl_add_u64 v[224:225], s[28:29], 0, v[130:131]
	global_load_lds_dwordx4 v[222:223], off
	v_lshl_add_u64 v[222:223], s[60:61], 0, v[128:129]
	s_mov_b32 m0, s38
	s_nop 0
	global_load_lds_dwordx4 v[222:223], off
	v_lshl_add_u64 v[222:223], s[28:29], 0, v[134:135]
	s_mov_b32 m0, s39
	s_nop 0
	global_load_lds_dwordx4 v[222:223], off
	s_mov_b32 m0, s40
	s_nop 0
	global_load_lds_dwordx4 v[224:225], off
	s_waitcnt vmcnt(8)
	s_waitcnt lgkmcnt(0)
	s_barrier
; #define PG8_STAGE(bufoff, gbase, voff) do { _Pragma("unroll") for (int _i = 0; _i < 2; ++_i) \
;         __builtin_amdgcn_global_load_lds((const unsigned*)((const char*)(gbase) + (voff)[_i]), (PG8_LAS unsigned*)(lds + (bufoff) + ldsw + _i * 8192), 16, 0, 0); } while (0)
; #define PG8_LDA(dst, b, h) do { _Pragma("unroll") for (int m = 0; m < 4; ++m) _Pragma("unroll") for (int k = 0; k < 2; ++k) dst[m][k] = *(const PG8_LAS bf16x8*)(lds + PG8_SA(b, h) + aoff + m * 2048 + k * 1024); } while (0)
; #define PG8_LDB(dst, b, h) do { _Pragma("unroll") for (int n = 0; n < 2; ++n) _Pragma("unroll") for (int k = 0; k < 2; ++k) dst[n][k] = *(const PG8_LAS bf16x8*)(lds + PG8_SB(b, h) + boff + n * 2048 + k * 1024); } while (0)
; #define PG8_MMA(ai, bj, At, Bt) do { __builtin_amdgcn_s_setprio(1); _Pragma("unroll") for (int m = 0; m < 4; ++m) _Pragma("unroll") for (int n = 0; n < 2; ++n) _Pragma("unroll") for (int k = 0; k < 2; ++k) \
;         acc[ai][bj][m][n] = __builtin_amdgcn_mfma_f32_16x16x32_bf16(Bt[n][k], At[m][k], acc[ai][bj][m][n], 0, 0, 0); __builtin_amdgcn_s_setprio(0); } while (0)
; #define PG8_WAIT_V(n) asm volatile("s_waitcnt vmcnt(" #n ")" ::: "memory")
; #define PG8_WAIT_L(n) asm volatile("s_waitcnt lgkmcnt(" #n ")" ::: "memory")
; #define PG8_BAR __builtin_amdgcn_s_barrier()
; #define PG8_SCHED __builtin_amdgcn_sched_barrier(0)
; template <class Epi, class Sched, bool ALIGN_EPI = false, bool SP2 = false>
; __device__ __forceinline__ void gemm_phase(PG8_LAS unsigned char* lds, const Gemm g, const Sched& S, const Epi& E, const int tid) {
;     ...
;             PG8_WAIT_V(8); PG8_WAIT_L(0); PG8_BAR; PG8_MMA(1, 0, At, B0); PG8_MMA(1, 1, At, B1); PG8_BAR; PG8_SCHED;
;             PG8_LDB(B0, 1, 0); PG8_LDB(B1, 1, 1); PG8_SCHED; PG8_LDA(At, 1, 0); PG8_STAGE(PG8_SA(0, 1), a2 + hstepA, voffA);
;             PG8_WAIT_V(8); PG8_WAIT_L(0); PG8_BAR; PG8_MMA(0, 0, At, B0); PG8_MMA(0, 1, At, B1); PG8_BAR; PG8_SCHED;
	s_waitcnt lgkmcnt(0)
	v_mfma_f32_16x16x32_bf16 v[60:63], v[144:147], v[184:187], v[60:63]
	v_mfma_f32_16x16x32_bf16 v[56:59], v[160:163], v[184:187], v[56:59]
	v_mfma_f32_16x16x32_bf16 v[44:47], v[144:147], v[192:195], v[44:47]
	v_mfma_f32_16x16x32_bf16 v[40:43], v[160:163], v[192:195], v[40:43]
	v_mfma_f32_16x16x32_bf16 v[28:31], v[144:147], v[204:207], v[28:31]
	v_mfma_f32_16x16x32_bf16 v[24:27], v[160:163], v[204:207], v[24:27]
	v_mfma_f32_16x16x32_bf16 v[12:15], v[144:147], v[212:215], v[12:15]
	v_mfma_f32_16x16x32_bf16 v[8:11], v[160:163], v[212:215], v[8:11]
	v_mfma_f32_16x16x32_bf16 v[60:63], v[148:151], v[188:191], v[60:63]
	v_mfma_f32_16x16x32_bf16 v[56:59], v[164:167], v[188:191], v[56:59]
	v_mfma_f32_16x16x32_bf16 v[44:47], v[148:151], v[200:203], v[44:47]
	v_mfma_f32_16x16x32_bf16 v[40:43], v[164:167], v[200:203], v[40:43]
	v_mfma_f32_16x16x32_bf16 v[28:31], v[148:151], v[208:211], v[28:31]
	v_mfma_f32_16x16x32_bf16 v[24:27], v[164:167], v[208:211], v[24:27]
	v_mfma_f32_16x16x32_bf16 v[12:15], v[148:151], v[216:219], v[12:15]
	v_mfma_f32_16x16x32_bf16 v[8:11], v[164:167], v[216:219], v[8:11]
	v_mfma_f32_16x16x32_bf16 v[52:55], v[168:171], v[184:187], v[52:55]
	v_mfma_f32_16x16x32_bf16 v[48:51], v[176:179], v[184:187], v[48:51]
	v_mfma_f32_16x16x32_bf16 v[36:39], v[168:171], v[192:195], v[36:39]
	v_mfma_f32_16x16x32_bf16 v[32:35], v[176:179], v[192:195], v[32:35]
	v_mfma_f32_16x16x32_bf16 v[20:23], v[168:171], v[204:207], v[20:23]
	v_mfma_f32_16x16x32_bf16 v[16:19], v[176:179], v[204:207], v[16:19]
	v_mfma_f32_16x16x32_bf16 v[4:7], v[168:171], v[212:215], v[4:7]
	v_mfma_f32_16x16x32_bf16 v[0:3], v[176:179], v[212:215], v[0:3]
	v_mfma_f32_16x16x32_bf16 v[52:55], v[172:175], v[188:191], v[52:55]
	v_mfma_f32_16x16x32_bf16 v[48:51], v[180:183], v[188:191], v[48:51]
	v_mfma_f32_16x16x32_bf16 v[36:39], v[172:175], v[200:203], v[36:39]
	v_mfma_f32_16x16x32_bf16 v[32:35], v[180:183], v[200:203], v[32:35]
	v_mfma_f32_16x16x32_bf16 v[20:23], v[172:175], v[208:211], v[20:23]
	v_mfma_f32_16x16x32_bf16 v[16:19], v[180:183], v[208:211], v[16:19]
	v_mfma_f32_16x16x32_bf16 v[4:7], v[172:175], v[216:219], v[4:7]
	v_mfma_f32_16x16x32_bf16 v[0:3], v[180:183], v[216:219], v[0:3]
	s_barrier
	ds_read_b128 v[144:147], v157
	ds_read_b128 v[148:151], v157 offset:1024
	ds_read_b128 v[160:163], v157 offset:2048
	ds_read_b128 v[164:167], v157 offset:3072
	ds_read_b128 v[168:171], v158
	ds_read_b128 v[172:175], v158 offset:1024
	ds_read_b128 v[176:179], v158 offset:2048
	ds_read_b128 v[180:183], v158 offset:3072
	s_add_u32 s28, s28, 0x40000
	s_addc_u32 s29, s29, 0
	s_mov_b32 m0, s41
	v_lshl_add_u64 v[226:227], s[28:29], 0, v[134:135]
	ds_read_b128 v[184:187], v156 offset:32768
	ds_read_b128 v[188:191], v156 offset:33792
	ds_read_b128 v[192:195], v156 offset:34816
	ds_read_b128 v[200:203], v156 offset:35840
	ds_read_b128 v[204:207], v156 offset:36864
	ds_read_b128 v[208:211], v156 offset:37888
	ds_read_b128 v[212:215], v156 offset:38912
	ds_read_b128 v[216:219], v156 offset:39936
	global_load_lds_dwordx4 v[226:227], off
	v_lshl_add_u64 v[226:227], s[28:29], 0, v[130:131]
	s_mov_b32 m0, s42
	s_nop 0
	global_load_lds_dwordx4 v[226:227], off
	s_waitcnt vmcnt(8)
	s_waitcnt lgkmcnt(0)
	s_barrier
	s_waitcnt lgkmcnt(0)
	v_mfma_f32_16x16x32_bf16 v[124:127], v[144:147], v[184:187], v[124:127]
	v_mfma_f32_16x16x32_bf16 v[120:123], v[160:163], v[184:187], v[120:123]
	v_mfma_f32_16x16x32_bf16 v[108:111], v[144:147], v[192:195], v[108:111]
	v_mfma_f32_16x16x32_bf16 v[104:107], v[160:163], v[192:195], v[104:107]
	v_mfma_f32_16x16x32_bf16 v[92:95], v[144:147], v[204:207], v[92:95]
	v_mfma_f32_16x16x32_bf16 v[88:91], v[160:163], v[204:207], v[88:91]
	v_mfma_f32_16x16x32_bf16 v[76:79], v[144:147], v[212:215], v[76:79]
	v_mfma_f32_16x16x32_bf16 v[72:75], v[160:163], v[212:215], v[72:75]
	v_mfma_f32_16x16x32_bf16 v[124:127], v[148:151], v[188:191], v[124:127]
	v_mfma_f32_16x16x32_bf16 v[120:123], v[164:167], v[188:191], v[120:123]
	v_mfma_f32_16x16x32_bf16 v[108:111], v[148:151], v[200:203], v[108:111]
	v_mfma_f32_16x16x32_bf16 v[104:107], v[164:167], v[200:203], v[104:107]
	v_mfma_f32_16x16x32_bf16 v[92:95], v[148:151], v[208:211], v[92:95]
	v_mfma_f32_16x16x32_bf16 v[88:91], v[164:167], v[208:211], v[88:91]
	v_mfma_f32_16x16x32_bf16 v[76:79], v[148:151], v[216:219], v[76:79]
	v_mfma_f32_16x16x32_bf16 v[72:75], v[164:167], v[216:219], v[72:75]
	v_mfma_f32_16x16x32_bf16 v[116:119], v[168:171], v[184:187], v[116:119]
	v_mfma_f32_16x16x32_bf16 v[112:115], v[176:179], v[184:187], v[112:115]
	v_mfma_f32_16x16x32_bf16 v[100:103], v[168:171], v[192:195], v[100:103]
	v_mfma_f32_16x16x32_bf16 v[96:99], v[176:179], v[192:195], v[96:99]
	v_mfma_f32_16x16x32_bf16 v[84:87], v[168:171], v[204:207], v[84:87]
	v_mfma_f32_16x16x32_bf16 v[80:83], v[176:179], v[204:207], v[80:83]
	v_mfma_f32_16x16x32_bf16 v[68:71], v[168:171], v[212:215], v[68:71]
	v_mfma_f32_16x16x32_bf16 v[64:67], v[176:179], v[212:215], v[64:67]
	v_mfma_f32_16x16x32_bf16 v[116:119], v[172:175], v[188:191], v[116:119]
	v_mfma_f32_16x16x32_bf16 v[112:115], v[180:183], v[188:191], v[112:115]
	v_mfma_f32_16x16x32_bf16 v[100:103], v[172:175], v[200:203], v[100:103]
	v_mfma_f32_16x16x32_bf16 v[96:99], v[180:183], v[200:203], v[96:99]
	v_mfma_f32_16x16x32_bf16 v[84:87], v[172:175], v[208:211], v[84:87]
	v_mfma_f32_16x16x32_bf16 v[80:83], v[180:183], v[208:211], v[80:83]
	v_mfma_f32_16x16x32_bf16 v[68:71], v[172:175], v[216:219], v[68:71]
	v_mfma_f32_16x16x32_bf16 v[64:67], v[180:183], v[216:219], v[64:67]
	s_barrier
; #define PG8_STAGE(bufoff, gbase, voff) do { _Pragma("unroll") for (int _i = 0; _i < 2; ++_i) \
;         __builtin_amdgcn_global_load_lds((const unsigned*)((const char*)(gbase) + (voff)[_i]), (PG8_LAS unsigned*)(lds + (bufoff) + ldsw + _i * 8192), 16, 0, 0); } while (0)
; #define PG8_LDA(dst, b, h) do { _Pragma("unroll") for (int m = 0; m < 4; ++m) _Pragma("unroll") for (int k = 0; k < 2; ++k) dst[m][k] = *(const PG8_LAS bf16x8*)(lds + PG8_SA(b, h) + aoff + m * 2048 + k * 1024); } while (0)
; #define PG8_MMA(ai, bj, At, Bt) do { __builtin_amdgcn_s_setprio(1); _Pragma("unroll") for (int m = 0; m < 4; ++m) _Pragma("unroll") for (int n = 0; n < 2; ++n) _Pragma("unroll") for (int k = 0; k < 2; ++k) \
;         acc[ai][bj][m][n] = __builtin_amdgcn_mfma_f32_16x16x32_bf16(Bt[n][k], At[m][k], acc[ai][bj][m][n], 0, 0, 0); __builtin_amdgcn_s_setprio(0); } while (0)
; #define PG8_WAIT_V(n) asm volatile("s_waitcnt vmcnt(" #n ")" ::: "memory")
; #define PG8_WAIT_L(n) asm volatile("s_waitcnt lgkmcnt(" #n ")" ::: "memory")
; #define PG8_BAR __builtin_amdgcn_s_barrier()
; #define PG8_SCHED __builtin_amdgcn_sched_barrier(0)
; __device__ __forceinline__ float ss_scale(const u64* ss, int row) { return __builtin_amdgcn_rsqf((float)ss[row] * (1.f / 4294967296.f / 1024.f) + EPS); }
; template <class Epi, class Sched, bool ALIGN_EPI = false, bool SP2 = false>
; __device__ __forceinline__ void gemm_phase(PG8_LAS unsigned char* lds, const Gemm g, const Sched& S, const Epi& E, const int tid) {
;     ...
;             PG8_LDA(At, 1, 1); PG8_STAGE(PG8_SB(1, 0), b3, voffB); PG8_STAGE(PG8_SB(1, 1), b3 + hstep, voffB); PG8_STAGE(PG8_SA(1, 0), a3, voffA);
;             PG8_WAIT_V(8); PG8_WAIT_L(0); PG8_BAR; PG8_MMA(1, 0, At, B0); PG8_MMA(1, 1, At, B1); PG8_BAR; PG8_SCHED;
;     __device__ __forceinline__ void operator()(const f32x4 (&acc)[2][2][4][2], const pg8::Unit& u, int wr, int wc, int fr, int fq) const {
;         const int row0 = u.pm * 256 + wr * 64 + fr, col0 = u.pn * 128 + wc * 32 + 8 * fq;
; #pragma unroll
;         for (int ai = 0; ai < 2; ++ai)
; #pragma unroll
;             for (int m = 0; m < 4; ++m) {
;                 const int row = row0 + ai * 128 + m * 16;
;                 float s = ss_scale(ss, row);
	s_mov_b32 m0, s45
	v_lshl_add_u64 v[196:197], v[196:197], 0, s[10:11]
	s_add_u32 s26, s26, 0x40080
	ds_read_b128 v[184:187], v156 offset:49152
	ds_read_b128 v[188:191], v156 offset:50176
	ds_read_b128 v[192:195], v156 offset:51200
	ds_read_b128 v[200:203], v156 offset:52224
	ds_read_b128 v[204:207], v156 offset:53248
	ds_read_b128 v[208:211], v156 offset:54272
	ds_read_b128 v[212:215], v156 offset:55296
	ds_read_b128 v[216:219], v156 offset:56320
	global_load_lds_dwordx4 v[196:197], off
	v_lshl_add_u64 v[196:197], v[220:221], 0, s[10:11]
	s_mov_b32 m0, s46
	s_addc_u32 s27, s27, 0
	global_load_lds_dwordx4 v[196:197], off
	v_lshl_add_u64 v[196:197], s[26:27], 0, v[132:133]
	s_mov_b32 m0, s49
	s_nop 0
	global_load_lds_dwordx4 v[196:197], off
	v_lshl_add_u64 v[196:197], s[26:27], 0, v[128:129]
	s_mov_b32 m0, s50
	s_nop 0
	global_load_lds_dwordx4 v[196:197], off
	v_lshl_add_u64 v[196:197], v[222:223], 0, s[10:11]
	s_mov_b32 m0, s47
	s_nop 0
	global_load_lds_dwordx4 v[196:197], off
	v_lshl_add_u64 v[196:197], v[224:225], 0, s[10:11]
	s_mov_b32 m0, s48
	s_nop 0
	global_load_lds_dwordx4 v[196:197], off
	s_waitcnt vmcnt(8)
	s_waitcnt lgkmcnt(0)
	s_barrier
	s_waitcnt lgkmcnt(0)
	v_mfma_f32_16x16x32_bf16 v[60:63], v[144:147], v[184:187], v[60:63]
	v_mfma_f32_16x16x32_bf16 v[56:59], v[160:163], v[184:187], v[56:59]
	v_mfma_f32_16x16x32_bf16 v[44:47], v[144:147], v[192:195], v[44:47]
	v_mfma_f32_16x16x32_bf16 v[40:43], v[160:163], v[192:195], v[40:43]
	v_mfma_f32_16x16x32_bf16 v[28:31], v[144:147], v[204:207], v[28:31]
	v_mfma_f32_16x16x32_bf16 v[24:27], v[160:163], v[204:207], v[24:27]
	v_mfma_f32_16x16x32_bf16 v[12:15], v[144:147], v[212:215], v[12:15]
	v_mfma_f32_16x16x32_bf16 v[8:11], v[160:163], v[212:215], v[8:11]
	v_mfma_f32_16x16x32_bf16 v[60:63], v[148:151], v[188:191], v[60:63]
	v_mfma_f32_16x16x32_bf16 v[56:59], v[164:167], v[188:191], v[56:59]
	v_mfma_f32_16x16x32_bf16 v[44:47], v[148:151], v[200:203], v[44:47]
	v_mfma_f32_16x16x32_bf16 v[40:43], v[164:167], v[200:203], v[40:43]
	v_mfma_f32_16x16x32_bf16 v[28:31], v[148:151], v[208:211], v[28:31]
	v_mfma_f32_16x16x32_bf16 v[24:27], v[164:167], v[208:211], v[24:27]
	v_mfma_f32_16x16x32_bf16 v[12:15], v[148:151], v[216:219], v[12:15]
	v_mfma_f32_16x16x32_bf16 v[8:11], v[164:167], v[216:219], v[8:11]
	v_mfma_f32_16x16x32_bf16 v[52:55], v[168:171], v[184:187], v[52:55]
	v_mfma_f32_16x16x32_bf16 v[48:51], v[176:179], v[184:187], v[48:51]
	v_mfma_f32_16x16x32_bf16 v[36:39], v[168:171], v[192:195], v[36:39]
	v_mfma_f32_16x16x32_bf16 v[32:35], v[176:179], v[192:195], v[32:35]
	v_mfma_f32_16x16x32_bf16 v[20:23], v[168:171], v[204:207], v[20:23]
	v_mfma_f32_16x16x32_bf16 v[16:19], v[176:179], v[204:207], v[16:19]
	v_mfma_f32_16x16x32_bf16 v[4:7], v[168:171], v[212:215], v[4:7]
	v_mfma_f32_16x16x32_bf16 v[0:3], v[176:179], v[212:215], v[0:3]
	v_mfma_f32_16x16x32_bf16 v[52:55], v[172:175], v[188:191], v[52:55]
	v_mfma_f32_16x16x32_bf16 v[48:51], v[180:183], v[188:191], v[48:51]
	v_mfma_f32_16x16x32_bf16 v[36:39], v[172:175], v[200:203], v[36:39]
	v_mfma_f32_16x16x32_bf16 v[32:35], v[180:183], v[200:203], v[32:35]
	v_mfma_f32_16x16x32_bf16 v[20:23], v[172:175], v[208:211], v[20:23]
	v_mfma_f32_16x16x32_bf16 v[16:19], v[180:183], v[208:211], v[16:19]
	v_mfma_f32_16x16x32_bf16 v[4:7], v[172:175], v[216:219], v[4:7]
	v_mfma_f32_16x16x32_bf16 v[0:3], v[180:183], v[216:219], v[0:3]
	s_barrier
	s_add_i32 s58, s58, 2
	s_add_u32 s24, s24, 0x100
	s_addc_u32 s25, s25, 0
	s_add_u32 s56, s56, 0x100
	s_addc_u32 s57, s57, 0
	s_cmp_gt_u32 s58, 13
	s_cbranch_scc0 .LBB0_279
	s_setprio 0
	v_lshl_add_u32 v144, s22, 8, v152
	v_mov_b32_e32 v145, 0
	v_lshl_add_u64 v[150:151], v[144:145], 3, s[6:7]
	global_load_dwordx2 v[176:177], v[150:151], off
	global_load_dwordx2 v[178:179], v[150:151], off offset:128
	global_load_dwordx2 v[180:181], v[150:151], off offset:256
	global_load_dwordx2 v[182:183], v[150:151], off offset:384
	global_load_dwordx2 v[184:185], v[150:151], off offset:1024
	global_load_dwordx2 v[186:187], v[150:151], off offset:1152
	global_load_dwordx2 v[188:189], v[150:151], off offset:1280
	global_load_dwordx2 v[190:191], v[150:151], off offset:1408
	v_lshl_or_b32 v148, s53, 7, v153
	v_mul_u32_u24_e32 v146, s52, v144
	v_lshl_add_u32 v146, v148, 1, v146
	v_mov_b32_e32 v147, 0
	v_lshl_add_u64 v[146:147], v[146:147], 0, s[8:9]
	v_mov_b32_e32 v164, 1.0
	v_mov_b32_e32 v165, 1.0
	s_mov_b32 s101, 0
	s_and_b64 vcc, exec, s[12:13]
	s_cbranch_vccz .LBB0_282
	s_barrier

; #define PG8_STAGE(bufoff, gbase, voff) do { _Pragma("unroll") for (int _i = 0; _i < 2; ++_i) \
;         __builtin_amdgcn_global_load_lds((const unsigned*)((const char*)(gbase) + (voff)[_i]), (PG8_LAS unsigned*)(lds + (bufoff) + ldsw + _i * 8192), 16, 0, 0); } while (0)
; #define PG8_LDA(dst, b, h) do { _Pragma("unroll") for (int m = 0; m < 4; ++m) _Pragma("unroll") for (int k = 0; k < 2; ++k) dst[m][k] = *(const PG8_LAS bf16x8*)(lds + PG8_SA(b, h) + aoff + m * 2048 + k * 1024); } while (0)
; #define PG8_LDB(dst, b, h) do { _Pragma("unroll") for (int n = 0; n < 2; ++n) _Pragma("unroll") for (int k = 0; k < 2; ++k) dst[n][k] = *(const PG8_LAS bf16x8*)(lds + PG8_SB(b, h) + boff + n * 2048 + k * 1024); } while (0)
; #define PG8_MMA(ai, bj, At, Bt) do { __builtin_amdgcn_s_setprio(1); _Pragma("unroll") for (int m = 0; m < 4; ++m) _Pragma("unroll") for (int n = 0; n < 2; ++n) _Pragma("unroll") for (int k = 0; k < 2; ++k) \
;         acc[ai][bj][m][n] = __builtin_amdgcn_mfma_f32_16x16x32_bf16(Bt[n][k], At[m][k], acc[ai][bj][m][n], 0, 0, 0); __builtin_amdgcn_s_setprio(0); } while (0)
; #define PG8_WAIT_V(n) asm volatile("s_waitcnt vmcnt(" #n ")" ::: "memory")
; #define PG8_WAIT_L(n) asm volatile("s_waitcnt lgkmcnt(" #n ")" ::: "memory")
; template <class Epi, class Sched, bool ALIGN_EPI = false, bool SP2 = false>
; __device__ __forceinline__ void gemm_phase(PG8_LAS unsigned char* lds, const Gemm g, const Sched& S, const Epi& E, const int tid) {
;     ...
;             const bool last = (t == nt - 2);
;             const char* a1 = cA + (size_t)(t + 1) * kstep;
;             const char* a2 = last ? nA : cA + (size_t)(t + 2) * kstep; const char* b2 = last ? nB : cB + (size_t)(t + 2) * kstep;
;             const char* a3 = a2 + kstep; const char* b3 = b2 + kstep;
;             if (last && has_next) S.a_ready(nxt);
;             if constexpr (SP2) {
;             PG8_LDB(B0, 0, 0); PG8_LDB(B1, 0, 1); PG8_SCHED; PG8_LDA(At, 0, 0); PG8_STAGE(PG8_SA(1, 1), a1 + hstepA, voffA);
;             PG8_WAIT_V(8); PG8_WAIT_L(0); PG8_BAR; PG8_MMA(0, 0, At, B0); PG8_MMA(0, 1, At, B1); PG8_BAR; PG8_SCHED;
;             PG8_LDA(At, 0, 1); PG8_STAGE(PG8_SB(0, 0), b2, voffB); PG8_STAGE(PG8_SB(0, 1), b2 + hstep, voffB); PG8_STAGE(PG8_SA(0, 0), a2, voffA);
;             PG8_WAIT_V(8); PG8_WAIT_L(0); PG8_BAR; PG8_MMA(1, 0, At, B0); PG8_MMA(1, 1, At, B1); PG8_BAR; PG8_SCHED;
.LBB0_353:
	s_cmp_lg_u64 s[16:17], 0
	s_cbranch_scc0 .Lsp_1
	s_setprio 1
.Lsp_1:
	ds_read_b128 v[144:147], v150
	ds_read_b128 v[156:159], v150 offset:1024
	ds_read_b128 v[160:163], v150 offset:2048
	ds_read_b128 v[164:167], v150 offset:3072
	ds_read_b128 v[168:171], v151
	ds_read_b128 v[172:175], v151 offset:1024
	ds_read_b128 v[176:179], v151 offset:2048
	ds_read_b128 v[180:183], v151 offset:3072
	s_add_u32 s24, s22, 0x100
	s_addc_u32 s25, s23, 0
	s_cmp_eq_u32 s59, 40
	s_cselect_b32 s29, s7, s25
	s_cselect_b32 s28, s6, s24
	s_cselect_b32 s27, s21, s58
	s_cselect_b32 s26, s20, s57
	v_lshl_add_u64 v[196:197], s[22:23], 0, v[136:137]
	s_add_i32 m0, s38, 0xc000
	ds_read_b128 v[184:187], v152
	ds_read_b128 v[188:191], v152 offset:1024
	ds_read_b128 v[192:195], v152 offset:2048
	ds_read_b128 v[200:203], v152 offset:3072
	ds_read_b128 v[204:207], v152 offset:4096
	ds_read_b128 v[208:211], v152 offset:5120
	ds_read_b128 v[212:215], v152 offset:6144
	ds_read_b128 v[216:219], v152 offset:7168
	global_load_lds_dwordx4 v[196:197], off
	v_lshl_add_u64 v[196:197], s[22:23], 0, v[138:139]
	s_add_i32 m0, s38, 0xe000
	s_nop 0
	global_load_lds_dwordx4 v[196:197], off
	s_waitcnt vmcnt(8)
	s_waitcnt lgkmcnt(0)
	s_barrier
	s_waitcnt lgkmcnt(0)
	v_mfma_f32_16x16x32_bf16 v[124:127], v[144:147], v[184:187], v[124:127]
	v_mfma_f32_16x16x32_bf16 v[120:123], v[160:163], v[184:187], v[120:123]
	v_mfma_f32_16x16x32_bf16 v[108:111], v[144:147], v[192:195], v[108:111]
	v_mfma_f32_16x16x32_bf16 v[104:107], v[160:163], v[192:195], v[104:107]
	v_mfma_f32_16x16x32_bf16 v[92:95], v[144:147], v[204:207], v[92:95]
	v_mfma_f32_16x16x32_bf16 v[88:91], v[160:163], v[204:207], v[88:91]
	v_mfma_f32_16x16x32_bf16 v[76:79], v[144:147], v[212:215], v[76:79]
	v_mfma_f32_16x16x32_bf16 v[72:75], v[160:163], v[212:215], v[72:75]
	v_mfma_f32_16x16x32_bf16 v[124:127], v[156:159], v[188:191], v[124:127]
	v_mfma_f32_16x16x32_bf16 v[120:123], v[164:167], v[188:191], v[120:123]
	v_mfma_f32_16x16x32_bf16 v[108:111], v[156:159], v[200:203], v[108:111]
	v_mfma_f32_16x16x32_bf16 v[104:107], v[164:167], v[200:203], v[104:107]
	v_mfma_f32_16x16x32_bf16 v[92:95], v[156:159], v[208:211], v[92:95]
	v_mfma_f32_16x16x32_bf16 v[88:91], v[164:167], v[208:211], v[88:91]
	v_mfma_f32_16x16x32_bf16 v[76:79], v[156:159], v[216:219], v[76:79]
	v_mfma_f32_16x16x32_bf16 v[72:75], v[164:167], v[216:219], v[72:75]
	v_mfma_f32_16x16x32_bf16 v[116:119], v[168:171], v[184:187], v[116:119]
	v_mfma_f32_16x16x32_bf16 v[112:115], v[176:179], v[184:187], v[112:115]
	v_mfma_f32_16x16x32_bf16 v[100:103], v[168:171], v[192:195], v[100:103]
	v_mfma_f32_16x16x32_bf16 v[96:99], v[176:179], v[192:195], v[96:99]
	v_mfma_f32_16x16x32_bf16 v[84:87], v[168:171], v[204:207], v[84:87]
	v_mfma_f32_16x16x32_bf16 v[80:83], v[176:179], v[204:207], v[80:83]
	v_mfma_f32_16x16x32_bf16 v[68:71], v[168:171], v[212:215], v[68:71]
	v_mfma_f32_16x16x32_bf16 v[64:67], v[176:179], v[212:215], v[64:67]
	v_mfma_f32_16x16x32_bf16 v[116:119], v[172:175], v[188:191], v[116:119]
	v_mfma_f32_16x16x32_bf16 v[112:115], v[180:183], v[188:191], v[112:115]
	v_mfma_f32_16x16x32_bf16 v[100:103], v[172:175], v[200:203], v[100:103]
	v_mfma_f32_16x16x32_bf16 v[96:99], v[180:183], v[200:203], v[96:99]
	v_mfma_f32_16x16x32_bf16 v[84:87], v[172:175], v[208:211], v[84:87]
	v_mfma_f32_16x16x32_bf16 v[80:83], v[180:183], v[208:211], v[80:83]
	v_mfma_f32_16x16x32_bf16 v[68:71], v[172:175], v[216:219], v[68:71]
	v_mfma_f32_16x16x32_bf16 v[64:67], v[180:183], v[216:219], v[64:67]
	s_barrier
	s_mov_b32 m0, s34
	v_lshl_add_u64 v[196:197], s[26:27], 0, v[130:131]
	s_add_u32 s22, s26, 0xb0000
	ds_read_b128 v[184:187], v152 offset:16384
	ds_read_b128 v[188:191], v152 offset:17408
	ds_read_b128 v[192:195], v152 offset:18432
	ds_read_b128 v[200:203], v152 offset:19456
	ds_read_b128 v[204:207], v152 offset:20480
	ds_read_b128 v[208:211], v152 offset:21504
	ds_read_b128 v[212:215], v152 offset:22528
	ds_read_b128 v[216:219], v152 offset:23552
	global_load_lds_dwordx4 v[196:197], off
	v_lshl_add_u64 v[220:221], s[26:27], 0, v[134:135]
	s_mov_b32 m0, s35
	s_addc_u32 s23, s27, 0
	global_load_lds_dwordx4 v[220:221], off
	v_lshl_add_u64 v[222:223], s[22:23], 0, v[130:131]
	s_mov_b32 m0, s36
	v_lshl_add_u64 v[224:225], s[28:29], 0, v[132:133]
	global_load_lds_dwordx4 v[222:223], off
	v_lshl_add_u64 v[222:223], s[22:23], 0, v[134:135]
	s_mov_b32 m0, s37
	s_nop 0
	global_load_lds_dwordx4 v[222:223], off
	v_lshl_add_u64 v[222:223], s[28:29], 0, v[128:129]
	s_mov_b32 m0, s38
	s_nop 0
	global_load_lds_dwordx4 v[222:223], off
	s_mov_b32 m0, s39
	s_nop 0
	global_load_lds_dwordx4 v[224:225], off
	s_waitcnt vmcnt(8)
	s_waitcnt lgkmcnt(0)
	s_barrier
; #define PG8_STAGE(bufoff, gbase, voff) do { _Pragma("unroll") for (int _i = 0; _i < 2; ++_i) \
;         __builtin_amdgcn_global_load_lds((const unsigned*)((const char*)(gbase) + (voff)[_i]), (PG8_LAS unsigned*)(lds + (bufoff) + ldsw + _i * 8192), 16, 0, 0); } while (0)
; #define PG8_LDA(dst, b, h) do { _Pragma("unroll") for (int m = 0; m < 4; ++m) _Pragma("unroll") for (int k = 0; k < 2; ++k) dst[m][k] = *(const PG8_LAS bf16x8*)(lds + PG8_SA(b, h) + aoff + m * 2048 + k * 1024); } while (0)
; #define PG8_LDB(dst, b, h) do { _Pragma("unroll") for (int n = 0; n < 2; ++n) _Pragma("unroll") for (int k = 0; k < 2; ++k) dst[n][k] = *(const PG8_LAS bf16x8*)(lds + PG8_SB(b, h) + boff + n * 2048 + k * 1024); } while (0)
; #define PG8_MMA(ai, bj, At, Bt) do { __builtin_amdgcn_s_setprio(1); _Pragma("unroll") for (int m = 0; m < 4; ++m) _Pragma("unroll") for (int n = 0; n < 2; ++n) _Pragma("unroll") for (int k = 0; k < 2; ++k) \
;         acc[ai][bj][m][n] = __builtin_amdgcn_mfma_f32_16x16x32_bf16(Bt[n][k], At[m][k], acc[ai][bj][m][n], 0, 0, 0); __builtin_amdgcn_s_setprio(0); } while (0)
; #define PG8_WAIT_V(n) asm volatile("s_waitcnt vmcnt(" #n ")" ::: "memory")
; #define PG8_WAIT_L(n) asm volatile("s_waitcnt lgkmcnt(" #n ")" ::: "memory")
; #define PG8_BAR __builtin_amdgcn_s_barrier()
; #define PG8_SCHED __builtin_amdgcn_sched_barrier(0)
; template <class Epi, class Sched, bool ALIGN_EPI = false, bool SP2 = false>
; __device__ __forceinline__ void gemm_phase(PG8_LAS unsigned char* lds, const Gemm g, const Sched& S, const Epi& E, const int tid) {
;     ...
;             PG8_WAIT_V(8); PG8_WAIT_L(0); PG8_BAR; PG8_MMA(1, 0, At, B0); PG8_MMA(1, 1, At, B1); PG8_BAR; PG8_SCHED;
;             PG8_LDB(B0, 1, 0); PG8_LDB(B1, 1, 1); PG8_SCHED; PG8_LDA(At, 1, 0); PG8_STAGE(PG8_SA(0, 1), a2 + hstepA, voffA);
;             PG8_WAIT_V(8); PG8_WAIT_L(0); PG8_BAR; PG8_MMA(0, 0, At, B0); PG8_MMA(0, 1, At, B1); PG8_BAR; PG8_SCHED;
	s_waitcnt lgkmcnt(0)
	v_mfma_f32_16x16x32_bf16 v[60:63], v[144:147], v[184:187], v[60:63]
	v_mfma_f32_16x16x32_bf16 v[56:59], v[160:163], v[184:187], v[56:59]
	v_mfma_f32_16x16x32_bf16 v[44:47], v[144:147], v[192:195], v[44:47]
	v_mfma_f32_16x16x32_bf16 v[40:43], v[160:163], v[192:195], v[40:43]
	v_mfma_f32_16x16x32_bf16 v[28:31], v[144:147], v[204:207], v[28:31]
	v_mfma_f32_16x16x32_bf16 v[24:27], v[160:163], v[204:207], v[24:27]
	v_mfma_f32_16x16x32_bf16 v[12:15], v[144:147], v[212:215], v[12:15]
	v_mfma_f32_16x16x32_bf16 v[8:11], v[160:163], v[212:215], v[8:11]
	v_mfma_f32_16x16x32_bf16 v[60:63], v[156:159], v[188:191], v[60:63]
	v_mfma_f32_16x16x32_bf16 v[56:59], v[164:167], v[188:191], v[56:59]
	v_mfma_f32_16x16x32_bf16 v[44:47], v[156:159], v[200:203], v[44:47]
	v_mfma_f32_16x16x32_bf16 v[40:43], v[164:167], v[200:203], v[40:43]
	v_mfma_f32_16x16x32_bf16 v[28:31], v[156:159], v[208:211], v[28:31]
	v_mfma_f32_16x16x32_bf16 v[24:27], v[164:167], v[208:211], v[24:27]
	v_mfma_f32_16x16x32_bf16 v[12:15], v[156:159], v[216:219], v[12:15]
	v_mfma_f32_16x16x32_bf16 v[8:11], v[164:167], v[216:219], v[8:11]
	v_mfma_f32_16x16x32_bf16 v[52:55], v[168:171], v[184:187], v[52:55]
	v_mfma_f32_16x16x32_bf16 v[48:51], v[176:179], v[184:187], v[48:51]
	v_mfma_f32_16x16x32_bf16 v[36:39], v[168:171], v[192:195], v[36:39]
	v_mfma_f32_16x16x32_bf16 v[32:35], v[176:179], v[192:195], v[32:35]
	v_mfma_f32_16x16x32_bf16 v[20:23], v[168:171], v[204:207], v[20:23]
	v_mfma_f32_16x16x32_bf16 v[16:19], v[176:179], v[204:207], v[16:19]
	v_mfma_f32_16x16x32_bf16 v[4:7], v[168:171], v[212:215], v[4:7]
	v_mfma_f32_16x16x32_bf16 v[0:3], v[176:179], v[212:215], v[0:3]
	v_mfma_f32_16x16x32_bf16 v[52:55], v[172:175], v[188:191], v[52:55]
	v_mfma_f32_16x16x32_bf16 v[48:51], v[180:183], v[188:191], v[48:51]
	v_mfma_f32_16x16x32_bf16 v[36:39], v[172:175], v[200:203], v[36:39]
	v_mfma_f32_16x16x32_bf16 v[32:35], v[180:183], v[200:203], v[32:35]
	v_mfma_f32_16x16x32_bf16 v[20:23], v[172:175], v[208:211], v[20:23]
	v_mfma_f32_16x16x32_bf16 v[16:19], v[180:183], v[208:211], v[16:19]
	v_mfma_f32_16x16x32_bf16 v[4:7], v[172:175], v[216:219], v[4:7]
	v_mfma_f32_16x16x32_bf16 v[0:3], v[180:183], v[216:219], v[0:3]
	s_barrier
	ds_read_b128 v[144:147], v153
	ds_read_b128 v[156:159], v153 offset:1024
	ds_read_b128 v[160:163], v153 offset:2048
	ds_read_b128 v[164:167], v153 offset:3072
	ds_read_b128 v[168:171], v154
	ds_read_b128 v[172:175], v154 offset:1024
	ds_read_b128 v[176:179], v154 offset:2048
	ds_read_b128 v[180:183], v154 offset:3072
	s_add_u32 s22, s28, 0xb0000
	s_addc_u32 s23, s29, 0
	s_mov_b32 m0, s40
	v_lshl_add_u64 v[226:227], s[22:23], 0, v[128:129]
	ds_read_b128 v[184:187], v152 offset:32768
	ds_read_b128 v[188:191], v152 offset:33792
	ds_read_b128 v[192:195], v152 offset:34816
	ds_read_b128 v[200:203], v152 offset:35840
	ds_read_b128 v[204:207], v152 offset:36864
	ds_read_b128 v[208:211], v152 offset:37888
	ds_read_b128 v[212:215], v152 offset:38912
	ds_read_b128 v[216:219], v152 offset:39936
	global_load_lds_dwordx4 v[226:227], off
	v_lshl_add_u64 v[226:227], s[22:23], 0, v[132:133]
	s_mov_b32 m0, s41
	s_nop 0
	global_load_lds_dwordx4 v[226:227], off
	s_waitcnt vmcnt(8)
	s_waitcnt lgkmcnt(0)
	s_barrier
	s_waitcnt lgkmcnt(0)
	v_mfma_f32_16x16x32_bf16 v[124:127], v[144:147], v[184:187], v[124:127]
	v_mfma_f32_16x16x32_bf16 v[120:123], v[160:163], v[184:187], v[120:123]
	v_mfma_f32_16x16x32_bf16 v[108:111], v[144:147], v[192:195], v[108:111]
	v_mfma_f32_16x16x32_bf16 v[104:107], v[160:163], v[192:195], v[104:107]
	v_mfma_f32_16x16x32_bf16 v[92:95], v[144:147], v[204:207], v[92:95]
	v_mfma_f32_16x16x32_bf16 v[88:91], v[160:163], v[204:207], v[88:91]
	v_mfma_f32_16x16x32_bf16 v[76:79], v[144:147], v[212:215], v[76:79]
	v_mfma_f32_16x16x32_bf16 v[72:75], v[160:163], v[212:215], v[72:75]
	v_mfma_f32_16x16x32_bf16 v[124:127], v[156:159], v[188:191], v[124:127]
	v_mfma_f32_16x16x32_bf16 v[120:123], v[164:167], v[188:191], v[120:123]
	v_mfma_f32_16x16x32_bf16 v[108:111], v[156:159], v[200:203], v[108:111]
	v_mfma_f32_16x16x32_bf16 v[104:107], v[164:167], v[200:203], v[104:107]
	v_mfma_f32_16x16x32_bf16 v[92:95], v[156:159], v[208:211], v[92:95]
	v_mfma_f32_16x16x32_bf16 v[88:91], v[164:167], v[208:211], v[88:91]
	v_mfma_f32_16x16x32_bf16 v[76:79], v[156:159], v[216:219], v[76:79]
	v_mfma_f32_16x16x32_bf16 v[72:75], v[164:167], v[216:219], v[72:75]
	v_mfma_f32_16x16x32_bf16 v[116:119], v[168:171], v[184:187], v[116:119]
	v_mfma_f32_16x16x32_bf16 v[112:115], v[176:179], v[184:187], v[112:115]
	v_mfma_f32_16x16x32_bf16 v[100:103], v[168:171], v[192:195], v[100:103]
	v_mfma_f32_16x16x32_bf16 v[96:99], v[176:179], v[192:195], v[96:99]
	v_mfma_f32_16x16x32_bf16 v[84:87], v[168:171], v[204:207], v[84:87]
	v_mfma_f32_16x16x32_bf16 v[80:83], v[176:179], v[204:207], v[80:83]
	v_mfma_f32_16x16x32_bf16 v[68:71], v[168:171], v[212:215], v[68:71]
	v_mfma_f32_16x16x32_bf16 v[64:67], v[176:179], v[212:215], v[64:67]
	v_mfma_f32_16x16x32_bf16 v[116:119], v[172:175], v[188:191], v[116:119]
	v_mfma_f32_16x16x32_bf16 v[112:115], v[180:183], v[188:191], v[112:115]
	v_mfma_f32_16x16x32_bf16 v[100:103], v[172:175], v[200:203], v[100:103]
	v_mfma_f32_16x16x32_bf16 v[96:99], v[180:183], v[200:203], v[96:99]
	v_mfma_f32_16x16x32_bf16 v[84:87], v[172:175], v[208:211], v[84:87]
	v_mfma_f32_16x16x32_bf16 v[80:83], v[180:183], v[208:211], v[80:83]
	v_mfma_f32_16x16x32_bf16 v[68:71], v[172:175], v[216:219], v[68:71]
	v_mfma_f32_16x16x32_bf16 v[64:67], v[180:183], v[216:219], v[64:67]
	s_barrier
; #define PG8_STAGE(bufoff, gbase, voff) do { _Pragma("unroll") for (int _i = 0; _i < 2; ++_i) \
;         __builtin_amdgcn_global_load_lds((const unsigned*)((const char*)(gbase) + (voff)[_i]), (PG8_LAS unsigned*)(lds + (bufoff) + ldsw + _i * 8192), 16, 0, 0); } while (0)
; #define PG8_LDA(dst, b, h) do { _Pragma("unroll") for (int m = 0; m < 4; ++m) _Pragma("unroll") for (int k = 0; k < 2; ++k) dst[m][k] = *(const PG8_LAS bf16x8*)(lds + PG8_SA(b, h) + aoff + m * 2048 + k * 1024); } while (0)
; #define PG8_MMA(ai, bj, At, Bt) do { __builtin_amdgcn_s_setprio(1); _Pragma("unroll") for (int m = 0; m < 4; ++m) _Pragma("unroll") for (int n = 0; n < 2; ++n) _Pragma("unroll") for (int k = 0; k < 2; ++k) \
;         acc[ai][bj][m][n] = __builtin_amdgcn_mfma_f32_16x16x32_bf16(Bt[n][k], At[m][k], acc[ai][bj][m][n], 0, 0, 0); __builtin_amdgcn_s_setprio(0); } while (0)
; #define PG8_WAIT_V(n) asm volatile("s_waitcnt vmcnt(" #n ")" ::: "memory")
; #define PG8_WAIT_L(n) asm volatile("s_waitcnt lgkmcnt(" #n ")" ::: "memory")
; #define PG8_BAR __builtin_amdgcn_s_barrier()
; #define PG8_SCHED __builtin_amdgcn_sched_barrier(0)
; template <class Epi, class Sched, bool ALIGN_EPI = false, bool SP2 = false>
; __device__ __forceinline__ void gemm_phase(PG8_LAS unsigned char* lds, const Gemm g, const Sched& S, const Epi& E, const int tid) {
;     ...
;             PG8_LDA(At, 1, 1); PG8_STAGE(PG8_SB(1, 0), b3, voffB); PG8_STAGE(PG8_SB(1, 1), b3 + hstep, voffB); PG8_STAGE(PG8_SA(1, 0), a3, voffA);
;             PG8_WAIT_V(8); PG8_WAIT_L(0); PG8_BAR; PG8_MMA(1, 0, At, B0); PG8_MMA(1, 1, At, B1); PG8_BAR; PG8_SCHED;
	s_mov_b32 m0, s44
	v_lshl_add_u64 v[196:197], v[196:197], 0, s[14:15]
	s_add_u32 s22, s26, 0xb0080
	ds_read_b128 v[184:187], v152 offset:49152
	ds_read_b128 v[188:191], v152 offset:50176
	ds_read_b128 v[192:195], v152 offset:51200
	ds_read_b128 v[200:203], v152 offset:52224
	ds_read_b128 v[204:207], v152 offset:53248
	ds_read_b128 v[208:211], v152 offset:54272
	ds_read_b128 v[212:215], v152 offset:55296
	ds_read_b128 v[216:219], v152 offset:56320
	global_load_lds_dwordx4 v[196:197], off
	v_lshl_add_u64 v[196:197], v[220:221], 0, s[14:15]
	s_mov_b32 m0, s45
	s_addc_u32 s23, s27, 0
	global_load_lds_dwordx4 v[196:197], off
	v_lshl_add_u64 v[196:197], s[22:23], 0, v[130:131]
	s_mov_b32 m0, s48
	s_nop 0
	global_load_lds_dwordx4 v[196:197], off
	v_lshl_add_u64 v[196:197], s[22:23], 0, v[134:135]
	s_mov_b32 m0, s49
	s_nop 0
	global_load_lds_dwordx4 v[196:197], off
	v_lshl_add_u64 v[196:197], v[222:223], 0, s[14:15]
	s_mov_b32 m0, s46
	s_nop 0
	global_load_lds_dwordx4 v[196:197], off
	v_lshl_add_u64 v[196:197], v[224:225], 0, s[14:15]
	s_mov_b32 m0, s47
	s_nop 0
	global_load_lds_dwordx4 v[196:197], off
	s_waitcnt vmcnt(8)
	s_waitcnt lgkmcnt(0)
	s_barrier
	s_waitcnt lgkmcnt(0)
	v_mfma_f32_16x16x32_bf16 v[60:63], v[144:147], v[184:187], v[60:63]
	v_mfma_f32_16x16x32_bf16 v[56:59], v[160:163], v[184:187], v[56:59]
	v_mfma_f32_16x16x32_bf16 v[44:47], v[144:147], v[192:195], v[44:47]
	v_mfma_f32_16x16x32_bf16 v[40:43], v[160:163], v[192:195], v[40:43]
	v_mfma_f32_16x16x32_bf16 v[28:31], v[144:147], v[204:207], v[28:31]
	v_mfma_f32_16x16x32_bf16 v[24:27], v[160:163], v[204:207], v[24:27]
	v_mfma_f32_16x16x32_bf16 v[12:15], v[144:147], v[212:215], v[12:15]
	v_mfma_f32_16x16x32_bf16 v[8:11], v[160:163], v[212:215], v[8:11]
	v_mfma_f32_16x16x32_bf16 v[60:63], v[156:159], v[188:191], v[60:63]
	v_mfma_f32_16x16x32_bf16 v[56:59], v[164:167], v[188:191], v[56:59]
	v_mfma_f32_16x16x32_bf16 v[44:47], v[156:159], v[200:203], v[44:47]
	v_mfma_f32_16x16x32_bf16 v[40:43], v[164:167], v[200:203], v[40:43]
	v_mfma_f32_16x16x32_bf16 v[28:31], v[156:159], v[208:211], v[28:31]
	v_mfma_f32_16x16x32_bf16 v[24:27], v[164:167], v[208:211], v[24:27]
	v_mfma_f32_16x16x32_bf16 v[12:15], v[156:159], v[216:219], v[12:15]
	v_mfma_f32_16x16x32_bf16 v[8:11], v[164:167], v[216:219], v[8:11]
	v_mfma_f32_16x16x32_bf16 v[52:55], v[168:171], v[184:187], v[52:55]
	v_mfma_f32_16x16x32_bf16 v[48:51], v[176:179], v[184:187], v[48:51]
	v_mfma_f32_16x16x32_bf16 v[36:39], v[168:171], v[192:195], v[36:39]
	v_mfma_f32_16x16x32_bf16 v[32:35], v[176:179], v[192:195], v[32:35]
	v_mfma_f32_16x16x32_bf16 v[20:23], v[168:171], v[204:207], v[20:23]
	v_mfma_f32_16x16x32_bf16 v[16:19], v[176:179], v[204:207], v[16:19]
	v_mfma_f32_16x16x32_bf16 v[4:7], v[168:171], v[212:215], v[4:7]
	v_mfma_f32_16x16x32_bf16 v[0:3], v[176:179], v[212:215], v[0:3]
	v_mfma_f32_16x16x32_bf16 v[52:55], v[172:175], v[188:191], v[52:55]
	v_mfma_f32_16x16x32_bf16 v[48:51], v[180:183], v[188:191], v[48:51]
	v_mfma_f32_16x16x32_bf16 v[36:39], v[172:175], v[200:203], v[36:39]
	v_mfma_f32_16x16x32_bf16 v[32:35], v[180:183], v[200:203], v[32:35]
	v_mfma_f32_16x16x32_bf16 v[20:23], v[172:175], v[208:211], v[20:23]
	v_mfma_f32_16x16x32_bf16 v[16:19], v[180:183], v[208:211], v[16:19]
	v_mfma_f32_16x16x32_bf16 v[4:7], v[172:175], v[216:219], v[4:7]
	v_mfma_f32_16x16x32_bf16 v[0:3], v[180:183], v[216:219], v[0:3]
	s_barrier
	s_add_i32 s59, s59, 2
	s_add_u32 s57, s57, 0x100
	s_addc_u32 s58, s58, 0
	s_cmp_gt_u32 s59, 41
	s_mov_b64 s[22:23], s[24:25]
	s_cbranch_scc0 .LBB0_353
	s_setprio 0
	s_and_b64 vcc, exec, s[16:17]
	s_cbranch_vccnz .LBB0_357
	s_andn2_b64 vcc, exec, s[18:19]
	s_cbranch_vccz .LBB0_358

; #define PG8_STAGE(bufoff, gbase, voff) do { _Pragma("unroll") for (int _i = 0; _i < 2; ++_i) \
;         __builtin_amdgcn_global_load_lds((const unsigned*)((const char*)(gbase) + (voff)[_i]), (PG8_LAS unsigned*)(lds + (bufoff) + ldsw + _i * 8192), 16, 0, 0); } while (0)
; #define PG8_LDA(dst, b, h) do { _Pragma("unroll") for (int m = 0; m < 4; ++m) _Pragma("unroll") for (int k = 0; k < 2; ++k) dst[m][k] = *(const PG8_LAS bf16x8*)(lds + PG8_SA(b, h) + aoff + m * 2048 + k * 1024); } while (0)
; #define PG8_LDB(dst, b, h) do { _Pragma("unroll") for (int n = 0; n < 2; ++n) _Pragma("unroll") for (int k = 0; k < 2; ++k) dst[n][k] = *(const PG8_LAS bf16x8*)(lds + PG8_SB(b, h) + boff + n * 2048 + k * 1024); } while (0)
; #define PG8_MMA(ai, bj, At, Bt) do { __builtin_amdgcn_s_setprio(1); _Pragma("unroll") for (int m = 0; m < 4; ++m) _Pragma("unroll") for (int n = 0; n < 2; ++n) _Pragma("unroll") for (int k = 0; k < 2; ++k) \
;         acc[ai][bj][m][n] = __builtin_amdgcn_mfma_f32_16x16x32_bf16(Bt[n][k], At[m][k], acc[ai][bj][m][n], 0, 0, 0); __builtin_amdgcn_s_setprio(0); } while (0)
; #define PG8_WAIT_V(n) asm volatile("s_waitcnt vmcnt(" #n ")" ::: "memory")
; #define PG8_WAIT_L(n) asm volatile("s_waitcnt lgkmcnt(" #n ")" ::: "memory")
; template <class Epi, class Sched, bool ALIGN_EPI = false, bool SP2 = false>
; __device__ __forceinline__ void gemm_phase(PG8_LAS unsigned char* lds, const Gemm g, const Sched& S, const Epi& E, const int tid) {
;     ...
;             const bool last = (t == nt - 2);
;             const char* a1 = cA + (size_t)(t + 1) * kstep;
;             const char* a2 = last ? nA : cA + (size_t)(t + 2) * kstep; const char* b2 = last ? nB : cB + (size_t)(t + 2) * kstep;
;             const char* a3 = a2 + kstep; const char* b3 = b2 + kstep;
;             if (last && has_next) S.a_ready(nxt);
;             if constexpr (SP2) {
;             PG8_LDB(B0, 0, 0); PG8_LDB(B1, 0, 1); PG8_SCHED; PG8_LDA(At, 0, 0); PG8_STAGE(PG8_SA(1, 1), a1 + hstepA, voffA);
;             PG8_WAIT_V(8); PG8_WAIT_L(0); PG8_BAR; PG8_MMA(0, 0, At, B0); PG8_MMA(0, 1, At, B1); PG8_BAR; PG8_SCHED;
;             PG8_LDA(At, 0, 1); PG8_STAGE(PG8_SB(0, 0), b2, voffB); PG8_STAGE(PG8_SB(0, 1), b2 + hstep, voffB); PG8_STAGE(PG8_SA(0, 0), a2, voffA);
;             PG8_WAIT_V(8); PG8_WAIT_L(0); PG8_BAR; PG8_MMA(1, 0, At, B0); PG8_MMA(1, 1, At, B1); PG8_BAR; PG8_SCHED;
.LBB0_437:
	s_cmp_lg_u64 s[18:19], 0
	s_cbranch_scc0 .Lsp_2
	s_setprio 1
.Lsp_2:
	ds_read_b128 v[152:155], v174
	ds_read_b128 v[156:159], v174 offset:1024
	ds_read_b128 v[160:163], v174 offset:2048
	ds_read_b128 v[164:167], v174 offset:3072
	ds_read_b128 v[168:171], v175
	ds_read_b128 v[182:185], v175 offset:1024
	ds_read_b128 v[186:189], v175 offset:2048
	ds_read_b128 v[190:193], v175 offset:3072
	s_add_u32 s34, s30, 0xfffc0080
	s_addc_u32 s35, s31, -1
	s_cmp_eq_u32 s39, 12
	s_cselect_b32 s37, s0, s35
	s_cselect_b32 s36, s21, s34
	s_cselect_b32 s35, s23, s38
	s_cselect_b32 s34, s25, s33
	v_lshl_add_u64 v[172:173], s[30:31], 0, v[142:143]
	s_add_i32 m0, s57, 0xc000
	ds_read_b128 v[194:197], v176
	ds_read_b128 v[200:203], v176 offset:1024
	ds_read_b128 v[204:207], v176 offset:2048
	ds_read_b128 v[208:211], v176 offset:3072
	ds_read_b128 v[212:215], v176 offset:4096
	ds_read_b128 v[216:219], v176 offset:5120
	ds_read_b128 v[220:223], v176 offset:6144
	ds_read_b128 v[224:227], v176 offset:7168
	global_load_lds_dwordx4 v[172:173], off
	v_lshl_add_u64 v[172:173], s[30:31], 0, v[144:145]
	s_add_i32 m0, s57, 0xe000
	s_nop 0
	global_load_lds_dwordx4 v[172:173], off
	s_waitcnt vmcnt(8)
	s_waitcnt lgkmcnt(0)
	s_barrier
	s_waitcnt lgkmcnt(0)
	v_mfma_f32_16x16x32_bf16 v[124:127], v[152:155], v[194:197], v[124:127]
	v_mfma_f32_16x16x32_bf16 v[120:123], v[160:163], v[194:197], v[120:123]
	v_mfma_f32_16x16x32_bf16 v[108:111], v[152:155], v[204:207], v[108:111]
	v_mfma_f32_16x16x32_bf16 v[104:107], v[160:163], v[204:207], v[104:107]
	v_mfma_f32_16x16x32_bf16 v[92:95], v[152:155], v[212:215], v[92:95]
	v_mfma_f32_16x16x32_bf16 v[88:91], v[160:163], v[212:215], v[88:91]
	v_mfma_f32_16x16x32_bf16 v[76:79], v[152:155], v[220:223], v[76:79]
	v_mfma_f32_16x16x32_bf16 v[72:75], v[160:163], v[220:223], v[72:75]
	v_mfma_f32_16x16x32_bf16 v[124:127], v[156:159], v[200:203], v[124:127]
	v_mfma_f32_16x16x32_bf16 v[120:123], v[164:167], v[200:203], v[120:123]
	v_mfma_f32_16x16x32_bf16 v[108:111], v[156:159], v[208:211], v[108:111]
	v_mfma_f32_16x16x32_bf16 v[104:107], v[164:167], v[208:211], v[104:107]
	v_mfma_f32_16x16x32_bf16 v[92:95], v[156:159], v[216:219], v[92:95]
	v_mfma_f32_16x16x32_bf16 v[88:91], v[164:167], v[216:219], v[88:91]
	v_mfma_f32_16x16x32_bf16 v[76:79], v[156:159], v[224:227], v[76:79]
	v_mfma_f32_16x16x32_bf16 v[72:75], v[164:167], v[224:227], v[72:75]
	v_mfma_f32_16x16x32_bf16 v[116:119], v[168:171], v[194:197], v[116:119]
	v_mfma_f32_16x16x32_bf16 v[112:115], v[186:189], v[194:197], v[112:115]
	v_mfma_f32_16x16x32_bf16 v[100:103], v[168:171], v[204:207], v[100:103]
	v_mfma_f32_16x16x32_bf16 v[96:99], v[186:189], v[204:207], v[96:99]
	v_mfma_f32_16x16x32_bf16 v[84:87], v[168:171], v[212:215], v[84:87]
	v_mfma_f32_16x16x32_bf16 v[80:83], v[186:189], v[212:215], v[80:83]
	v_mfma_f32_16x16x32_bf16 v[68:71], v[168:171], v[220:223], v[68:71]
	v_mfma_f32_16x16x32_bf16 v[64:67], v[186:189], v[220:223], v[64:67]
	v_mfma_f32_16x16x32_bf16 v[116:119], v[182:185], v[200:203], v[116:119]
	v_mfma_f32_16x16x32_bf16 v[112:115], v[190:193], v[200:203], v[112:115]
	v_mfma_f32_16x16x32_bf16 v[100:103], v[182:185], v[208:211], v[100:103]
	v_mfma_f32_16x16x32_bf16 v[96:99], v[190:193], v[208:211], v[96:99]
	v_mfma_f32_16x16x32_bf16 v[84:87], v[182:185], v[216:219], v[84:87]
	v_mfma_f32_16x16x32_bf16 v[80:83], v[190:193], v[216:219], v[80:83]
	v_mfma_f32_16x16x32_bf16 v[68:71], v[182:185], v[224:227], v[68:71]
	v_mfma_f32_16x16x32_bf16 v[64:67], v[190:193], v[224:227], v[64:67]
	s_barrier
	s_mov_b32 m0, s53
	v_lshl_add_u64 v[172:173], s[34:35], 0, v[132:133]
	s_add_u32 s44, s34, 0x40000
	ds_read_b128 v[194:197], v176 offset:16384
	ds_read_b128 v[200:203], v176 offset:17408
	ds_read_b128 v[204:207], v176 offset:18432
	ds_read_b128 v[208:211], v176 offset:19456
	ds_read_b128 v[212:215], v176 offset:20480
	ds_read_b128 v[216:219], v176 offset:21504
	ds_read_b128 v[220:223], v176 offset:22528
	ds_read_b128 v[224:227], v176 offset:23552
	global_load_lds_dwordx4 v[172:173], off
	v_lshl_add_u64 v[228:229], s[34:35], 0, v[128:129]
	s_mov_b32 m0, s54
	s_addc_u32 s45, s35, 0
	global_load_lds_dwordx4 v[228:229], off
	v_lshl_add_u64 v[230:231], s[44:45], 0, v[132:133]
	s_mov_b32 m0, s55
	v_lshl_add_u64 v[232:233], s[36:37], 0, v[130:131]
	global_load_lds_dwordx4 v[230:231], off
	v_lshl_add_u64 v[230:231], s[44:45], 0, v[128:129]
	s_mov_b32 m0, s56
	s_nop 0
	global_load_lds_dwordx4 v[230:231], off
	v_lshl_add_u64 v[230:231], s[36:37], 0, v[134:135]
	s_mov_b32 m0, s57
	s_nop 0
	global_load_lds_dwordx4 v[230:231], off
	s_mov_b32 m0, s58
	s_nop 0
	global_load_lds_dwordx4 v[232:233], off
	s_waitcnt vmcnt(8)
	s_waitcnt lgkmcnt(0)
	s_barrier
; #define PG8_STAGE(bufoff, gbase, voff) do { _Pragma("unroll") for (int _i = 0; _i < 2; ++_i) \
;         __builtin_amdgcn_global_load_lds((const unsigned*)((const char*)(gbase) + (voff)[_i]), (PG8_LAS unsigned*)(lds + (bufoff) + ldsw + _i * 8192), 16, 0, 0); } while (0)
; #define PG8_LDA(dst, b, h) do { _Pragma("unroll") for (int m = 0; m < 4; ++m) _Pragma("unroll") for (int k = 0; k < 2; ++k) dst[m][k] = *(const PG8_LAS bf16x8*)(lds + PG8_SA(b, h) + aoff + m * 2048 + k * 1024); } while (0)
; #define PG8_LDB(dst, b, h) do { _Pragma("unroll") for (int n = 0; n < 2; ++n) _Pragma("unroll") for (int k = 0; k < 2; ++k) dst[n][k] = *(const PG8_LAS bf16x8*)(lds + PG8_SB(b, h) + boff + n * 2048 + k * 1024); } while (0)
; #define PG8_MMA(ai, bj, At, Bt) do { __builtin_amdgcn_s_setprio(1); _Pragma("unroll") for (int m = 0; m < 4; ++m) _Pragma("unroll") for (int n = 0; n < 2; ++n) _Pragma("unroll") for (int k = 0; k < 2; ++k) \
;         acc[ai][bj][m][n] = __builtin_amdgcn_mfma_f32_16x16x32_bf16(Bt[n][k], At[m][k], acc[ai][bj][m][n], 0, 0, 0); __builtin_amdgcn_s_setprio(0); } while (0)
; #define PG8_WAIT_V(n) asm volatile("s_waitcnt vmcnt(" #n ")" ::: "memory")
; #define PG8_WAIT_L(n) asm volatile("s_waitcnt lgkmcnt(" #n ")" ::: "memory")
; #define PG8_BAR __builtin_amdgcn_s_barrier()
; #define PG8_SCHED __builtin_amdgcn_sched_barrier(0)
; template <class Epi, class Sched, bool ALIGN_EPI = false, bool SP2 = false>
; __device__ __forceinline__ void gemm_phase(PG8_LAS unsigned char* lds, const Gemm g, const Sched& S, const Epi& E, const int tid) {
;     ...
;             PG8_WAIT_V(8); PG8_WAIT_L(0); PG8_BAR; PG8_MMA(1, 0, At, B0); PG8_MMA(1, 1, At, B1); PG8_BAR; PG8_SCHED;
;             PG8_LDB(B0, 1, 0); PG8_LDB(B1, 1, 1); PG8_SCHED; PG8_LDA(At, 1, 0); PG8_STAGE(PG8_SA(0, 1), a2 + hstepA, voffA);
;             PG8_WAIT_V(8); PG8_WAIT_L(0); PG8_BAR; PG8_MMA(0, 0, At, B0); PG8_MMA(0, 1, At, B1); PG8_BAR; PG8_SCHED;
	s_waitcnt lgkmcnt(0)
	v_mfma_f32_16x16x32_bf16 v[60:63], v[152:155], v[194:197], v[60:63]
	v_mfma_f32_16x16x32_bf16 v[56:59], v[160:163], v[194:197], v[56:59]
	v_mfma_f32_16x16x32_bf16 v[44:47], v[152:155], v[204:207], v[44:47]
	v_mfma_f32_16x16x32_bf16 v[40:43], v[160:163], v[204:207], v[40:43]
	v_mfma_f32_16x16x32_bf16 v[28:31], v[152:155], v[212:215], v[28:31]
	v_mfma_f32_16x16x32_bf16 v[24:27], v[160:163], v[212:215], v[24:27]
	v_mfma_f32_16x16x32_bf16 v[12:15], v[152:155], v[220:223], v[12:15]
	v_mfma_f32_16x16x32_bf16 v[8:11], v[160:163], v[220:223], v[8:11]
	v_mfma_f32_16x16x32_bf16 v[60:63], v[156:159], v[200:203], v[60:63]
	v_mfma_f32_16x16x32_bf16 v[56:59], v[164:167], v[200:203], v[56:59]
	v_mfma_f32_16x16x32_bf16 v[44:47], v[156:159], v[208:211], v[44:47]
	v_mfma_f32_16x16x32_bf16 v[40:43], v[164:167], v[208:211], v[40:43]
	v_mfma_f32_16x16x32_bf16 v[28:31], v[156:159], v[216:219], v[28:31]
	v_mfma_f32_16x16x32_bf16 v[24:27], v[164:167], v[216:219], v[24:27]
	v_mfma_f32_16x16x32_bf16 v[12:15], v[156:159], v[224:227], v[12:15]
	v_mfma_f32_16x16x32_bf16 v[8:11], v[164:167], v[224:227], v[8:11]
	v_mfma_f32_16x16x32_bf16 v[52:55], v[168:171], v[194:197], v[52:55]
	v_mfma_f32_16x16x32_bf16 v[48:51], v[186:189], v[194:197], v[48:51]
	v_mfma_f32_16x16x32_bf16 v[36:39], v[168:171], v[204:207], v[36:39]
	v_mfma_f32_16x16x32_bf16 v[32:35], v[186:189], v[204:207], v[32:35]
	v_mfma_f32_16x16x32_bf16 v[20:23], v[168:171], v[212:215], v[20:23]
	v_mfma_f32_16x16x32_bf16 v[16:19], v[186:189], v[212:215], v[16:19]
	v_mfma_f32_16x16x32_bf16 v[4:7], v[168:171], v[220:223], v[4:7]
	v_mfma_f32_16x16x32_bf16 v[0:3], v[186:189], v[220:223], v[0:3]
	v_mfma_f32_16x16x32_bf16 v[52:55], v[182:185], v[200:203], v[52:55]
	v_mfma_f32_16x16x32_bf16 v[48:51], v[190:193], v[200:203], v[48:51]
	v_mfma_f32_16x16x32_bf16 v[36:39], v[182:185], v[208:211], v[36:39]
	v_mfma_f32_16x16x32_bf16 v[32:35], v[190:193], v[208:211], v[32:35]
	v_mfma_f32_16x16x32_bf16 v[20:23], v[182:185], v[216:219], v[20:23]
	v_mfma_f32_16x16x32_bf16 v[16:19], v[190:193], v[216:219], v[16:19]
	v_mfma_f32_16x16x32_bf16 v[4:7], v[182:185], v[224:227], v[4:7]
	v_mfma_f32_16x16x32_bf16 v[0:3], v[190:193], v[224:227], v[0:3]
	s_barrier
	ds_read_b128 v[152:155], v177
	ds_read_b128 v[156:159], v177 offset:1024
	ds_read_b128 v[160:163], v177 offset:2048
	ds_read_b128 v[164:167], v177 offset:3072
	ds_read_b128 v[168:171], v178
	ds_read_b128 v[182:185], v178 offset:1024
	ds_read_b128 v[186:189], v178 offset:2048
	ds_read_b128 v[190:193], v178 offset:3072
	s_add_u32 s36, s36, 0x40000
	s_addc_u32 s37, s37, 0
	s_mov_b32 m0, s59
	v_lshl_add_u64 v[234:235], s[36:37], 0, v[134:135]
	ds_read_b128 v[194:197], v176 offset:32768
	ds_read_b128 v[200:203], v176 offset:33792
	ds_read_b128 v[204:207], v176 offset:34816
	ds_read_b128 v[208:211], v176 offset:35840
	ds_read_b128 v[212:215], v176 offset:36864
	ds_read_b128 v[216:219], v176 offset:37888
	ds_read_b128 v[220:223], v176 offset:38912
	ds_read_b128 v[224:227], v176 offset:39936
	global_load_lds_dwordx4 v[234:235], off
	v_lshl_add_u64 v[234:235], s[36:37], 0, v[130:131]
	s_mov_b32 m0, s60
	s_nop 0
	global_load_lds_dwordx4 v[234:235], off
	s_waitcnt vmcnt(8)
	s_waitcnt lgkmcnt(0)
	s_barrier
	s_waitcnt lgkmcnt(0)
	v_mfma_f32_16x16x32_bf16 v[124:127], v[152:155], v[194:197], v[124:127]
	v_mfma_f32_16x16x32_bf16 v[120:123], v[160:163], v[194:197], v[120:123]
	v_mfma_f32_16x16x32_bf16 v[108:111], v[152:155], v[204:207], v[108:111]
	v_mfma_f32_16x16x32_bf16 v[104:107], v[160:163], v[204:207], v[104:107]
	v_mfma_f32_16x16x32_bf16 v[92:95], v[152:155], v[212:215], v[92:95]
	v_mfma_f32_16x16x32_bf16 v[88:91], v[160:163], v[212:215], v[88:91]
	v_mfma_f32_16x16x32_bf16 v[76:79], v[152:155], v[220:223], v[76:79]
	v_mfma_f32_16x16x32_bf16 v[72:75], v[160:163], v[220:223], v[72:75]
	v_mfma_f32_16x16x32_bf16 v[124:127], v[156:159], v[200:203], v[124:127]
	v_mfma_f32_16x16x32_bf16 v[120:123], v[164:167], v[200:203], v[120:123]
	v_mfma_f32_16x16x32_bf16 v[108:111], v[156:159], v[208:211], v[108:111]
	v_mfma_f32_16x16x32_bf16 v[104:107], v[164:167], v[208:211], v[104:107]
	v_mfma_f32_16x16x32_bf16 v[92:95], v[156:159], v[216:219], v[92:95]
	v_mfma_f32_16x16x32_bf16 v[88:91], v[164:167], v[216:219], v[88:91]
	v_mfma_f32_16x16x32_bf16 v[76:79], v[156:159], v[224:227], v[76:79]
	v_mfma_f32_16x16x32_bf16 v[72:75], v[164:167], v[224:227], v[72:75]
	v_mfma_f32_16x16x32_bf16 v[116:119], v[168:171], v[194:197], v[116:119]
	v_mfma_f32_16x16x32_bf16 v[112:115], v[186:189], v[194:197], v[112:115]
	v_mfma_f32_16x16x32_bf16 v[100:103], v[168:171], v[204:207], v[100:103]
	v_mfma_f32_16x16x32_bf16 v[96:99], v[186:189], v[204:207], v[96:99]
	v_mfma_f32_16x16x32_bf16 v[84:87], v[168:171], v[212:215], v[84:87]
	v_mfma_f32_16x16x32_bf16 v[80:83], v[186:189], v[212:215], v[80:83]
	v_mfma_f32_16x16x32_bf16 v[68:71], v[168:171], v[220:223], v[68:71]
	v_mfma_f32_16x16x32_bf16 v[64:67], v[186:189], v[220:223], v[64:67]
	v_mfma_f32_16x16x32_bf16 v[116:119], v[182:185], v[200:203], v[116:119]
	v_mfma_f32_16x16x32_bf16 v[112:115], v[190:193], v[200:203], v[112:115]
	v_mfma_f32_16x16x32_bf16 v[100:103], v[182:185], v[208:211], v[100:103]
	v_mfma_f32_16x16x32_bf16 v[96:99], v[190:193], v[208:211], v[96:99]
	v_mfma_f32_16x16x32_bf16 v[84:87], v[182:185], v[216:219], v[84:87]
	v_mfma_f32_16x16x32_bf16 v[80:83], v[190:193], v[216:219], v[80:83]
	v_mfma_f32_16x16x32_bf16 v[68:71], v[182:185], v[224:227], v[68:71]
	v_mfma_f32_16x16x32_bf16 v[64:67], v[190:193], v[224:227], v[64:67]
	s_barrier
; #define PG8_STAGE(bufoff, gbase, voff) do { _Pragma("unroll") for (int _i = 0; _i < 2; ++_i) \
;         __builtin_amdgcn_global_load_lds((const unsigned*)((const char*)(gbase) + (voff)[_i]), (PG8_LAS unsigned*)(lds + (bufoff) + ldsw + _i * 8192), 16, 0, 0); } while (0)
; #define PG8_LDA(dst, b, h) do { _Pragma("unroll") for (int m = 0; m < 4; ++m) _Pragma("unroll") for (int k = 0; k < 2; ++k) dst[m][k] = *(const PG8_LAS bf16x8*)(lds + PG8_SA(b, h) + aoff + m * 2048 + k * 1024); } while (0)
; #define PG8_MMA(ai, bj, At, Bt) do { __builtin_amdgcn_s_setprio(1); _Pragma("unroll") for (int m = 0; m < 4; ++m) _Pragma("unroll") for (int n = 0; n < 2; ++n) _Pragma("unroll") for (int k = 0; k < 2; ++k) \
;         acc[ai][bj][m][n] = __builtin_amdgcn_mfma_f32_16x16x32_bf16(Bt[n][k], At[m][k], acc[ai][bj][m][n], 0, 0, 0); __builtin_amdgcn_s_setprio(0); } while (0)
; #define PG8_WAIT_V(n) asm volatile("s_waitcnt vmcnt(" #n ")" ::: "memory")
; #define PG8_WAIT_L(n) asm volatile("s_waitcnt lgkmcnt(" #n ")" ::: "memory")
; #define PG8_BAR __builtin_amdgcn_s_barrier()
; #define PG8_SCHED __builtin_amdgcn_sched_barrier(0)
; template <class Epi, class Sched, bool ALIGN_EPI = false, bool SP2 = false>
; __device__ __forceinline__ void gemm_phase(PG8_LAS unsigned char* lds, const Gemm g, const Sched& S, const Epi& E, const int tid) {
;     ...
;             PG8_LDA(At, 1, 1); PG8_STAGE(PG8_SB(1, 0), b3, voffB); PG8_STAGE(PG8_SB(1, 1), b3 + hstep, voffB); PG8_STAGE(PG8_SA(1, 0), a3, voffA);
;             PG8_WAIT_V(8); PG8_WAIT_L(0); PG8_BAR; PG8_MMA(1, 0, At, B0); PG8_MMA(1, 1, At, B1); PG8_BAR; PG8_SCHED;
;     ...
;         if constexpr (ALIGN_EPI) { if (wr == 0) PG8_BAR; }
	s_mov_b32 m0, s62
	v_lshl_add_u64 v[172:173], v[172:173], 0, s[16:17]
	s_add_u32 s34, s34, 0x40080
	ds_read_b128 v[194:197], v176 offset:49152
	ds_read_b128 v[200:203], v176 offset:50176
	ds_read_b128 v[204:207], v176 offset:51200
	ds_read_b128 v[208:211], v176 offset:52224
	ds_read_b128 v[212:215], v176 offset:53248
	ds_read_b128 v[216:219], v176 offset:54272
	ds_read_b128 v[220:223], v176 offset:55296
	ds_read_b128 v[224:227], v176 offset:56320
	global_load_lds_dwordx4 v[172:173], off
	v_lshl_add_u64 v[172:173], v[228:229], 0, s[16:17]
	s_mov_b32 m0, s63
	s_addc_u32 s35, s35, 0
	global_load_lds_dwordx4 v[172:173], off
	v_lshl_add_u64 v[172:173], s[34:35], 0, v[132:133]
	s_mov_b32 m0, s68
	s_nop 0
	global_load_lds_dwordx4 v[172:173], off
	v_lshl_add_u64 v[172:173], s[34:35], 0, v[128:129]
	s_mov_b32 m0, s69
	s_nop 0
	global_load_lds_dwordx4 v[172:173], off
	v_lshl_add_u64 v[172:173], v[230:231], 0, s[16:17]
	s_mov_b32 m0, s64
	s_nop 0
	global_load_lds_dwordx4 v[172:173], off
	v_lshl_add_u64 v[172:173], v[232:233], 0, s[16:17]
	s_mov_b32 m0, s65
	s_nop 0
	global_load_lds_dwordx4 v[172:173], off
	s_waitcnt vmcnt(8)
	s_waitcnt lgkmcnt(0)
	s_barrier
	s_waitcnt lgkmcnt(0)
	v_mfma_f32_16x16x32_bf16 v[60:63], v[152:155], v[194:197], v[60:63]
	v_mfma_f32_16x16x32_bf16 v[56:59], v[160:163], v[194:197], v[56:59]
	v_mfma_f32_16x16x32_bf16 v[44:47], v[152:155], v[204:207], v[44:47]
	v_mfma_f32_16x16x32_bf16 v[40:43], v[160:163], v[204:207], v[40:43]
	v_mfma_f32_16x16x32_bf16 v[28:31], v[152:155], v[212:215], v[28:31]
	v_mfma_f32_16x16x32_bf16 v[24:27], v[160:163], v[212:215], v[24:27]
	v_mfma_f32_16x16x32_bf16 v[12:15], v[152:155], v[220:223], v[12:15]
	v_mfma_f32_16x16x32_bf16 v[8:11], v[160:163], v[220:223], v[8:11]
	v_mfma_f32_16x16x32_bf16 v[60:63], v[156:159], v[200:203], v[60:63]
	v_mfma_f32_16x16x32_bf16 v[56:59], v[164:167], v[200:203], v[56:59]
	v_mfma_f32_16x16x32_bf16 v[44:47], v[156:159], v[208:211], v[44:47]
	v_mfma_f32_16x16x32_bf16 v[40:43], v[164:167], v[208:211], v[40:43]
	v_mfma_f32_16x16x32_bf16 v[28:31], v[156:159], v[216:219], v[28:31]
	v_mfma_f32_16x16x32_bf16 v[24:27], v[164:167], v[216:219], v[24:27]
	v_mfma_f32_16x16x32_bf16 v[12:15], v[156:159], v[224:227], v[12:15]
	v_mfma_f32_16x16x32_bf16 v[8:11], v[164:167], v[224:227], v[8:11]
	v_mfma_f32_16x16x32_bf16 v[52:55], v[168:171], v[194:197], v[52:55]
	v_mfma_f32_16x16x32_bf16 v[48:51], v[186:189], v[194:197], v[48:51]
	v_mfma_f32_16x16x32_bf16 v[36:39], v[168:171], v[204:207], v[36:39]
	v_mfma_f32_16x16x32_bf16 v[32:35], v[186:189], v[204:207], v[32:35]
	v_mfma_f32_16x16x32_bf16 v[20:23], v[168:171], v[212:215], v[20:23]
	v_mfma_f32_16x16x32_bf16 v[16:19], v[186:189], v[212:215], v[16:19]
	v_mfma_f32_16x16x32_bf16 v[4:7], v[168:171], v[220:223], v[4:7]
	v_mfma_f32_16x16x32_bf16 v[0:3], v[186:189], v[220:223], v[0:3]
	v_mfma_f32_16x16x32_bf16 v[52:55], v[182:185], v[200:203], v[52:55]
	v_mfma_f32_16x16x32_bf16 v[48:51], v[190:193], v[200:203], v[48:51]
	v_mfma_f32_16x16x32_bf16 v[36:39], v[182:185], v[208:211], v[36:39]
	v_mfma_f32_16x16x32_bf16 v[32:35], v[190:193], v[208:211], v[32:35]
	v_mfma_f32_16x16x32_bf16 v[20:23], v[182:185], v[216:219], v[20:23]
	v_mfma_f32_16x16x32_bf16 v[16:19], v[190:193], v[216:219], v[16:19]
	v_mfma_f32_16x16x32_bf16 v[4:7], v[182:185], v[224:227], v[4:7]
	v_mfma_f32_16x16x32_bf16 v[0:3], v[190:193], v[224:227], v[0:3]
	s_barrier
	s_add_i32 s39, s39, 2
	s_add_u32 s30, s30, 0x100
	s_addc_u32 s31, s31, 0
	s_add_u32 s33, s33, 0x100
	s_addc_u32 s38, s38, 0
	s_cmp_gt_u32 s39, 13
	s_cbranch_scc0 .LBB0_437
	s_setprio 0
	s_and_b64 vcc, exec, s[18:19]
	s_cbranch_vccz .LBB0_440
	s_barrier

; #define PG8_STAGE(bufoff, gbase, voff) do { _Pragma("unroll") for (int _i = 0; _i < 2; ++_i) \
;         __builtin_amdgcn_global_load_lds((const unsigned*)((const char*)(gbase) + (voff)[_i]), (PG8_LAS unsigned*)(lds + (bufoff) + ldsw + _i * 8192), 16, 0, 0); } while (0)
; #define PG8_LDA(dst, b, h) do { _Pragma("unroll") for (int m = 0; m < 4; ++m) _Pragma("unroll") for (int k = 0; k < 2; ++k) dst[m][k] = *(const PG8_LAS bf16x8*)(lds + PG8_SA(b, h) + aoff + m * 2048 + k * 1024); } while (0)
; #define PG8_LDB(dst, b, h) do { _Pragma("unroll") for (int n = 0; n < 2; ++n) _Pragma("unroll") for (int k = 0; k < 2; ++k) dst[n][k] = *(const PG8_LAS bf16x8*)(lds + PG8_SB(b, h) + boff + n * 2048 + k * 1024); } while (0)
; #define PG8_MMA(ai, bj, At, Bt) do { __builtin_amdgcn_s_setprio(1); _Pragma("unroll") for (int m = 0; m < 4; ++m) _Pragma("unroll") for (int n = 0; n < 2; ++n) _Pragma("unroll") for (int k = 0; k < 2; ++k) \
;         acc[ai][bj][m][n] = __builtin_amdgcn_mfma_f32_16x16x32_bf16(Bt[n][k], At[m][k], acc[ai][bj][m][n], 0, 0, 0); __builtin_amdgcn_s_setprio(0); } while (0)
; #define PG8_WAIT_V(n) asm volatile("s_waitcnt vmcnt(" #n ")" ::: "memory")
; #define PG8_WAIT_L(n) asm volatile("s_waitcnt lgkmcnt(" #n ")" ::: "memory")
; template <class Epi, class Sched, bool ALIGN_EPI = false, bool SP2 = false>
; __device__ __forceinline__ void gemm_phase(PG8_LAS unsigned char* lds, const Gemm g, const Sched& S, const Epi& E, const int tid) {
;     ...
;             const bool last = (t == nt - 2);
;             const char* a1 = cA + (size_t)(t + 1) * kstep;
;             const char* a2 = last ? nA : cA + (size_t)(t + 2) * kstep; const char* b2 = last ? nB : cB + (size_t)(t + 2) * kstep;
;             const char* a3 = a2 + kstep; const char* b3 = b2 + kstep;
;             if (last && has_next) S.a_ready(nxt);
;             if constexpr (SP2) {
;             PG8_LDB(B0, 0, 0); PG8_LDB(B1, 0, 1); PG8_SCHED; PG8_LDA(At, 0, 0); PG8_STAGE(PG8_SA(1, 1), a1 + hstepA, voffA);
;             PG8_WAIT_V(8); PG8_WAIT_L(0); PG8_BAR; PG8_MMA(0, 0, At, B0); PG8_MMA(0, 1, At, B1); PG8_BAR; PG8_SCHED;
;             PG8_LDA(At, 0, 1); PG8_STAGE(PG8_SB(0, 0), b2, voffB); PG8_STAGE(PG8_SB(0, 1), b2 + hstep, voffB); PG8_STAGE(PG8_SA(0, 0), a2, voffA);
;             PG8_WAIT_V(8); PG8_WAIT_L(0); PG8_BAR; PG8_MMA(1, 0, At, B0); PG8_MMA(1, 1, At, B1); PG8_BAR; PG8_SCHED;
.Lsp_3:
	ds_read_b128 v[144:147], v150
	ds_read_b128 v[156:159], v150 offset:1024
	ds_read_b128 v[160:163], v150 offset:2048
	ds_read_b128 v[164:167], v150 offset:3072
	ds_read_b128 v[168:171], v151
	ds_read_b128 v[172:175], v151 offset:1024
	ds_read_b128 v[176:179], v151 offset:2048
	ds_read_b128 v[180:183], v151 offset:3072
	s_add_u32 s6, s28, 0x100
	s_addc_u32 s7, s29, 0
	s_cmp_eq_u32 s61, 12
	s_cselect_b32 s35, s23, s7
	s_cselect_b32 s34, s22, s6
	s_cselect_b32 s31, s21, s60
	s_cselect_b32 s30, s58, s59
	v_lshl_add_u64 v[196:197], s[28:29], 0, v[136:137]
	s_add_i32 m0, s41, 0xc000
	ds_read_b128 v[184:187], v152
	ds_read_b128 v[188:191], v152 offset:1024
	ds_read_b128 v[192:195], v152 offset:2048
	ds_read_b128 v[200:203], v152 offset:3072
	ds_read_b128 v[204:207], v152 offset:4096
	ds_read_b128 v[208:211], v152 offset:5120
	ds_read_b128 v[212:215], v152 offset:6144
	ds_read_b128 v[216:219], v152 offset:7168
	global_load_lds_dwordx4 v[196:197], off
	v_lshl_add_u64 v[196:197], s[28:29], 0, v[138:139]
	s_add_i32 m0, s41, 0xe000
	s_nop 0
	global_load_lds_dwordx4 v[196:197], off
	s_waitcnt vmcnt(8)
	s_waitcnt lgkmcnt(0)
	s_barrier
	s_waitcnt lgkmcnt(0)
	v_mfma_f32_16x16x32_bf16 v[124:127], v[144:147], v[184:187], v[124:127]
	v_mfma_f32_16x16x32_bf16 v[120:123], v[160:163], v[184:187], v[120:123]
	v_mfma_f32_16x16x32_bf16 v[108:111], v[144:147], v[192:195], v[108:111]
	v_mfma_f32_16x16x32_bf16 v[104:107], v[160:163], v[192:195], v[104:107]
	v_mfma_f32_16x16x32_bf16 v[92:95], v[144:147], v[204:207], v[92:95]
	v_mfma_f32_16x16x32_bf16 v[88:91], v[160:163], v[204:207], v[88:91]
	v_mfma_f32_16x16x32_bf16 v[76:79], v[144:147], v[212:215], v[76:79]
	v_mfma_f32_16x16x32_bf16 v[72:75], v[160:163], v[212:215], v[72:75]
	v_mfma_f32_16x16x32_bf16 v[124:127], v[156:159], v[188:191], v[124:127]
	v_mfma_f32_16x16x32_bf16 v[120:123], v[164:167], v[188:191], v[120:123]
	v_mfma_f32_16x16x32_bf16 v[108:111], v[156:159], v[200:203], v[108:111]
	v_mfma_f32_16x16x32_bf16 v[104:107], v[164:167], v[200:203], v[104:107]
	v_mfma_f32_16x16x32_bf16 v[92:95], v[156:159], v[208:211], v[92:95]
	v_mfma_f32_16x16x32_bf16 v[88:91], v[164:167], v[208:211], v[88:91]
	v_mfma_f32_16x16x32_bf16 v[76:79], v[156:159], v[216:219], v[76:79]
	v_mfma_f32_16x16x32_bf16 v[72:75], v[164:167], v[216:219], v[72:75]
	v_mfma_f32_16x16x32_bf16 v[116:119], v[168:171], v[184:187], v[116:119]
	v_mfma_f32_16x16x32_bf16 v[112:115], v[176:179], v[184:187], v[112:115]
	v_mfma_f32_16x16x32_bf16 v[100:103], v[168:171], v[192:195], v[100:103]
	v_mfma_f32_16x16x32_bf16 v[96:99], v[176:179], v[192:195], v[96:99]
	v_mfma_f32_16x16x32_bf16 v[84:87], v[168:171], v[204:207], v[84:87]
	v_mfma_f32_16x16x32_bf16 v[80:83], v[176:179], v[204:207], v[80:83]
	v_mfma_f32_16x16x32_bf16 v[68:71], v[168:171], v[212:215], v[68:71]
	v_mfma_f32_16x16x32_bf16 v[64:67], v[176:179], v[212:215], v[64:67]
	v_mfma_f32_16x16x32_bf16 v[116:119], v[172:175], v[188:191], v[116:119]
	v_mfma_f32_16x16x32_bf16 v[112:115], v[180:183], v[188:191], v[112:115]
	v_mfma_f32_16x16x32_bf16 v[100:103], v[172:175], v[200:203], v[100:103]
	v_mfma_f32_16x16x32_bf16 v[96:99], v[180:183], v[200:203], v[96:99]
	v_mfma_f32_16x16x32_bf16 v[84:87], v[172:175], v[208:211], v[84:87]
	v_mfma_f32_16x16x32_bf16 v[80:83], v[180:183], v[208:211], v[80:83]
	v_mfma_f32_16x16x32_bf16 v[68:71], v[172:175], v[216:219], v[68:71]
	v_mfma_f32_16x16x32_bf16 v[64:67], v[180:183], v[216:219], v[64:67]
	s_barrier
	s_mov_b32 m0, s27
	v_lshl_add_u64 v[196:197], s[30:31], 0, v[130:131]
	s_add_u32 s28, s30, 0x40000
	ds_read_b128 v[184:187], v152 offset:16384
	ds_read_b128 v[188:191], v152 offset:17408
	ds_read_b128 v[192:195], v152 offset:18432
	ds_read_b128 v[200:203], v152 offset:19456
	ds_read_b128 v[204:207], v152 offset:20480
	ds_read_b128 v[208:211], v152 offset:21504
	ds_read_b128 v[212:215], v152 offset:22528
	ds_read_b128 v[216:219], v152 offset:23552
	global_load_lds_dwordx4 v[196:197], off
	v_lshl_add_u64 v[220:221], s[30:31], 0, v[134:135]
	s_mov_b32 m0, s38
	s_addc_u32 s29, s31, 0
	global_load_lds_dwordx4 v[220:221], off
	v_lshl_add_u64 v[222:223], s[28:29], 0, v[130:131]
	s_mov_b32 m0, s39
	v_lshl_add_u64 v[224:225], s[34:35], 0, v[132:133]
	global_load_lds_dwordx4 v[222:223], off
	v_lshl_add_u64 v[222:223], s[28:29], 0, v[134:135]
	s_mov_b32 m0, s40
	s_nop 0
	global_load_lds_dwordx4 v[222:223], off
	v_lshl_add_u64 v[222:223], s[34:35], 0, v[128:129]
	s_mov_b32 m0, s41
	s_nop 0
	global_load_lds_dwordx4 v[222:223], off
	s_mov_b32 m0, s42
	s_nop 0
	global_load_lds_dwordx4 v[224:225], off
	s_waitcnt vmcnt(8)
	s_waitcnt lgkmcnt(0)
	s_barrier
; #define PG8_STAGE(bufoff, gbase, voff) do { _Pragma("unroll") for (int _i = 0; _i < 2; ++_i) \
;         __builtin_amdgcn_global_load_lds((const unsigned*)((const char*)(gbase) + (voff)[_i]), (PG8_LAS unsigned*)(lds + (bufoff) + ldsw + _i * 8192), 16, 0, 0); } while (0)
; #define PG8_LDA(dst, b, h) do { _Pragma("unroll") for (int m = 0; m < 4; ++m) _Pragma("unroll") for (int k = 0; k < 2; ++k) dst[m][k] = *(const PG8_LAS bf16x8*)(lds + PG8_SA(b, h) + aoff + m * 2048 + k * 1024); } while (0)
; #define PG8_LDB(dst, b, h) do { _Pragma("unroll") for (int n = 0; n < 2; ++n) _Pragma("unroll") for (int k = 0; k < 2; ++k) dst[n][k] = *(const PG8_LAS bf16x8*)(lds + PG8_SB(b, h) + boff + n * 2048 + k * 1024); } while (0)
; #define PG8_MMA(ai, bj, At, Bt) do { __builtin_amdgcn_s_setprio(1); _Pragma("unroll") for (int m = 0; m < 4; ++m) _Pragma("unroll") for (int n = 0; n < 2; ++n) _Pragma("unroll") for (int k = 0; k < 2; ++k) \
;         acc[ai][bj][m][n] = __builtin_amdgcn_mfma_f32_16x16x32_bf16(Bt[n][k], At[m][k], acc[ai][bj][m][n], 0, 0, 0); __builtin_amdgcn_s_setprio(0); } while (0)
; #define PG8_WAIT_V(n) asm volatile("s_waitcnt vmcnt(" #n ")" ::: "memory")
; #define PG8_WAIT_L(n) asm volatile("s_waitcnt lgkmcnt(" #n ")" ::: "memory")
; #define PG8_BAR __builtin_amdgcn_s_barrier()
; #define PG8_SCHED __builtin_amdgcn_sched_barrier(0)
; template <class Epi, class Sched, bool ALIGN_EPI = false, bool SP2 = false>
; __device__ __forceinline__ void gemm_phase(PG8_LAS unsigned char* lds, const Gemm g, const Sched& S, const Epi& E, const int tid) {
;     ...
;             PG8_WAIT_V(8); PG8_WAIT_L(0); PG8_BAR; PG8_MMA(1, 0, At, B0); PG8_MMA(1, 1, At, B1); PG8_BAR; PG8_SCHED;
;             PG8_LDB(B0, 1, 0); PG8_LDB(B1, 1, 1); PG8_SCHED; PG8_LDA(At, 1, 0); PG8_STAGE(PG8_SA(0, 1), a2 + hstepA, voffA);
;             PG8_WAIT_V(8); PG8_WAIT_L(0); PG8_BAR; PG8_MMA(0, 0, At, B0); PG8_MMA(0, 1, At, B1); PG8_BAR; PG8_SCHED;
	s_waitcnt lgkmcnt(0)
	v_mfma_f32_16x16x32_bf16 v[60:63], v[144:147], v[184:187], v[60:63]
	v_mfma_f32_16x16x32_bf16 v[56:59], v[160:163], v[184:187], v[56:59]
	v_mfma_f32_16x16x32_bf16 v[44:47], v[144:147], v[192:195], v[44:47]
	v_mfma_f32_16x16x32_bf16 v[40:43], v[160:163], v[192:195], v[40:43]
	v_mfma_f32_16x16x32_bf16 v[28:31], v[144:147], v[204:207], v[28:31]
	v_mfma_f32_16x16x32_bf16 v[24:27], v[160:163], v[204:207], v[24:27]
	v_mfma_f32_16x16x32_bf16 v[12:15], v[144:147], v[212:215], v[12:15]
	v_mfma_f32_16x16x32_bf16 v[8:11], v[160:163], v[212:215], v[8:11]
	v_mfma_f32_16x16x32_bf16 v[60:63], v[156:159], v[188:191], v[60:63]
	v_mfma_f32_16x16x32_bf16 v[56:59], v[164:167], v[188:191], v[56:59]
	v_mfma_f32_16x16x32_bf16 v[44:47], v[156:159], v[200:203], v[44:47]
	v_mfma_f32_16x16x32_bf16 v[40:43], v[164:167], v[200:203], v[40:43]
	v_mfma_f32_16x16x32_bf16 v[28:31], v[156:159], v[208:211], v[28:31]
	v_mfma_f32_16x16x32_bf16 v[24:27], v[164:167], v[208:211], v[24:27]
	v_mfma_f32_16x16x32_bf16 v[12:15], v[156:159], v[216:219], v[12:15]
	v_mfma_f32_16x16x32_bf16 v[8:11], v[164:167], v[216:219], v[8:11]
	v_mfma_f32_16x16x32_bf16 v[52:55], v[168:171], v[184:187], v[52:55]
	v_mfma_f32_16x16x32_bf16 v[48:51], v[176:179], v[184:187], v[48:51]
	v_mfma_f32_16x16x32_bf16 v[36:39], v[168:171], v[192:195], v[36:39]
	v_mfma_f32_16x16x32_bf16 v[32:35], v[176:179], v[192:195], v[32:35]
	v_mfma_f32_16x16x32_bf16 v[20:23], v[168:171], v[204:207], v[20:23]
	v_mfma_f32_16x16x32_bf16 v[16:19], v[176:179], v[204:207], v[16:19]
	v_mfma_f32_16x16x32_bf16 v[4:7], v[168:171], v[212:215], v[4:7]
	v_mfma_f32_16x16x32_bf16 v[0:3], v[176:179], v[212:215], v[0:3]
	v_mfma_f32_16x16x32_bf16 v[52:55], v[172:175], v[188:191], v[52:55]
	v_mfma_f32_16x16x32_bf16 v[48:51], v[180:183], v[188:191], v[48:51]
	v_mfma_f32_16x16x32_bf16 v[36:39], v[172:175], v[200:203], v[36:39]
	v_mfma_f32_16x16x32_bf16 v[32:35], v[180:183], v[200:203], v[32:35]
	v_mfma_f32_16x16x32_bf16 v[20:23], v[172:175], v[208:211], v[20:23]
	v_mfma_f32_16x16x32_bf16 v[16:19], v[180:183], v[208:211], v[16:19]
	v_mfma_f32_16x16x32_bf16 v[4:7], v[172:175], v[216:219], v[4:7]
	v_mfma_f32_16x16x32_bf16 v[0:3], v[180:183], v[216:219], v[0:3]
	s_barrier
	ds_read_b128 v[144:147], v153
	ds_read_b128 v[156:159], v153 offset:1024
	ds_read_b128 v[160:163], v153 offset:2048
	ds_read_b128 v[164:167], v153 offset:3072
	ds_read_b128 v[168:171], v154
	ds_read_b128 v[172:175], v154 offset:1024
	ds_read_b128 v[176:179], v154 offset:2048
	ds_read_b128 v[180:183], v154 offset:3072
	s_add_u32 s28, s34, 0xe0000
	s_addc_u32 s29, s35, 0
	s_mov_b32 m0, s43
	v_lshl_add_u64 v[226:227], s[28:29], 0, v[128:129]
	ds_read_b128 v[184:187], v152 offset:32768
	ds_read_b128 v[188:191], v152 offset:33792
	ds_read_b128 v[192:195], v152 offset:34816
	ds_read_b128 v[200:203], v152 offset:35840
	ds_read_b128 v[204:207], v152 offset:36864
	ds_read_b128 v[208:211], v152 offset:37888
	ds_read_b128 v[212:215], v152 offset:38912
	ds_read_b128 v[216:219], v152 offset:39936
	global_load_lds_dwordx4 v[226:227], off
	v_lshl_add_u64 v[226:227], s[28:29], 0, v[132:133]
	s_mov_b32 m0, s44
	s_nop 0
	global_load_lds_dwordx4 v[226:227], off
	s_waitcnt vmcnt(8)
	s_waitcnt lgkmcnt(0)
	s_barrier
	s_waitcnt lgkmcnt(0)
	v_mfma_f32_16x16x32_bf16 v[124:127], v[144:147], v[184:187], v[124:127]
	v_mfma_f32_16x16x32_bf16 v[120:123], v[160:163], v[184:187], v[120:123]
	v_mfma_f32_16x16x32_bf16 v[108:111], v[144:147], v[192:195], v[108:111]
	v_mfma_f32_16x16x32_bf16 v[104:107], v[160:163], v[192:195], v[104:107]
	v_mfma_f32_16x16x32_bf16 v[92:95], v[144:147], v[204:207], v[92:95]
	v_mfma_f32_16x16x32_bf16 v[88:91], v[160:163], v[204:207], v[88:91]
	v_mfma_f32_16x16x32_bf16 v[76:79], v[144:147], v[212:215], v[76:79]
	v_mfma_f32_16x16x32_bf16 v[72:75], v[160:163], v[212:215], v[72:75]
	v_mfma_f32_16x16x32_bf16 v[124:127], v[156:159], v[188:191], v[124:127]
	v_mfma_f32_16x16x32_bf16 v[120:123], v[164:167], v[188:191], v[120:123]
	v_mfma_f32_16x16x32_bf16 v[108:111], v[156:159], v[200:203], v[108:111]
	v_mfma_f32_16x16x32_bf16 v[104:107], v[164:167], v[200:203], v[104:107]
	v_mfma_f32_16x16x32_bf16 v[92:95], v[156:159], v[208:211], v[92:95]
	v_mfma_f32_16x16x32_bf16 v[88:91], v[164:167], v[208:211], v[88:91]
	v_mfma_f32_16x16x32_bf16 v[76:79], v[156:159], v[216:219], v[76:79]
	v_mfma_f32_16x16x32_bf16 v[72:75], v[164:167], v[216:219], v[72:75]
	v_mfma_f32_16x16x32_bf16 v[116:119], v[168:171], v[184:187], v[116:119]
	v_mfma_f32_16x16x32_bf16 v[112:115], v[176:179], v[184:187], v[112:115]
	v_mfma_f32_16x16x32_bf16 v[100:103], v[168:171], v[192:195], v[100:103]
	v_mfma_f32_16x16x32_bf16 v[96:99], v[176:179], v[192:195], v[96:99]
	v_mfma_f32_16x16x32_bf16 v[84:87], v[168:171], v[204:207], v[84:87]
	v_mfma_f32_16x16x32_bf16 v[80:83], v[176:179], v[204:207], v[80:83]
	v_mfma_f32_16x16x32_bf16 v[68:71], v[168:171], v[212:215], v[68:71]
	v_mfma_f32_16x16x32_bf16 v[64:67], v[176:179], v[212:215], v[64:67]
	v_mfma_f32_16x16x32_bf16 v[116:119], v[172:175], v[188:191], v[116:119]
	v_mfma_f32_16x16x32_bf16 v[112:115], v[180:183], v[188:191], v[112:115]
	v_mfma_f32_16x16x32_bf16 v[100:103], v[172:175], v[200:203], v[100:103]
	v_mfma_f32_16x16x32_bf16 v[96:99], v[180:183], v[200:203], v[96:99]
	v_mfma_f32_16x16x32_bf16 v[84:87], v[172:175], v[208:211], v[84:87]
	v_mfma_f32_16x16x32_bf16 v[80:83], v[180:183], v[208:211], v[80:83]
	v_mfma_f32_16x16x32_bf16 v[68:71], v[172:175], v[216:219], v[68:71]
	v_mfma_f32_16x16x32_bf16 v[64:67], v[180:183], v[216:219], v[64:67]
	s_barrier
; #define PG8_STAGE(bufoff, gbase, voff) do { _Pragma("unroll") for (int _i = 0; _i < 2; ++_i) \
;         __builtin_amdgcn_global_load_lds((const unsigned*)((const char*)(gbase) + (voff)[_i]), (PG8_LAS unsigned*)(lds + (bufoff) + ldsw + _i * 8192), 16, 0, 0); } while (0)
; #define PG8_LDA(dst, b, h) do { _Pragma("unroll") for (int m = 0; m < 4; ++m) _Pragma("unroll") for (int k = 0; k < 2; ++k) dst[m][k] = *(const PG8_LAS bf16x8*)(lds + PG8_SA(b, h) + aoff + m * 2048 + k * 1024); } while (0)
; #define PG8_MMA(ai, bj, At, Bt) do { __builtin_amdgcn_s_setprio(1); _Pragma("unroll") for (int m = 0; m < 4; ++m) _Pragma("unroll") for (int n = 0; n < 2; ++n) _Pragma("unroll") for (int k = 0; k < 2; ++k) \
;         acc[ai][bj][m][n] = __builtin_amdgcn_mfma_f32_16x16x32_bf16(Bt[n][k], At[m][k], acc[ai][bj][m][n], 0, 0, 0); __builtin_amdgcn_s_setprio(0); } while (0)
; #define PG8_WAIT_V(n) asm volatile("s_waitcnt vmcnt(" #n ")" ::: "memory")
; #define PG8_WAIT_L(n) asm volatile("s_waitcnt lgkmcnt(" #n ")" ::: "memory")
; #define PG8_BAR __builtin_amdgcn_s_barrier()
; #define PG8_SCHED __builtin_amdgcn_sched_barrier(0)
; template <class Epi, class Sched, bool ALIGN_EPI = false, bool SP2 = false>
; __device__ __forceinline__ void gemm_phase(PG8_LAS unsigned char* lds, const Gemm g, const Sched& S, const Epi& E, const int tid) {
;     ...
;             PG8_LDA(At, 1, 1); PG8_STAGE(PG8_SB(1, 0), b3, voffB); PG8_STAGE(PG8_SB(1, 1), b3 + hstep, voffB); PG8_STAGE(PG8_SA(1, 0), a3, voffA);
;             PG8_WAIT_V(8); PG8_WAIT_L(0); PG8_BAR; PG8_MMA(1, 0, At, B0); PG8_MMA(1, 1, At, B1); PG8_BAR; PG8_SCHED;
	s_mov_b32 m0, s47
	v_lshl_add_u64 v[196:197], v[196:197], 0, s[14:15]
	s_add_u32 s28, s30, 0x40080
	ds_read_b128 v[184:187], v152 offset:49152
	ds_read_b128 v[188:191], v152 offset:50176
	ds_read_b128 v[192:195], v152 offset:51200
	ds_read_b128 v[200:203], v152 offset:52224
	ds_read_b128 v[204:207], v152 offset:53248
	ds_read_b128 v[208:211], v152 offset:54272
	ds_read_b128 v[212:215], v152 offset:55296
	ds_read_b128 v[216:219], v152 offset:56320
	global_load_lds_dwordx4 v[196:197], off
	v_lshl_add_u64 v[196:197], v[220:221], 0, s[14:15]
	s_mov_b32 m0, s48
	s_addc_u32 s29, s31, 0
	global_load_lds_dwordx4 v[196:197], off
	v_lshl_add_u64 v[196:197], s[28:29], 0, v[130:131]
	s_mov_b32 m0, s51
	s_nop 0
	global_load_lds_dwordx4 v[196:197], off
	v_lshl_add_u64 v[196:197], s[28:29], 0, v[134:135]
	s_mov_b32 m0, s52
	s_nop 0
	global_load_lds_dwordx4 v[196:197], off
	v_lshl_add_u64 v[196:197], v[222:223], 0, s[14:15]
	s_mov_b32 m0, s49
	s_nop 0
	global_load_lds_dwordx4 v[196:197], off
	v_lshl_add_u64 v[196:197], v[224:225], 0, s[14:15]
	s_mov_b32 m0, s50
	s_nop 0
	global_load_lds_dwordx4 v[196:197], off
	s_waitcnt vmcnt(8)
	s_waitcnt lgkmcnt(0)
	s_barrier
	s_waitcnt lgkmcnt(0)
	v_mfma_f32_16x16x32_bf16 v[60:63], v[144:147], v[184:187], v[60:63]
	v_mfma_f32_16x16x32_bf16 v[56:59], v[160:163], v[184:187], v[56:59]
	v_mfma_f32_16x16x32_bf16 v[44:47], v[144:147], v[192:195], v[44:47]
	v_mfma_f32_16x16x32_bf16 v[40:43], v[160:163], v[192:195], v[40:43]
	v_mfma_f32_16x16x32_bf16 v[28:31], v[144:147], v[204:207], v[28:31]
	v_mfma_f32_16x16x32_bf16 v[24:27], v[160:163], v[204:207], v[24:27]
	v_mfma_f32_16x16x32_bf16 v[12:15], v[144:147], v[212:215], v[12:15]
	v_mfma_f32_16x16x32_bf16 v[8:11], v[160:163], v[212:215], v[8:11]
	v_mfma_f32_16x16x32_bf16 v[60:63], v[156:159], v[188:191], v[60:63]
	v_mfma_f32_16x16x32_bf16 v[56:59], v[164:167], v[188:191], v[56:59]
	v_mfma_f32_16x16x32_bf16 v[44:47], v[156:159], v[200:203], v[44:47]
	v_mfma_f32_16x16x32_bf16 v[40:43], v[164:167], v[200:203], v[40:43]
	v_mfma_f32_16x16x32_bf16 v[28:31], v[156:159], v[208:211], v[28:31]
	v_mfma_f32_16x16x32_bf16 v[24:27], v[164:167], v[208:211], v[24:27]
	v_mfma_f32_16x16x32_bf16 v[12:15], v[156:159], v[216:219], v[12:15]
	v_mfma_f32_16x16x32_bf16 v[8:11], v[164:167], v[216:219], v[8:11]
	v_mfma_f32_16x16x32_bf16 v[52:55], v[168:171], v[184:187], v[52:55]
	v_mfma_f32_16x16x32_bf16 v[48:51], v[176:179], v[184:187], v[48:51]
	v_mfma_f32_16x16x32_bf16 v[36:39], v[168:171], v[192:195], v[36:39]
	v_mfma_f32_16x16x32_bf16 v[32:35], v[176:179], v[192:195], v[32:35]
	v_mfma_f32_16x16x32_bf16 v[20:23], v[168:171], v[204:207], v[20:23]
	v_mfma_f32_16x16x32_bf16 v[16:19], v[176:179], v[204:207], v[16:19]
	v_mfma_f32_16x16x32_bf16 v[4:7], v[168:171], v[212:215], v[4:7]
	v_mfma_f32_16x16x32_bf16 v[0:3], v[176:179], v[212:215], v[0:3]
	v_mfma_f32_16x16x32_bf16 v[52:55], v[172:175], v[188:191], v[52:55]
	v_mfma_f32_16x16x32_bf16 v[48:51], v[180:183], v[188:191], v[48:51]
	v_mfma_f32_16x16x32_bf16 v[36:39], v[172:175], v[200:203], v[36:39]
	v_mfma_f32_16x16x32_bf16 v[32:35], v[180:183], v[200:203], v[32:35]
	v_mfma_f32_16x16x32_bf16 v[20:23], v[172:175], v[208:211], v[20:23]
	v_mfma_f32_16x16x32_bf16 v[16:19], v[180:183], v[208:211], v[16:19]
	v_mfma_f32_16x16x32_bf16 v[4:7], v[172:175], v[216:219], v[4:7]
	v_mfma_f32_16x16x32_bf16 v[0:3], v[180:183], v[216:219], v[0:3]
	s_barrier
	s_add_i32 s61, s61, 2
	s_add_u32 s59, s59, 0x100
	s_addc_u32 s60, s60, 0
	s_cmp_gt_u32 s61, 13
	s_mov_b64 s[28:29], s[6:7]
	s_cbranch_scc0 .LBB0_765
	s_setprio 0
	s_and_b64 vcc, exec, s[16:17]
	s_cbranch_vccnz .LBB0_769
	s_andn2_b64 vcc, exec, s[18:19]
	s_cbranch_vccz .LBB0_770

; #define PG8_STAGE(bufoff, gbase, voff) do { _Pragma("unroll") for (int _i = 0; _i < 2; ++_i) \
;         __builtin_amdgcn_global_load_lds((const unsigned*)((const char*)(gbase) + (voff)[_i]), (PG8_LAS unsigned*)(lds + (bufoff) + ldsw + _i * 8192), 16, 0, 0); } while (0)
; #define PG8_LDA(dst, b, h) do { _Pragma("unroll") for (int m = 0; m < 4; ++m) _Pragma("unroll") for (int k = 0; k < 2; ++k) dst[m][k] = *(const PG8_LAS bf16x8*)(lds + PG8_SA(b, h) + aoff + m * 2048 + k * 1024); } while (0)
; #define PG8_LDB(dst, b, h) do { _Pragma("unroll") for (int n = 0; n < 2; ++n) _Pragma("unroll") for (int k = 0; k < 2; ++k) dst[n][k] = *(const PG8_LAS bf16x8*)(lds + PG8_SB(b, h) + boff + n * 2048 + k * 1024); } while (0)
; #define PG8_MMA(ai, bj, At, Bt) do { __builtin_amdgcn_s_setprio(1); _Pragma("unroll") for (int m = 0; m < 4; ++m) _Pragma("unroll") for (int n = 0; n < 2; ++n) _Pragma("unroll") for (int k = 0; k < 2; ++k) \
;         acc[ai][bj][m][n] = __builtin_amdgcn_mfma_f32_16x16x32_bf16(Bt[n][k], At[m][k], acc[ai][bj][m][n], 0, 0, 0); __builtin_amdgcn_s_setprio(0); } while (0)
; #define PG8_WAIT_V(n) asm volatile("s_waitcnt vmcnt(" #n ")" ::: "memory")
; #define PG8_WAIT_L(n) asm volatile("s_waitcnt lgkmcnt(" #n ")" ::: "memory")
; template <class Epi, class Sched, bool ALIGN_EPI = false, bool SP2 = false>
; __device__ __forceinline__ void gemm_phase(PG8_LAS unsigned char* lds, const Gemm g, const Sched& S, const Epi& E, const int tid) {
;     ...
;             const bool last = (t == nt - 2);
;             const char* a1 = cA + (size_t)(t + 1) * kstep;
;             const char* a2 = last ? nA : cA + (size_t)(t + 2) * kstep; const char* b2 = last ? nB : cB + (size_t)(t + 2) * kstep;
;             const char* a3 = a2 + kstep; const char* b3 = b2 + kstep;
;             if (last && has_next) S.a_ready(nxt);
;             if constexpr (SP2) {
;             PG8_LDB(B0, 0, 0); PG8_LDB(B1, 0, 1); PG8_SCHED; PG8_LDA(At, 0, 0); PG8_STAGE(PG8_SA(1, 1), a1 + hstepA, voffA);
;             PG8_WAIT_V(8); PG8_WAIT_L(0); PG8_BAR; PG8_MMA(0, 0, At, B0); PG8_MMA(0, 1, At, B1); PG8_BAR; PG8_SCHED;
;             PG8_LDA(At, 0, 1); PG8_STAGE(PG8_SB(0, 0), b2, voffB); PG8_STAGE(PG8_SB(0, 1), b2 + hstep, voffB); PG8_STAGE(PG8_SA(0, 0), a2, voffA);
;             PG8_WAIT_V(8); PG8_WAIT_L(0); PG8_BAR; PG8_MMA(1, 0, At, B0); PG8_MMA(1, 1, At, B1); PG8_BAR; PG8_SCHED;
.Lsp_4:
	ds_read_b128 v[144:147], v154
	ds_read_b128 v[148:151], v154 offset:1024
	ds_read_b128 v[160:163], v154 offset:2048
	ds_read_b128 v[164:167], v154 offset:3072
	ds_read_b128 v[168:171], v155
	ds_read_b128 v[172:175], v155 offset:1024
	ds_read_b128 v[176:179], v155 offset:2048
	ds_read_b128 v[180:183], v155 offset:3072
	s_add_u32 s26, s24, 0xfffc0080
	s_addc_u32 s27, s25, -1
	s_cmp_eq_u32 s58, 12
	s_cselect_b32 s29, s17, s27
	s_cselect_b32 s28, s54, s26
	s_cselect_b32 s27, s15, s57
	s_cselect_b32 s26, s55, s56
	v_lshl_add_u64 v[196:197], s[24:25], 0, v[136:137]
	s_add_i32 m0, s39, 0xc000
	ds_read_b128 v[184:187], v156
	ds_read_b128 v[188:191], v156 offset:1024
	ds_read_b128 v[192:195], v156 offset:2048
	ds_read_b128 v[200:203], v156 offset:3072
	ds_read_b128 v[204:207], v156 offset:4096
	ds_read_b128 v[208:211], v156 offset:5120
	ds_read_b128 v[212:215], v156 offset:6144
	ds_read_b128 v[216:219], v156 offset:7168
	global_load_lds_dwordx4 v[196:197], off
	v_lshl_add_u64 v[196:197], s[24:25], 0, v[138:139]
	s_add_i32 m0, s39, 0xe000
	s_nop 0
	global_load_lds_dwordx4 v[196:197], off
	s_waitcnt vmcnt(8)
	s_waitcnt lgkmcnt(0)
	s_barrier
	s_waitcnt lgkmcnt(0)
	v_mfma_f32_16x16x32_bf16 v[124:127], v[144:147], v[184:187], v[124:127]
	v_mfma_f32_16x16x32_bf16 v[120:123], v[160:163], v[184:187], v[120:123]
	v_mfma_f32_16x16x32_bf16 v[108:111], v[144:147], v[192:195], v[108:111]
	v_mfma_f32_16x16x32_bf16 v[104:107], v[160:163], v[192:195], v[104:107]
	v_mfma_f32_16x16x32_bf16 v[92:95], v[144:147], v[204:207], v[92:95]
	v_mfma_f32_16x16x32_bf16 v[88:91], v[160:163], v[204:207], v[88:91]
	v_mfma_f32_16x16x32_bf16 v[76:79], v[144:147], v[212:215], v[76:79]
	v_mfma_f32_16x16x32_bf16 v[72:75], v[160:163], v[212:215], v[72:75]
	v_mfma_f32_16x16x32_bf16 v[124:127], v[148:151], v[188:191], v[124:127]
	v_mfma_f32_16x16x32_bf16 v[120:123], v[164:167], v[188:191], v[120:123]
	v_mfma_f32_16x16x32_bf16 v[108:111], v[148:151], v[200:203], v[108:111]
	v_mfma_f32_16x16x32_bf16 v[104:107], v[164:167], v[200:203], v[104:107]
	v_mfma_f32_16x16x32_bf16 v[92:95], v[148:151], v[208:211], v[92:95]
	v_mfma_f32_16x16x32_bf16 v[88:91], v[164:167], v[208:211], v[88:91]
	v_mfma_f32_16x16x32_bf16 v[76:79], v[148:151], v[216:219], v[76:79]
	v_mfma_f32_16x16x32_bf16 v[72:75], v[164:167], v[216:219], v[72:75]
	v_mfma_f32_16x16x32_bf16 v[116:119], v[168:171], v[184:187], v[116:119]
	v_mfma_f32_16x16x32_bf16 v[112:115], v[176:179], v[184:187], v[112:115]
	v_mfma_f32_16x16x32_bf16 v[100:103], v[168:171], v[192:195], v[100:103]
	v_mfma_f32_16x16x32_bf16 v[96:99], v[176:179], v[192:195], v[96:99]
	v_mfma_f32_16x16x32_bf16 v[84:87], v[168:171], v[204:207], v[84:87]
	v_mfma_f32_16x16x32_bf16 v[80:83], v[176:179], v[204:207], v[80:83]
	v_mfma_f32_16x16x32_bf16 v[68:71], v[168:171], v[212:215], v[68:71]
	v_mfma_f32_16x16x32_bf16 v[64:67], v[176:179], v[212:215], v[64:67]
	v_mfma_f32_16x16x32_bf16 v[116:119], v[172:175], v[188:191], v[116:119]
	v_mfma_f32_16x16x32_bf16 v[112:115], v[180:183], v[188:191], v[112:115]
	v_mfma_f32_16x16x32_bf16 v[100:103], v[172:175], v[200:203], v[100:103]
	v_mfma_f32_16x16x32_bf16 v[96:99], v[180:183], v[200:203], v[96:99]
	v_mfma_f32_16x16x32_bf16 v[84:87], v[172:175], v[208:211], v[84:87]
	v_mfma_f32_16x16x32_bf16 v[80:83], v[180:183], v[208:211], v[80:83]
	v_mfma_f32_16x16x32_bf16 v[68:71], v[172:175], v[216:219], v[68:71]
	v_mfma_f32_16x16x32_bf16 v[64:67], v[180:183], v[216:219], v[64:67]
	s_barrier
	s_mov_b32 m0, s23
	v_lshl_add_u64 v[196:197], s[26:27], 0, v[132:133]
	s_add_u32 s60, s26, 0x40000
	ds_read_b128 v[184:187], v156 offset:16384
	ds_read_b128 v[188:191], v156 offset:17408
	ds_read_b128 v[192:195], v156 offset:18432
	ds_read_b128 v[200:203], v156 offset:19456
	ds_read_b128 v[204:207], v156 offset:20480
	ds_read_b128 v[208:211], v156 offset:21504
	ds_read_b128 v[212:215], v156 offset:22528
	ds_read_b128 v[216:219], v156 offset:23552
	global_load_lds_dwordx4 v[196:197], off
	v_lshl_add_u64 v[220:221], s[26:27], 0, v[128:129]
	s_mov_b32 m0, s36
	s_addc_u32 s61, s27, 0
	global_load_lds_dwordx4 v[220:221], off
	v_lshl_add_u64 v[222:223], s[60:61], 0, v[132:133]
	s_mov_b32 m0, s37
	v_lshl_add_u64 v[224:225], s[28:29], 0, v[130:131]
	global_load_lds_dwordx4 v[222:223], off
	v_lshl_add_u64 v[222:223], s[60:61], 0, v[128:129]
	s_mov_b32 m0, s38
	s_nop 0
	global_load_lds_dwordx4 v[222:223], off
	v_lshl_add_u64 v[222:223], s[28:29], 0, v[134:135]
	s_mov_b32 m0, s39
	s_nop 0
	global_load_lds_dwordx4 v[222:223], off
	s_mov_b32 m0, s40
	s_nop 0
	global_load_lds_dwordx4 v[224:225], off
	s_waitcnt vmcnt(8)
	s_waitcnt lgkmcnt(0)
	s_barrier
; #define PG8_STAGE(bufoff, gbase, voff) do { _Pragma("unroll") for (int _i = 0; _i < 2; ++_i) \
;         __builtin_amdgcn_global_load_lds((const unsigned*)((const char*)(gbase) + (voff)[_i]), (PG8_LAS unsigned*)(lds + (bufoff) + ldsw + _i * 8192), 16, 0, 0); } while (0)
; #define PG8_LDA(dst, b, h) do { _Pragma("unroll") for (int m = 0; m < 4; ++m) _Pragma("unroll") for (int k = 0; k < 2; ++k) dst[m][k] = *(const PG8_LAS bf16x8*)(lds + PG8_SA(b, h) + aoff + m * 2048 + k * 1024); } while (0)
; #define PG8_LDB(dst, b, h) do { _Pragma("unroll") for (int n = 0; n < 2; ++n) _Pragma("unroll") for (int k = 0; k < 2; ++k) dst[n][k] = *(const PG8_LAS bf16x8*)(lds + PG8_SB(b, h) + boff + n * 2048 + k * 1024); } while (0)
; #define PG8_MMA(ai, bj, At, Bt) do { __builtin_amdgcn_s_setprio(1); _Pragma("unroll") for (int m = 0; m < 4; ++m) _Pragma("unroll") for (int n = 0; n < 2; ++n) _Pragma("unroll") for (int k = 0; k < 2; ++k) \
;         acc[ai][bj][m][n] = __builtin_amdgcn_mfma_f32_16x16x32_bf16(Bt[n][k], At[m][k], acc[ai][bj][m][n], 0, 0, 0); __builtin_amdgcn_s_setprio(0); } while (0)
; #define PG8_WAIT_V(n) asm volatile("s_waitcnt vmcnt(" #n ")" ::: "memory")
; #define PG8_WAIT_L(n) asm volatile("s_waitcnt lgkmcnt(" #n ")" ::: "memory")
; #define PG8_BAR __builtin_amdgcn_s_barrier()
; #define PG8_SCHED __builtin_amdgcn_sched_barrier(0)
; template <class Epi, class Sched, bool ALIGN_EPI = false, bool SP2 = false>
; __device__ __forceinline__ void gemm_phase(PG8_LAS unsigned char* lds, const Gemm g, const Sched& S, const Epi& E, const int tid) {
;     ...
;             PG8_WAIT_V(8); PG8_WAIT_L(0); PG8_BAR; PG8_MMA(1, 0, At, B0); PG8_MMA(1, 1, At, B1); PG8_BAR; PG8_SCHED;
;             PG8_LDB(B0, 1, 0); PG8_LDB(B1, 1, 1); PG8_SCHED; PG8_LDA(At, 1, 0); PG8_STAGE(PG8_SA(0, 1), a2 + hstepA, voffA);
;             PG8_WAIT_V(8); PG8_WAIT_L(0); PG8_BAR; PG8_MMA(0, 0, At, B0); PG8_MMA(0, 1, At, B1); PG8_BAR; PG8_SCHED;
	s_waitcnt lgkmcnt(0)
	v_mfma_f32_16x16x32_bf16 v[60:63], v[144:147], v[184:187], v[60:63]
	v_mfma_f32_16x16x32_bf16 v[56:59], v[160:163], v[184:187], v[56:59]
	v_mfma_f32_16x16x32_bf16 v[44:47], v[144:147], v[192:195], v[44:47]
	v_mfma_f32_16x16x32_bf16 v[40:43], v[160:163], v[192:195], v[40:43]
	v_mfma_f32_16x16x32_bf16 v[28:31], v[144:147], v[204:207], v[28:31]
	v_mfma_f32_16x16x32_bf16 v[24:27], v[160:163], v[204:207], v[24:27]
	v_mfma_f32_16x16x32_bf16 v[12:15], v[144:147], v[212:215], v[12:15]
	v_mfma_f32_16x16x32_bf16 v[8:11], v[160:163], v[212:215], v[8:11]
	v_mfma_f32_16x16x32_bf16 v[60:63], v[148:151], v[188:191], v[60:63]
	v_mfma_f32_16x16x32_bf16 v[56:59], v[164:167], v[188:191], v[56:59]
	v_mfma_f32_16x16x32_bf16 v[44:47], v[148:151], v[200:203], v[44:47]
	v_mfma_f32_16x16x32_bf16 v[40:43], v[164:167], v[200:203], v[40:43]
	v_mfma_f32_16x16x32_bf16 v[28:31], v[148:151], v[208:211], v[28:31]
	v_mfma_f32_16x16x32_bf16 v[24:27], v[164:167], v[208:211], v[24:27]
	v_mfma_f32_16x16x32_bf16 v[12:15], v[148:151], v[216:219], v[12:15]
	v_mfma_f32_16x16x32_bf16 v[8:11], v[164:167], v[216:219], v[8:11]
	v_mfma_f32_16x16x32_bf16 v[52:55], v[168:171], v[184:187], v[52:55]
	v_mfma_f32_16x16x32_bf16 v[48:51], v[176:179], v[184:187], v[48:51]
	v_mfma_f32_16x16x32_bf16 v[36:39], v[168:171], v[192:195], v[36:39]
	v_mfma_f32_16x16x32_bf16 v[32:35], v[176:179], v[192:195], v[32:35]
	v_mfma_f32_16x16x32_bf16 v[20:23], v[168:171], v[204:207], v[20:23]
	v_mfma_f32_16x16x32_bf16 v[16:19], v[176:179], v[204:207], v[16:19]
	v_mfma_f32_16x16x32_bf16 v[4:7], v[168:171], v[212:215], v[4:7]
	v_mfma_f32_16x16x32_bf16 v[0:3], v[176:179], v[212:215], v[0:3]
	v_mfma_f32_16x16x32_bf16 v[52:55], v[172:175], v[188:191], v[52:55]
	v_mfma_f32_16x16x32_bf16 v[48:51], v[180:183], v[188:191], v[48:51]
	v_mfma_f32_16x16x32_bf16 v[36:39], v[172:175], v[200:203], v[36:39]
	v_mfma_f32_16x16x32_bf16 v[32:35], v[180:183], v[200:203], v[32:35]
	v_mfma_f32_16x16x32_bf16 v[20:23], v[172:175], v[208:211], v[20:23]
	v_mfma_f32_16x16x32_bf16 v[16:19], v[180:183], v[208:211], v[16:19]
	v_mfma_f32_16x16x32_bf16 v[4:7], v[172:175], v[216:219], v[4:7]
	v_mfma_f32_16x16x32_bf16 v[0:3], v[180:183], v[216:219], v[0:3]
	s_barrier
	ds_read_b128 v[144:147], v157
	ds_read_b128 v[148:151], v157 offset:1024
	ds_read_b128 v[160:163], v157 offset:2048
	ds_read_b128 v[164:167], v157 offset:3072
	ds_read_b128 v[168:171], v158
	ds_read_b128 v[172:175], v158 offset:1024
	ds_read_b128 v[176:179], v158 offset:2048
	ds_read_b128 v[180:183], v158 offset:3072
	s_add_u32 s28, s28, 0x40000
	s_addc_u32 s29, s29, 0
	s_mov_b32 m0, s41
	v_lshl_add_u64 v[226:227], s[28:29], 0, v[134:135]
	ds_read_b128 v[184:187], v156 offset:32768
	ds_read_b128 v[188:191], v156 offset:33792
	ds_read_b128 v[192:195], v156 offset:34816
	ds_read_b128 v[200:203], v156 offset:35840
	ds_read_b128 v[204:207], v156 offset:36864
	ds_read_b128 v[208:211], v156 offset:37888
	ds_read_b128 v[212:215], v156 offset:38912
	ds_read_b128 v[216:219], v156 offset:39936
	global_load_lds_dwordx4 v[226:227], off
	v_lshl_add_u64 v[226:227], s[28:29], 0, v[130:131]
	s_mov_b32 m0, s42
	s_nop 0
	global_load_lds_dwordx4 v[226:227], off
	s_waitcnt vmcnt(8)
	s_waitcnt lgkmcnt(0)
	s_barrier
	s_waitcnt lgkmcnt(0)
	v_mfma_f32_16x16x32_bf16 v[124:127], v[144:147], v[184:187], v[124:127]
	v_mfma_f32_16x16x32_bf16 v[120:123], v[160:163], v[184:187], v[120:123]
	v_mfma_f32_16x16x32_bf16 v[108:111], v[144:147], v[192:195], v[108:111]
	v_mfma_f32_16x16x32_bf16 v[104:107], v[160:163], v[192:195], v[104:107]
	v_mfma_f32_16x16x32_bf16 v[92:95], v[144:147], v[204:207], v[92:95]
	v_mfma_f32_16x16x32_bf16 v[88:91], v[160:163], v[204:207], v[88:91]
	v_mfma_f32_16x16x32_bf16 v[76:79], v[144:147], v[212:215], v[76:79]
	v_mfma_f32_16x16x32_bf16 v[72:75], v[160:163], v[212:215], v[72:75]
	v_mfma_f32_16x16x32_bf16 v[124:127], v[148:151], v[188:191], v[124:127]
	v_mfma_f32_16x16x32_bf16 v[120:123], v[164:167], v[188:191], v[120:123]
	v_mfma_f32_16x16x32_bf16 v[108:111], v[148:151], v[200:203], v[108:111]
	v_mfma_f32_16x16x32_bf16 v[104:107], v[164:167], v[200:203], v[104:107]
	v_mfma_f32_16x16x32_bf16 v[92:95], v[148:151], v[208:211], v[92:95]
	v_mfma_f32_16x16x32_bf16 v[88:91], v[164:167], v[208:211], v[88:91]
	v_mfma_f32_16x16x32_bf16 v[76:79], v[148:151], v[216:219], v[76:79]
	v_mfma_f32_16x16x32_bf16 v[72:75], v[164:167], v[216:219], v[72:75]
	v_mfma_f32_16x16x32_bf16 v[116:119], v[168:171], v[184:187], v[116:119]
	v_mfma_f32_16x16x32_bf16 v[112:115], v[176:179], v[184:187], v[112:115]
	v_mfma_f32_16x16x32_bf16 v[100:103], v[168:171], v[192:195], v[100:103]
	v_mfma_f32_16x16x32_bf16 v[96:99], v[176:179], v[192:195], v[96:99]
	v_mfma_f32_16x16x32_bf16 v[84:87], v[168:171], v[204:207], v[84:87]
	v_mfma_f32_16x16x32_bf16 v[80:83], v[176:179], v[204:207], v[80:83]
	v_mfma_f32_16x16x32_bf16 v[68:71], v[168:171], v[212:215], v[68:71]
	v_mfma_f32_16x16x32_bf16 v[64:67], v[176:179], v[212:215], v[64:67]
	v_mfma_f32_16x16x32_bf16 v[116:119], v[172:175], v[188:191], v[116:119]
	v_mfma_f32_16x16x32_bf16 v[112:115], v[180:183], v[188:191], v[112:115]
	v_mfma_f32_16x16x32_bf16 v[100:103], v[172:175], v[200:203], v[100:103]
	v_mfma_f32_16x16x32_bf16 v[96:99], v[180:183], v[200:203], v[96:99]
	v_mfma_f32_16x16x32_bf16 v[84:87], v[172:175], v[208:211], v[84:87]
	v_mfma_f32_16x16x32_bf16 v[80:83], v[180:183], v[208:211], v[80:83]
	v_mfma_f32_16x16x32_bf16 v[68:71], v[172:175], v[216:219], v[68:71]
	v_mfma_f32_16x16x32_bf16 v[64:67], v[180:183], v[216:219], v[64:67]
	s_barrier
; #define PG8_STAGE(bufoff, gbase, voff) do { _Pragma("unroll") for (int _i = 0; _i < 2; ++_i) \
;         __builtin_amdgcn_global_load_lds((const unsigned*)((const char*)(gbase) + (voff)[_i]), (PG8_LAS unsigned*)(lds + (bufoff) + ldsw + _i * 8192), 16, 0, 0); } while (0)
; #define PG8_LDA(dst, b, h) do { _Pragma("unroll") for (int m = 0; m < 4; ++m) _Pragma("unroll") for (int k = 0; k < 2; ++k) dst[m][k] = *(const PG8_LAS bf16x8*)(lds + PG8_SA(b, h) + aoff + m * 2048 + k * 1024); } while (0)
; #define PG8_MMA(ai, bj, At, Bt) do { __builtin_amdgcn_s_setprio(1); _Pragma("unroll") for (int m = 0; m < 4; ++m) _Pragma("unroll") for (int n = 0; n < 2; ++n) _Pragma("unroll") for (int k = 0; k < 2; ++k) \
;         acc[ai][bj][m][n] = __builtin_amdgcn_mfma_f32_16x16x32_bf16(Bt[n][k], At[m][k], acc[ai][bj][m][n], 0, 0, 0); __builtin_amdgcn_s_setprio(0); } while (0)
; #define PG8_WAIT_V(n) asm volatile("s_waitcnt vmcnt(" #n ")" ::: "memory")
; #define PG8_WAIT_L(n) asm volatile("s_waitcnt lgkmcnt(" #n ")" ::: "memory")
; #define PG8_BAR __builtin_amdgcn_s_barrier()
; #define PG8_SCHED __builtin_amdgcn_sched_barrier(0)
; __device__ __forceinline__ float ss_scale(const u64* ss, int row) { return __builtin_amdgcn_rsqf((float)ss[row] * (1.f / 4294967296.f / 1024.f) + EPS); }
; template <class Epi, class Sched, bool ALIGN_EPI = false, bool SP2 = false>
; __device__ __forceinline__ void gemm_phase(PG8_LAS unsigned char* lds, const Gemm g, const Sched& S, const Epi& E, const int tid) {
;     ...
;             PG8_LDA(At, 1, 1); PG8_STAGE(PG8_SB(1, 0), b3, voffB); PG8_STAGE(PG8_SB(1, 1), b3 + hstep, voffB); PG8_STAGE(PG8_SA(1, 0), a3, voffA);
;             PG8_WAIT_V(8); PG8_WAIT_L(0); PG8_BAR; PG8_MMA(1, 0, At, B0); PG8_MMA(1, 1, At, B1); PG8_BAR; PG8_SCHED;
;     __device__ __forceinline__ void operator()(const f32x4 (&acc)[2][2][4][2], const pg8::Unit& u, int wr, int wc, int fr, int fq) const {
;         const int row0 = u.pm * 256 + wr * 64 + fr, col0 = u.pn * 128 + wc * 32 + 8 * fq;
; #pragma unroll
;         for (int ai = 0; ai < 2; ++ai)
; #pragma unroll
;             for (int m = 0; m < 4; ++m) {
;                 const int row = row0 + ai * 128 + m * 16;
;                 float s = ss_scale(ss, row);
	s_mov_b32 m0, s45
	v_lshl_add_u64 v[196:197], v[196:197], 0, s[10:11]
	s_add_u32 s26, s26, 0x40080
	ds_read_b128 v[184:187], v156 offset:49152
	ds_read_b128 v[188:191], v156 offset:50176
	ds_read_b128 v[192:195], v156 offset:51200
	ds_read_b128 v[200:203], v156 offset:52224
	ds_read_b128 v[204:207], v156 offset:53248
	ds_read_b128 v[208:211], v156 offset:54272
	ds_read_b128 v[212:215], v156 offset:55296
	ds_read_b128 v[216:219], v156 offset:56320
	global_load_lds_dwordx4 v[196:197], off
	v_lshl_add_u64 v[196:197], v[220:221], 0, s[10:11]
	s_mov_b32 m0, s46
	s_addc_u32 s27, s27, 0
	global_load_lds_dwordx4 v[196:197], off
	v_lshl_add_u64 v[196:197], s[26:27], 0, v[132:133]
	s_mov_b32 m0, s49
	s_nop 0
	global_load_lds_dwordx4 v[196:197], off
	v_lshl_add_u64 v[196:197], s[26:27], 0, v[128:129]
	s_mov_b32 m0, s50
	s_nop 0
	global_load_lds_dwordx4 v[196:197], off
	v_lshl_add_u64 v[196:197], v[222:223], 0, s[10:11]
	s_mov_b32 m0, s47
	s_nop 0
	global_load_lds_dwordx4 v[196:197], off
	v_lshl_add_u64 v[196:197], v[224:225], 0, s[10:11]
	s_mov_b32 m0, s48
	s_nop 0
	global_load_lds_dwordx4 v[196:197], off
	s_waitcnt vmcnt(8)
	s_waitcnt lgkmcnt(0)
	s_barrier
	s_waitcnt lgkmcnt(0)
	v_mfma_f32_16x16x32_bf16 v[60:63], v[144:147], v[184:187], v[60:63]
	v_mfma_f32_16x16x32_bf16 v[56:59], v[160:163], v[184:187], v[56:59]
	v_mfma_f32_16x16x32_bf16 v[44:47], v[144:147], v[192:195], v[44:47]
	v_mfma_f32_16x16x32_bf16 v[40:43], v[160:163], v[192:195], v[40:43]
	v_mfma_f32_16x16x32_bf16 v[28:31], v[144:147], v[204:207], v[28:31]
	v_mfma_f32_16x16x32_bf16 v[24:27], v[160:163], v[204:207], v[24:27]
	v_mfma_f32_16x16x32_bf16 v[12:15], v[144:147], v[212:215], v[12:15]
	v_mfma_f32_16x16x32_bf16 v[8:11], v[160:163], v[212:215], v[8:11]
	v_mfma_f32_16x16x32_bf16 v[60:63], v[148:151], v[188:191], v[60:63]
	v_mfma_f32_16x16x32_bf16 v[56:59], v[164:167], v[188:191], v[56:59]
	v_mfma_f32_16x16x32_bf16 v[44:47], v[148:151], v[200:203], v[44:47]
	v_mfma_f32_16x16x32_bf16 v[40:43], v[164:167], v[200:203], v[40:43]
	v_mfma_f32_16x16x32_bf16 v[28:31], v[148:151], v[208:211], v[28:31]
	v_mfma_f32_16x16x32_bf16 v[24:27], v[164:167], v[208:211], v[24:27]
	v_mfma_f32_16x16x32_bf16 v[12:15], v[148:151], v[216:219], v[12:15]
	v_mfma_f32_16x16x32_bf16 v[8:11], v[164:167], v[216:219], v[8:11]
	v_mfma_f32_16x16x32_bf16 v[52:55], v[168:171], v[184:187], v[52:55]
	v_mfma_f32_16x16x32_bf16 v[48:51], v[176:179], v[184:187], v[48:51]
	v_mfma_f32_16x16x32_bf16 v[36:39], v[168:171], v[192:195], v[36:39]
	v_mfma_f32_16x16x32_bf16 v[32:35], v[176:179], v[192:195], v[32:35]
	v_mfma_f32_16x16x32_bf16 v[20:23], v[168:171], v[204:207], v[20:23]
	v_mfma_f32_16x16x32_bf16 v[16:19], v[176:179], v[204:207], v[16:19]
	v_mfma_f32_16x16x32_bf16 v[4:7], v[168:171], v[212:215], v[4:7]
	v_mfma_f32_16x16x32_bf16 v[0:3], v[176:179], v[212:215], v[0:3]
	v_mfma_f32_16x16x32_bf16 v[52:55], v[172:175], v[188:191], v[52:55]
	v_mfma_f32_16x16x32_bf16 v[48:51], v[180:183], v[188:191], v[48:51]
	v_mfma_f32_16x16x32_bf16 v[36:39], v[172:175], v[200:203], v[36:39]
	v_mfma_f32_16x16x32_bf16 v[32:35], v[180:183], v[200:203], v[32:35]
	v_mfma_f32_16x16x32_bf16 v[20:23], v[172:175], v[208:211], v[20:23]
	v_mfma_f32_16x16x32_bf16 v[16:19], v[180:183], v[208:211], v[16:19]
	v_mfma_f32_16x16x32_bf16 v[4:7], v[172:175], v[216:219], v[4:7]
	v_mfma_f32_16x16x32_bf16 v[0:3], v[180:183], v[216:219], v[0:3]
	s_barrier
	s_add_i32 s58, s58, 2
	s_add_u32 s24, s24, 0x100
	s_addc_u32 s25, s25, 0
	s_add_u32 s56, s56, 0x100
	s_addc_u32 s57, s57, 0
	s_cmp_gt_u32 s58, 13
	s_cbranch_scc0 .LBB0_849
	s_setprio 0
	v_lshl_add_u32 v144, s22, 8, v152
	v_mov_b32_e32 v145, 0
	v_lshl_add_u64 v[150:151], v[144:145], 3, s[8:9]
	global_load_dwordx2 v[176:177], v[150:151], off
	global_load_dwordx2 v[178:179], v[150:151], off offset:128
	global_load_dwordx2 v[180:181], v[150:151], off offset:256
	global_load_dwordx2 v[182:183], v[150:151], off offset:384
	global_load_dwordx2 v[184:185], v[150:151], off offset:1024
	global_load_dwordx2 v[186:187], v[150:151], off offset:1152
	global_load_dwordx2 v[188:189], v[150:151], off offset:1280
	global_load_dwordx2 v[190:191], v[150:151], off offset:1408
	v_lshl_or_b32 v148, s53, 7, v153
	v_mul_u32_u24_e32 v146, s52, v144
	v_lshl_add_u32 v146, v148, 1, v146
	v_mov_b32_e32 v147, 0
	v_lshl_add_u64 v[146:147], v[146:147], 0, s[6:7]
	v_mov_b32_e32 v164, 1.0
	v_mov_b32_e32 v165, 1.0
	s_mov_b32 s101, 0
	s_and_b64 vcc, exec, s[12:13]
	s_cbranch_vccz .LBB0_852
	s_barrier

; #define PG8_STAGE(bufoff, gbase, voff) do { _Pragma("unroll") for (int _i = 0; _i < 2; ++_i) \
;         __builtin_amdgcn_global_load_lds((const unsigned*)((const char*)(gbase) + (voff)[_i]), (PG8_LAS unsigned*)(lds + (bufoff) + ldsw + _i * 8192), 16, 0, 0); } while (0)
; #define PG8_LDA(dst, b, h) do { _Pragma("unroll") for (int m = 0; m < 4; ++m) _Pragma("unroll") for (int k = 0; k < 2; ++k) dst[m][k] = *(const PG8_LAS bf16x8*)(lds + PG8_SA(b, h) + aoff + m * 2048 + k * 1024); } while (0)
; #define PG8_LDB(dst, b, h) do { _Pragma("unroll") for (int n = 0; n < 2; ++n) _Pragma("unroll") for (int k = 0; k < 2; ++k) dst[n][k] = *(const PG8_LAS bf16x8*)(lds + PG8_SB(b, h) + boff + n * 2048 + k * 1024); } while (0)
; #define PG8_MMA(ai, bj, At, Bt) do { __builtin_amdgcn_s_setprio(1); _Pragma("unroll") for (int m = 0; m < 4; ++m) _Pragma("unroll") for (int n = 0; n < 2; ++n) _Pragma("unroll") for (int k = 0; k < 2; ++k) \
;         acc[ai][bj][m][n] = __builtin_amdgcn_mfma_f32_16x16x32_bf16(Bt[n][k], At[m][k], acc[ai][bj][m][n], 0, 0, 0); __builtin_amdgcn_s_setprio(0); } while (0)
; #define PG8_WAIT_V(n) asm volatile("s_waitcnt vmcnt(" #n ")" ::: "memory")
; #define PG8_WAIT_L(n) asm volatile("s_waitcnt lgkmcnt(" #n ")" ::: "memory")
; template <class Epi, class Sched, bool ALIGN_EPI = false, bool SP2 = false>
; __device__ __forceinline__ void gemm_phase(PG8_LAS unsigned char* lds, const Gemm g, const Sched& S, const Epi& E, const int tid) {
;     ...
;             const bool last = (t == nt - 2);
;             const char* a1 = cA + (size_t)(t + 1) * kstep;
;             const char* a2 = last ? nA : cA + (size_t)(t + 2) * kstep; const char* b2 = last ? nB : cB + (size_t)(t + 2) * kstep;
;             const char* a3 = a2 + kstep; const char* b3 = b2 + kstep;
;             if (last && has_next) S.a_ready(nxt);
;             if constexpr (SP2) {
;             PG8_LDB(B0, 0, 0); PG8_LDB(B1, 0, 1); PG8_SCHED; PG8_LDA(At, 0, 0); PG8_STAGE(PG8_SA(1, 1), a1 + hstepA, voffA);
;             PG8_WAIT_V(8); PG8_WAIT_L(0); PG8_BAR; PG8_MMA(0, 0, At, B0); PG8_MMA(0, 1, At, B1); PG8_BAR; PG8_SCHED;
;             PG8_LDA(At, 0, 1); PG8_STAGE(PG8_SB(0, 0), b2, voffB); PG8_STAGE(PG8_SB(0, 1), b2 + hstep, voffB); PG8_STAGE(PG8_SA(0, 0), a2, voffA);
;             PG8_WAIT_V(8); PG8_WAIT_L(0); PG8_BAR; PG8_MMA(1, 0, At, B0); PG8_MMA(1, 1, At, B1); PG8_BAR; PG8_SCHED;
.LBB0_923:
	s_cmp_lg_u64 s[20:21], 0
	s_cbranch_scc0 .Lsp_5
	s_setprio 1
.Lsp_5:
	ds_read_b128 v[144:147], v166
	ds_read_b128 v[148:151], v166 offset:1024
	ds_read_b128 v[152:155], v166 offset:2048
	ds_read_b128 v[156:159], v166 offset:3072
	ds_read_b128 v[160:163], v167
	ds_read_b128 v[172:175], v167 offset:1024
	ds_read_b128 v[176:179], v167 offset:2048
	ds_read_b128 v[180:183], v167 offset:3072
	s_add_u32 s28, s26, 0x100
	s_addc_u32 s29, s27, 0
	s_cmp_eq_u32 s63, 40
	s_cselect_b32 s35, s7, s29
	s_cselect_b32 s34, s6, s28
	s_cselect_b32 s31, s25, s62
	s_cselect_b32 s30, s24, s61
	v_lshl_add_u64 v[196:197], s[26:27], 0, v[136:137]
	s_add_i32 m0, s42, 0xc000
	ds_read_b128 v[184:187], v168
	ds_read_b128 v[188:191], v168 offset:1024
	ds_read_b128 v[192:195], v168 offset:2048
	ds_read_b128 v[200:203], v168 offset:3072
	ds_read_b128 v[204:207], v168 offset:4096
	ds_read_b128 v[208:211], v168 offset:5120
	ds_read_b128 v[212:215], v168 offset:6144
	ds_read_b128 v[216:219], v168 offset:7168
	global_load_lds_dwordx4 v[196:197], off
	v_lshl_add_u64 v[196:197], s[26:27], 0, v[138:139]
	s_add_i32 m0, s42, 0xe000
	s_nop 0
	global_load_lds_dwordx4 v[196:197], off
	s_waitcnt vmcnt(8)
	s_waitcnt lgkmcnt(0)
	s_barrier
	s_waitcnt lgkmcnt(0)
	v_mfma_f32_16x16x32_bf16 v[124:127], v[144:147], v[184:187], v[124:127]
	v_mfma_f32_16x16x32_bf16 v[120:123], v[152:155], v[184:187], v[120:123]
	v_mfma_f32_16x16x32_bf16 v[108:111], v[144:147], v[192:195], v[108:111]
	v_mfma_f32_16x16x32_bf16 v[104:107], v[152:155], v[192:195], v[104:107]
	v_mfma_f32_16x16x32_bf16 v[92:95], v[144:147], v[204:207], v[92:95]
	v_mfma_f32_16x16x32_bf16 v[88:91], v[152:155], v[204:207], v[88:91]
	v_mfma_f32_16x16x32_bf16 v[76:79], v[144:147], v[212:215], v[76:79]
	v_mfma_f32_16x16x32_bf16 v[72:75], v[152:155], v[212:215], v[72:75]
	v_mfma_f32_16x16x32_bf16 v[124:127], v[148:151], v[188:191], v[124:127]
	v_mfma_f32_16x16x32_bf16 v[120:123], v[156:159], v[188:191], v[120:123]
	v_mfma_f32_16x16x32_bf16 v[108:111], v[148:151], v[200:203], v[108:111]
	v_mfma_f32_16x16x32_bf16 v[104:107], v[156:159], v[200:203], v[104:107]
	v_mfma_f32_16x16x32_bf16 v[92:95], v[148:151], v[208:211], v[92:95]
	v_mfma_f32_16x16x32_bf16 v[88:91], v[156:159], v[208:211], v[88:91]
	v_mfma_f32_16x16x32_bf16 v[76:79], v[148:151], v[216:219], v[76:79]
	v_mfma_f32_16x16x32_bf16 v[72:75], v[156:159], v[216:219], v[72:75]
	v_mfma_f32_16x16x32_bf16 v[116:119], v[160:163], v[184:187], v[116:119]
	v_mfma_f32_16x16x32_bf16 v[112:115], v[176:179], v[184:187], v[112:115]
	v_mfma_f32_16x16x32_bf16 v[100:103], v[160:163], v[192:195], v[100:103]
	v_mfma_f32_16x16x32_bf16 v[96:99], v[176:179], v[192:195], v[96:99]
	v_mfma_f32_16x16x32_bf16 v[84:87], v[160:163], v[204:207], v[84:87]
	v_mfma_f32_16x16x32_bf16 v[80:83], v[176:179], v[204:207], v[80:83]
	v_mfma_f32_16x16x32_bf16 v[68:71], v[160:163], v[212:215], v[68:71]
	v_mfma_f32_16x16x32_bf16 v[64:67], v[176:179], v[212:215], v[64:67]
	v_mfma_f32_16x16x32_bf16 v[116:119], v[172:175], v[188:191], v[116:119]
	v_mfma_f32_16x16x32_bf16 v[112:115], v[180:183], v[188:191], v[112:115]
	v_mfma_f32_16x16x32_bf16 v[100:103], v[172:175], v[200:203], v[100:103]
	v_mfma_f32_16x16x32_bf16 v[96:99], v[180:183], v[200:203], v[96:99]
	v_mfma_f32_16x16x32_bf16 v[84:87], v[172:175], v[208:211], v[84:87]
	v_mfma_f32_16x16x32_bf16 v[80:83], v[180:183], v[208:211], v[80:83]
	v_mfma_f32_16x16x32_bf16 v[68:71], v[172:175], v[216:219], v[68:71]
	v_mfma_f32_16x16x32_bf16 v[64:67], v[180:183], v[216:219], v[64:67]
	s_barrier
	s_mov_b32 m0, s38
	v_lshl_add_u64 v[196:197], s[30:31], 0, v[130:131]
	s_add_u32 s26, s30, 0xb0000
	ds_read_b128 v[184:187], v168 offset:16384
	ds_read_b128 v[188:191], v168 offset:17408
	ds_read_b128 v[192:195], v168 offset:18432
	ds_read_b128 v[200:203], v168 offset:19456
	ds_read_b128 v[204:207], v168 offset:20480
	ds_read_b128 v[208:211], v168 offset:21504
	ds_read_b128 v[212:215], v168 offset:22528
	ds_read_b128 v[216:219], v168 offset:23552
	global_load_lds_dwordx4 v[196:197], off
	v_lshl_add_u64 v[220:221], s[30:31], 0, v[134:135]
	s_mov_b32 m0, s39
	s_addc_u32 s27, s31, 0
	global_load_lds_dwordx4 v[220:221], off
	v_lshl_add_u64 v[222:223], s[26:27], 0, v[130:131]
	s_mov_b32 m0, s40
	v_lshl_add_u64 v[224:225], s[34:35], 0, v[132:133]
	global_load_lds_dwordx4 v[222:223], off
	v_lshl_add_u64 v[222:223], s[26:27], 0, v[134:135]
	s_mov_b32 m0, s41
	s_nop 0
	global_load_lds_dwordx4 v[222:223], off
	v_lshl_add_u64 v[222:223], s[34:35], 0, v[128:129]
	s_mov_b32 m0, s42
	s_nop 0
	global_load_lds_dwordx4 v[222:223], off
	s_mov_b32 m0, s43
	s_nop 0
	global_load_lds_dwordx4 v[224:225], off
	s_waitcnt vmcnt(8)
	s_waitcnt lgkmcnt(0)
	s_barrier
; #define PG8_STAGE(bufoff, gbase, voff) do { _Pragma("unroll") for (int _i = 0; _i < 2; ++_i) \
;         __builtin_amdgcn_global_load_lds((const unsigned*)((const char*)(gbase) + (voff)[_i]), (PG8_LAS unsigned*)(lds + (bufoff) + ldsw + _i * 8192), 16, 0, 0); } while (0)
; #define PG8_LDA(dst, b, h) do { _Pragma("unroll") for (int m = 0; m < 4; ++m) _Pragma("unroll") for (int k = 0; k < 2; ++k) dst[m][k] = *(const PG8_LAS bf16x8*)(lds + PG8_SA(b, h) + aoff + m * 2048 + k * 1024); } while (0)
; #define PG8_LDB(dst, b, h) do { _Pragma("unroll") for (int n = 0; n < 2; ++n) _Pragma("unroll") for (int k = 0; k < 2; ++k) dst[n][k] = *(const PG8_LAS bf16x8*)(lds + PG8_SB(b, h) + boff + n * 2048 + k * 1024); } while (0)
; #define PG8_MMA(ai, bj, At, Bt) do { __builtin_amdgcn_s_setprio(1); _Pragma("unroll") for (int m = 0; m < 4; ++m) _Pragma("unroll") for (int n = 0; n < 2; ++n) _Pragma("unroll") for (int k = 0; k < 2; ++k) \
;         acc[ai][bj][m][n] = __builtin_amdgcn_mfma_f32_16x16x32_bf16(Bt[n][k], At[m][k], acc[ai][bj][m][n], 0, 0, 0); __builtin_amdgcn_s_setprio(0); } while (0)
; #define PG8_WAIT_V(n) asm volatile("s_waitcnt vmcnt(" #n ")" ::: "memory")
; #define PG8_WAIT_L(n) asm volatile("s_waitcnt lgkmcnt(" #n ")" ::: "memory")
; #define PG8_BAR __builtin_amdgcn_s_barrier()
; #define PG8_SCHED __builtin_amdgcn_sched_barrier(0)
; template <class Epi, class Sched, bool ALIGN_EPI = false, bool SP2 = false>
; __device__ __forceinline__ void gemm_phase(PG8_LAS unsigned char* lds, const Gemm g, const Sched& S, const Epi& E, const int tid) {
;     ...
;             PG8_WAIT_V(8); PG8_WAIT_L(0); PG8_BAR; PG8_MMA(1, 0, At, B0); PG8_MMA(1, 1, At, B1); PG8_BAR; PG8_SCHED;
;             PG8_LDB(B0, 1, 0); PG8_LDB(B1, 1, 1); PG8_SCHED; PG8_LDA(At, 1, 0); PG8_STAGE(PG8_SA(0, 1), a2 + hstepA, voffA);
;             PG8_WAIT_V(8); PG8_WAIT_L(0); PG8_BAR; PG8_MMA(0, 0, At, B0); PG8_MMA(0, 1, At, B1); PG8_BAR; PG8_SCHED;
	s_waitcnt lgkmcnt(0)
	v_mfma_f32_16x16x32_bf16 v[60:63], v[144:147], v[184:187], v[60:63]
	v_mfma_f32_16x16x32_bf16 v[56:59], v[152:155], v[184:187], v[56:59]
	v_mfma_f32_16x16x32_bf16 v[44:47], v[144:147], v[192:195], v[44:47]
	v_mfma_f32_16x16x32_bf16 v[40:43], v[152:155], v[192:195], v[40:43]
	v_mfma_f32_16x16x32_bf16 v[28:31], v[144:147], v[204:207], v[28:31]
	v_mfma_f32_16x16x32_bf16 v[24:27], v[152:155], v[204:207], v[24:27]
	v_mfma_f32_16x16x32_bf16 v[12:15], v[144:147], v[212:215], v[12:15]
	v_mfma_f32_16x16x32_bf16 v[8:11], v[152:155], v[212:215], v[8:11]
	v_mfma_f32_16x16x32_bf16 v[60:63], v[148:151], v[188:191], v[60:63]
	v_mfma_f32_16x16x32_bf16 v[56:59], v[156:159], v[188:191], v[56:59]
	v_mfma_f32_16x16x32_bf16 v[44:47], v[148:151], v[200:203], v[44:47]
	v_mfma_f32_16x16x32_bf16 v[40:43], v[156:159], v[200:203], v[40:43]
	v_mfma_f32_16x16x32_bf16 v[28:31], v[148:151], v[208:211], v[28:31]
	v_mfma_f32_16x16x32_bf16 v[24:27], v[156:159], v[208:211], v[24:27]
	v_mfma_f32_16x16x32_bf16 v[12:15], v[148:151], v[216:219], v[12:15]
	v_mfma_f32_16x16x32_bf16 v[8:11], v[156:159], v[216:219], v[8:11]
	v_mfma_f32_16x16x32_bf16 v[52:55], v[160:163], v[184:187], v[52:55]
	v_mfma_f32_16x16x32_bf16 v[48:51], v[176:179], v[184:187], v[48:51]
	v_mfma_f32_16x16x32_bf16 v[36:39], v[160:163], v[192:195], v[36:39]
	v_mfma_f32_16x16x32_bf16 v[32:35], v[176:179], v[192:195], v[32:35]
	v_mfma_f32_16x16x32_bf16 v[20:23], v[160:163], v[204:207], v[20:23]
	v_mfma_f32_16x16x32_bf16 v[16:19], v[176:179], v[204:207], v[16:19]
	v_mfma_f32_16x16x32_bf16 v[4:7], v[160:163], v[212:215], v[4:7]
	v_mfma_f32_16x16x32_bf16 v[0:3], v[176:179], v[212:215], v[0:3]
	v_mfma_f32_16x16x32_bf16 v[52:55], v[172:175], v[188:191], v[52:55]
	v_mfma_f32_16x16x32_bf16 v[48:51], v[180:183], v[188:191], v[48:51]
	v_mfma_f32_16x16x32_bf16 v[36:39], v[172:175], v[200:203], v[36:39]
	v_mfma_f32_16x16x32_bf16 v[32:35], v[180:183], v[200:203], v[32:35]
	v_mfma_f32_16x16x32_bf16 v[20:23], v[172:175], v[208:211], v[20:23]
	v_mfma_f32_16x16x32_bf16 v[16:19], v[180:183], v[208:211], v[16:19]
	v_mfma_f32_16x16x32_bf16 v[4:7], v[172:175], v[216:219], v[4:7]
	v_mfma_f32_16x16x32_bf16 v[0:3], v[180:183], v[216:219], v[0:3]
	s_barrier
	ds_read_b128 v[144:147], v169
	ds_read_b128 v[148:151], v169 offset:1024
	ds_read_b128 v[152:155], v169 offset:2048
	ds_read_b128 v[156:159], v169 offset:3072
	ds_read_b128 v[160:163], v170
	ds_read_b128 v[172:175], v170 offset:1024
	ds_read_b128 v[176:179], v170 offset:2048
	ds_read_b128 v[180:183], v170 offset:3072
	s_add_u32 s26, s34, 0xb0000
	s_addc_u32 s27, s35, 0
	s_mov_b32 m0, s44
	v_lshl_add_u64 v[226:227], s[26:27], 0, v[128:129]
	ds_read_b128 v[184:187], v168 offset:32768
	ds_read_b128 v[188:191], v168 offset:33792
	ds_read_b128 v[192:195], v168 offset:34816
	ds_read_b128 v[200:203], v168 offset:35840
	ds_read_b128 v[204:207], v168 offset:36864
	ds_read_b128 v[208:211], v168 offset:37888
	ds_read_b128 v[212:215], v168 offset:38912
	ds_read_b128 v[216:219], v168 offset:39936
	global_load_lds_dwordx4 v[226:227], off
	v_lshl_add_u64 v[226:227], s[26:27], 0, v[132:133]
	s_mov_b32 m0, s45
	s_nop 0
	global_load_lds_dwordx4 v[226:227], off
	s_waitcnt vmcnt(8)
	s_waitcnt lgkmcnt(0)
	s_barrier
	s_waitcnt lgkmcnt(0)
	v_mfma_f32_16x16x32_bf16 v[124:127], v[144:147], v[184:187], v[124:127]
	v_mfma_f32_16x16x32_bf16 v[120:123], v[152:155], v[184:187], v[120:123]
	v_mfma_f32_16x16x32_bf16 v[108:111], v[144:147], v[192:195], v[108:111]
	v_mfma_f32_16x16x32_bf16 v[104:107], v[152:155], v[192:195], v[104:107]
	v_mfma_f32_16x16x32_bf16 v[92:95], v[144:147], v[204:207], v[92:95]
	v_mfma_f32_16x16x32_bf16 v[88:91], v[152:155], v[204:207], v[88:91]
	v_mfma_f32_16x16x32_bf16 v[76:79], v[144:147], v[212:215], v[76:79]
	v_mfma_f32_16x16x32_bf16 v[72:75], v[152:155], v[212:215], v[72:75]
	v_mfma_f32_16x16x32_bf16 v[124:127], v[148:151], v[188:191], v[124:127]
	v_mfma_f32_16x16x32_bf16 v[120:123], v[156:159], v[188:191], v[120:123]
	v_mfma_f32_16x16x32_bf16 v[108:111], v[148:151], v[200:203], v[108:111]
	v_mfma_f32_16x16x32_bf16 v[104:107], v[156:159], v[200:203], v[104:107]
	v_mfma_f32_16x16x32_bf16 v[92:95], v[148:151], v[208:211], v[92:95]
	v_mfma_f32_16x16x32_bf16 v[88:91], v[156:159], v[208:211], v[88:91]
	v_mfma_f32_16x16x32_bf16 v[76:79], v[148:151], v[216:219], v[76:79]
	v_mfma_f32_16x16x32_bf16 v[72:75], v[156:159], v[216:219], v[72:75]
	v_mfma_f32_16x16x32_bf16 v[116:119], v[160:163], v[184:187], v[116:119]
	v_mfma_f32_16x16x32_bf16 v[112:115], v[176:179], v[184:187], v[112:115]
	v_mfma_f32_16x16x32_bf16 v[100:103], v[160:163], v[192:195], v[100:103]
	v_mfma_f32_16x16x32_bf16 v[96:99], v[176:179], v[192:195], v[96:99]
	v_mfma_f32_16x16x32_bf16 v[84:87], v[160:163], v[204:207], v[84:87]
	v_mfma_f32_16x16x32_bf16 v[80:83], v[176:179], v[204:207], v[80:83]
	v_mfma_f32_16x16x32_bf16 v[68:71], v[160:163], v[212:215], v[68:71]
	v_mfma_f32_16x16x32_bf16 v[64:67], v[176:179], v[212:215], v[64:67]
	v_mfma_f32_16x16x32_bf16 v[116:119], v[172:175], v[188:191], v[116:119]
	v_mfma_f32_16x16x32_bf16 v[112:115], v[180:183], v[188:191], v[112:115]
	v_mfma_f32_16x16x32_bf16 v[100:103], v[172:175], v[200:203], v[100:103]
	v_mfma_f32_16x16x32_bf16 v[96:99], v[180:183], v[200:203], v[96:99]
	v_mfma_f32_16x16x32_bf16 v[84:87], v[172:175], v[208:211], v[84:87]
	v_mfma_f32_16x16x32_bf16 v[80:83], v[180:183], v[208:211], v[80:83]
	v_mfma_f32_16x16x32_bf16 v[68:71], v[172:175], v[216:219], v[68:71]
	v_mfma_f32_16x16x32_bf16 v[64:67], v[180:183], v[216:219], v[64:67]
	s_barrier
; #define PG8_STAGE(bufoff, gbase, voff) do { _Pragma("unroll") for (int _i = 0; _i < 2; ++_i) \
;         __builtin_amdgcn_global_load_lds((const unsigned*)((const char*)(gbase) + (voff)[_i]), (PG8_LAS unsigned*)(lds + (bufoff) + ldsw + _i * 8192), 16, 0, 0); } while (0)
; #define PG8_LDA(dst, b, h) do { _Pragma("unroll") for (int m = 0; m < 4; ++m) _Pragma("unroll") for (int k = 0; k < 2; ++k) dst[m][k] = *(const PG8_LAS bf16x8*)(lds + PG8_SA(b, h) + aoff + m * 2048 + k * 1024); } while (0)
; #define PG8_MMA(ai, bj, At, Bt) do { __builtin_amdgcn_s_setprio(1); _Pragma("unroll") for (int m = 0; m < 4; ++m) _Pragma("unroll") for (int n = 0; n < 2; ++n) _Pragma("unroll") for (int k = 0; k < 2; ++k) \
;         acc[ai][bj][m][n] = __builtin_amdgcn_mfma_f32_16x16x32_bf16(Bt[n][k], At[m][k], acc[ai][bj][m][n], 0, 0, 0); __builtin_amdgcn_s_setprio(0); } while (0)
; #define PG8_WAIT_V(n) asm volatile("s_waitcnt vmcnt(" #n ")" ::: "memory")
; #define PG8_WAIT_L(n) asm volatile("s_waitcnt lgkmcnt(" #n ")" ::: "memory")
; #define PG8_BAR __builtin_amdgcn_s_barrier()
; #define PG8_SCHED __builtin_amdgcn_sched_barrier(0)
; template <class Epi, class Sched, bool ALIGN_EPI = false, bool SP2 = false>
; __device__ __forceinline__ void gemm_phase(PG8_LAS unsigned char* lds, const Gemm g, const Sched& S, const Epi& E, const int tid) {
;     ...
;             PG8_LDA(At, 1, 1); PG8_STAGE(PG8_SB(1, 0), b3, voffB); PG8_STAGE(PG8_SB(1, 1), b3 + hstep, voffB); PG8_STAGE(PG8_SA(1, 0), a3, voffA);
;             PG8_WAIT_V(8); PG8_WAIT_L(0); PG8_BAR; PG8_MMA(1, 0, At, B0); PG8_MMA(1, 1, At, B1); PG8_BAR; PG8_SCHED;
	s_mov_b32 m0, s48
	v_lshl_add_u64 v[196:197], v[196:197], 0, s[18:19]
	s_add_u32 s26, s30, 0xb0080
	ds_read_b128 v[184:187], v168 offset:49152
	ds_read_b128 v[188:191], v168 offset:50176
	ds_read_b128 v[192:195], v168 offset:51200
	ds_read_b128 v[200:203], v168 offset:52224
	ds_read_b128 v[204:207], v168 offset:53248
	ds_read_b128 v[208:211], v168 offset:54272
	ds_read_b128 v[212:215], v168 offset:55296
	ds_read_b128 v[216:219], v168 offset:56320
	global_load_lds_dwordx4 v[196:197], off
	v_lshl_add_u64 v[196:197], v[220:221], 0, s[18:19]
	s_mov_b32 m0, s49
	s_addc_u32 s27, s31, 0
	global_load_lds_dwordx4 v[196:197], off
	v_lshl_add_u64 v[196:197], s[26:27], 0, v[130:131]
	s_mov_b32 m0, s52
	s_nop 0
	global_load_lds_dwordx4 v[196:197], off
	v_lshl_add_u64 v[196:197], s[26:27], 0, v[134:135]
	s_mov_b32 m0, s53
	s_nop 0
	global_load_lds_dwordx4 v[196:197], off
	v_lshl_add_u64 v[196:197], v[222:223], 0, s[18:19]
	s_mov_b32 m0, s50
	s_nop 0
	global_load_lds_dwordx4 v[196:197], off
	v_lshl_add_u64 v[196:197], v[224:225], 0, s[18:19]
	s_mov_b32 m0, s51
	s_nop 0
	global_load_lds_dwordx4 v[196:197], off
	s_waitcnt vmcnt(8)
	s_waitcnt lgkmcnt(0)
	s_barrier
	s_waitcnt lgkmcnt(0)
	v_mfma_f32_16x16x32_bf16 v[60:63], v[144:147], v[184:187], v[60:63]
	v_mfma_f32_16x16x32_bf16 v[56:59], v[152:155], v[184:187], v[56:59]
	v_mfma_f32_16x16x32_bf16 v[44:47], v[144:147], v[192:195], v[44:47]
	v_mfma_f32_16x16x32_bf16 v[40:43], v[152:155], v[192:195], v[40:43]
	v_mfma_f32_16x16x32_bf16 v[28:31], v[144:147], v[204:207], v[28:31]
	v_mfma_f32_16x16x32_bf16 v[24:27], v[152:155], v[204:207], v[24:27]
	v_mfma_f32_16x16x32_bf16 v[12:15], v[144:147], v[212:215], v[12:15]
	v_mfma_f32_16x16x32_bf16 v[8:11], v[152:155], v[212:215], v[8:11]
	v_mfma_f32_16x16x32_bf16 v[60:63], v[148:151], v[188:191], v[60:63]
	v_mfma_f32_16x16x32_bf16 v[56:59], v[156:159], v[188:191], v[56:59]
	v_mfma_f32_16x16x32_bf16 v[44:47], v[148:151], v[200:203], v[44:47]
	v_mfma_f32_16x16x32_bf16 v[40:43], v[156:159], v[200:203], v[40:43]
	v_mfma_f32_16x16x32_bf16 v[28:31], v[148:151], v[208:211], v[28:31]
	v_mfma_f32_16x16x32_bf16 v[24:27], v[156:159], v[208:211], v[24:27]
	v_mfma_f32_16x16x32_bf16 v[12:15], v[148:151], v[216:219], v[12:15]
	v_mfma_f32_16x16x32_bf16 v[8:11], v[156:159], v[216:219], v[8:11]
	v_mfma_f32_16x16x32_bf16 v[52:55], v[160:163], v[184:187], v[52:55]
	v_mfma_f32_16x16x32_bf16 v[48:51], v[176:179], v[184:187], v[48:51]
	v_mfma_f32_16x16x32_bf16 v[36:39], v[160:163], v[192:195], v[36:39]
	v_mfma_f32_16x16x32_bf16 v[32:35], v[176:179], v[192:195], v[32:35]
	v_mfma_f32_16x16x32_bf16 v[20:23], v[160:163], v[204:207], v[20:23]
	v_mfma_f32_16x16x32_bf16 v[16:19], v[176:179], v[204:207], v[16:19]
	v_mfma_f32_16x16x32_bf16 v[4:7], v[160:163], v[212:215], v[4:7]
	v_mfma_f32_16x16x32_bf16 v[0:3], v[176:179], v[212:215], v[0:3]
	v_mfma_f32_16x16x32_bf16 v[52:55], v[172:175], v[188:191], v[52:55]
	v_mfma_f32_16x16x32_bf16 v[48:51], v[180:183], v[188:191], v[48:51]
	v_mfma_f32_16x16x32_bf16 v[36:39], v[172:175], v[200:203], v[36:39]
	v_mfma_f32_16x16x32_bf16 v[32:35], v[180:183], v[200:203], v[32:35]
	v_mfma_f32_16x16x32_bf16 v[20:23], v[172:175], v[208:211], v[20:23]
	v_mfma_f32_16x16x32_bf16 v[16:19], v[180:183], v[208:211], v[16:19]
	v_mfma_f32_16x16x32_bf16 v[4:7], v[172:175], v[216:219], v[4:7]
	v_mfma_f32_16x16x32_bf16 v[0:3], v[180:183], v[216:219], v[0:3]
	s_barrier
	s_add_i32 s63, s63, 2
	s_add_u32 s61, s61, 0x100
	s_addc_u32 s62, s62, 0
	s_cmp_gt_u32 s63, 41
	s_mov_b64 s[26:27], s[28:29]
	s_cbranch_scc0 .LBB0_923
	s_setprio 0
	s_and_b64 vcc, exec, s[20:21]
	s_cbranch_vccnz .LBB0_927
	s_andn2_b64 vcc, exec, s[22:23]
	s_cbranch_vccz .LBB0_928

; #define PG8_STAGE(bufoff, gbase, voff) do { _Pragma("unroll") for (int _i = 0; _i < 2; ++_i) \
;         __builtin_amdgcn_global_load_lds((const unsigned*)((const char*)(gbase) + (voff)[_i]), (PG8_LAS unsigned*)(lds + (bufoff) + ldsw + _i * 8192), 16, 0, 0); } while (0)
; #define PG8_LDA(dst, b, h) do { _Pragma("unroll") for (int m = 0; m < 4; ++m) _Pragma("unroll") for (int k = 0; k < 2; ++k) dst[m][k] = *(const PG8_LAS bf16x8*)(lds + PG8_SA(b, h) + aoff + m * 2048 + k * 1024); } while (0)
; #define PG8_LDB(dst, b, h) do { _Pragma("unroll") for (int n = 0; n < 2; ++n) _Pragma("unroll") for (int k = 0; k < 2; ++k) dst[n][k] = *(const PG8_LAS bf16x8*)(lds + PG8_SB(b, h) + boff + n * 2048 + k * 1024); } while (0)
; #define PG8_MMA(ai, bj, At, Bt) do { __builtin_amdgcn_s_setprio(1); _Pragma("unroll") for (int m = 0; m < 4; ++m) _Pragma("unroll") for (int n = 0; n < 2; ++n) _Pragma("unroll") for (int k = 0; k < 2; ++k) \
;         acc[ai][bj][m][n] = __builtin_amdgcn_mfma_f32_16x16x32_bf16(Bt[n][k], At[m][k], acc[ai][bj][m][n], 0, 0, 0); __builtin_amdgcn_s_setprio(0); } while (0)
; #define PG8_WAIT_V(n) asm volatile("s_waitcnt vmcnt(" #n ")" ::: "memory")
; #define PG8_WAIT_L(n) asm volatile("s_waitcnt lgkmcnt(" #n ")" ::: "memory")
; template <class Epi, class Sched, bool ALIGN_EPI = false, bool SP2 = false>
; __device__ __forceinline__ void gemm_phase(PG8_LAS unsigned char* lds, const Gemm g, const Sched& S, const Epi& E, const int tid) {
;     ...
;             const bool last = (t == nt - 2);
;             const char* a1 = cA + (size_t)(t + 1) * kstep;
;             const char* a2 = last ? nA : cA + (size_t)(t + 2) * kstep; const char* b2 = last ? nB : cB + (size_t)(t + 2) * kstep;
;             const char* a3 = a2 + kstep; const char* b3 = b2 + kstep;
;             if (last && has_next) S.a_ready(nxt);
;             if constexpr (SP2) {
;             PG8_LDB(B0, 0, 0); PG8_LDB(B1, 0, 1); PG8_SCHED; PG8_LDA(At, 0, 0); PG8_STAGE(PG8_SA(1, 1), a1 + hstepA, voffA);
;             PG8_WAIT_V(8); PG8_WAIT_L(0); PG8_BAR; PG8_MMA(0, 0, At, B0); PG8_MMA(0, 1, At, B1); PG8_BAR; PG8_SCHED;
;             PG8_LDA(At, 0, 1); PG8_STAGE(PG8_SB(0, 0), b2, voffB); PG8_STAGE(PG8_SB(0, 1), b2 + hstep, voffB); PG8_STAGE(PG8_SA(0, 0), a2, voffA);
;             PG8_WAIT_V(8); PG8_WAIT_L(0); PG8_BAR; PG8_MMA(1, 0, At, B0); PG8_MMA(1, 1, At, B1); PG8_BAR; PG8_SCHED;
.LBB0_1007:
	s_cmp_lg_u64 s[14:15], 0
	s_cbranch_scc0 .Lsp_6
	s_setprio 1
.Lsp_6:
	ds_read_b128 v[144:147], v156
	ds_read_b128 v[148:151], v156 offset:1024
	ds_read_b128 v[162:165], v156 offset:2048
	ds_read_b128 v[166:169], v156 offset:3072
	ds_read_b128 v[170:173], v157
	ds_read_b128 v[174:177], v157 offset:1024
	ds_read_b128 v[178:181], v157 offset:2048
	ds_read_b128 v[182:185], v157 offset:3072
	s_add_u32 s28, s26, 0xfffc0080
	s_addc_u32 s29, s27, -1
	s_cmp_eq_u32 s60, 12
	s_cselect_b32 s31, s19, s29
	s_cselect_b32 s30, s56, s28
	s_cselect_b32 s29, s17, s59
	s_cselect_b32 s28, s57, s58
	v_lshl_add_u64 v[152:153], s[26:27], 0, v[136:137]
	s_add_i32 m0, s41, 0xc000
	ds_read_b128 v[186:189], v158
	ds_read_b128 v[190:193], v158 offset:1024
	ds_read_b128 v[194:197], v158 offset:2048
	ds_read_b128 v[200:203], v158 offset:3072
	ds_read_b128 v[204:207], v158 offset:4096
	ds_read_b128 v[208:211], v158 offset:5120
	ds_read_b128 v[212:215], v158 offset:6144
	ds_read_b128 v[216:219], v158 offset:7168
	global_load_lds_dwordx4 v[152:153], off
	v_lshl_add_u64 v[152:153], s[26:27], 0, v[138:139]
	s_add_i32 m0, s41, 0xe000
	s_nop 0
	global_load_lds_dwordx4 v[152:153], off
	s_waitcnt vmcnt(8)
	s_waitcnt lgkmcnt(0)
	s_barrier
	s_waitcnt lgkmcnt(0)
	v_mfma_f32_16x16x32_bf16 v[124:127], v[144:147], v[186:189], v[124:127]
	v_mfma_f32_16x16x32_bf16 v[120:123], v[162:165], v[186:189], v[120:123]
	v_mfma_f32_16x16x32_bf16 v[108:111], v[144:147], v[194:197], v[108:111]
	v_mfma_f32_16x16x32_bf16 v[104:107], v[162:165], v[194:197], v[104:107]
	v_mfma_f32_16x16x32_bf16 v[92:95], v[144:147], v[204:207], v[92:95]
	v_mfma_f32_16x16x32_bf16 v[88:91], v[162:165], v[204:207], v[88:91]
	v_mfma_f32_16x16x32_bf16 v[76:79], v[144:147], v[212:215], v[76:79]
	v_mfma_f32_16x16x32_bf16 v[72:75], v[162:165], v[212:215], v[72:75]
	v_mfma_f32_16x16x32_bf16 v[124:127], v[148:151], v[190:193], v[124:127]
	v_mfma_f32_16x16x32_bf16 v[120:123], v[166:169], v[190:193], v[120:123]
	v_mfma_f32_16x16x32_bf16 v[108:111], v[148:151], v[200:203], v[108:111]
	v_mfma_f32_16x16x32_bf16 v[104:107], v[166:169], v[200:203], v[104:107]
	v_mfma_f32_16x16x32_bf16 v[92:95], v[148:151], v[208:211], v[92:95]
	v_mfma_f32_16x16x32_bf16 v[88:91], v[166:169], v[208:211], v[88:91]
	v_mfma_f32_16x16x32_bf16 v[76:79], v[148:151], v[216:219], v[76:79]
	v_mfma_f32_16x16x32_bf16 v[72:75], v[166:169], v[216:219], v[72:75]
	v_mfma_f32_16x16x32_bf16 v[116:119], v[170:173], v[186:189], v[116:119]
	v_mfma_f32_16x16x32_bf16 v[112:115], v[178:181], v[186:189], v[112:115]
	v_mfma_f32_16x16x32_bf16 v[100:103], v[170:173], v[194:197], v[100:103]
	v_mfma_f32_16x16x32_bf16 v[96:99], v[178:181], v[194:197], v[96:99]
	v_mfma_f32_16x16x32_bf16 v[84:87], v[170:173], v[204:207], v[84:87]
	v_mfma_f32_16x16x32_bf16 v[80:83], v[178:181], v[204:207], v[80:83]
	v_mfma_f32_16x16x32_bf16 v[68:71], v[170:173], v[212:215], v[68:71]
	v_mfma_f32_16x16x32_bf16 v[64:67], v[178:181], v[212:215], v[64:67]
	v_mfma_f32_16x16x32_bf16 v[116:119], v[174:177], v[190:193], v[116:119]
	v_mfma_f32_16x16x32_bf16 v[112:115], v[182:185], v[190:193], v[112:115]
	v_mfma_f32_16x16x32_bf16 v[100:103], v[174:177], v[200:203], v[100:103]
	v_mfma_f32_16x16x32_bf16 v[96:99], v[182:185], v[200:203], v[96:99]
	v_mfma_f32_16x16x32_bf16 v[84:87], v[174:177], v[208:211], v[84:87]
	v_mfma_f32_16x16x32_bf16 v[80:83], v[182:185], v[208:211], v[80:83]
	v_mfma_f32_16x16x32_bf16 v[68:71], v[174:177], v[216:219], v[68:71]
	v_mfma_f32_16x16x32_bf16 v[64:67], v[182:185], v[216:219], v[64:67]
	s_barrier
	s_mov_b32 m0, s25
	v_lshl_add_u64 v[152:153], s[28:29], 0, v[132:133]
	s_add_u32 s62, s28, 0x40000
	ds_read_b128 v[186:189], v158 offset:16384
	ds_read_b128 v[190:193], v158 offset:17408
	ds_read_b128 v[194:197], v158 offset:18432
	ds_read_b128 v[200:203], v158 offset:19456
	ds_read_b128 v[204:207], v158 offset:20480
	ds_read_b128 v[208:211], v158 offset:21504
	ds_read_b128 v[212:215], v158 offset:22528
	ds_read_b128 v[216:219], v158 offset:23552
	global_load_lds_dwordx4 v[152:153], off
	v_lshl_add_u64 v[220:221], s[28:29], 0, v[128:129]
	s_mov_b32 m0, s38
	s_addc_u32 s63, s29, 0
	global_load_lds_dwordx4 v[220:221], off
	v_lshl_add_u64 v[222:223], s[62:63], 0, v[132:133]
	s_mov_b32 m0, s39
	v_lshl_add_u64 v[224:225], s[30:31], 0, v[130:131]
	global_load_lds_dwordx4 v[222:223], off
	v_lshl_add_u64 v[222:223], s[62:63], 0, v[128:129]
	s_mov_b32 m0, s40
	s_nop 0
	global_load_lds_dwordx4 v[222:223], off
	v_lshl_add_u64 v[222:223], s[30:31], 0, v[134:135]
	s_mov_b32 m0, s41
	s_nop 0
	global_load_lds_dwordx4 v[222:223], off
	s_mov_b32 m0, s42
	s_nop 0
	global_load_lds_dwordx4 v[224:225], off
	s_waitcnt vmcnt(8)
	s_waitcnt lgkmcnt(0)
	s_barrier
; #define PG8_STAGE(bufoff, gbase, voff) do { _Pragma("unroll") for (int _i = 0; _i < 2; ++_i) \
;         __builtin_amdgcn_global_load_lds((const unsigned*)((const char*)(gbase) + (voff)[_i]), (PG8_LAS unsigned*)(lds + (bufoff) + ldsw + _i * 8192), 16, 0, 0); } while (0)
; #define PG8_LDA(dst, b, h) do { _Pragma("unroll") for (int m = 0; m < 4; ++m) _Pragma("unroll") for (int k = 0; k < 2; ++k) dst[m][k] = *(const PG8_LAS bf16x8*)(lds + PG8_SA(b, h) + aoff + m * 2048 + k * 1024); } while (0)
; #define PG8_LDB(dst, b, h) do { _Pragma("unroll") for (int n = 0; n < 2; ++n) _Pragma("unroll") for (int k = 0; k < 2; ++k) dst[n][k] = *(const PG8_LAS bf16x8*)(lds + PG8_SB(b, h) + boff + n * 2048 + k * 1024); } while (0)
; #define PG8_MMA(ai, bj, At, Bt) do { __builtin_amdgcn_s_setprio(1); _Pragma("unroll") for (int m = 0; m < 4; ++m) _Pragma("unroll") for (int n = 0; n < 2; ++n) _Pragma("unroll") for (int k = 0; k < 2; ++k) \
;         acc[ai][bj][m][n] = __builtin_amdgcn_mfma_f32_16x16x32_bf16(Bt[n][k], At[m][k], acc[ai][bj][m][n], 0, 0, 0); __builtin_amdgcn_s_setprio(0); } while (0)
; #define PG8_WAIT_V(n) asm volatile("s_waitcnt vmcnt(" #n ")" ::: "memory")
; #define PG8_WAIT_L(n) asm volatile("s_waitcnt lgkmcnt(" #n ")" ::: "memory")
; #define PG8_BAR __builtin_amdgcn_s_barrier()
; #define PG8_SCHED __builtin_amdgcn_sched_barrier(0)
; template <class Epi, class Sched, bool ALIGN_EPI = false, bool SP2 = false>
; __device__ __forceinline__ void gemm_phase(PG8_LAS unsigned char* lds, const Gemm g, const Sched& S, const Epi& E, const int tid) {
;     ...
;             PG8_WAIT_V(8); PG8_WAIT_L(0); PG8_BAR; PG8_MMA(1, 0, At, B0); PG8_MMA(1, 1, At, B1); PG8_BAR; PG8_SCHED;
;             PG8_LDB(B0, 1, 0); PG8_LDB(B1, 1, 1); PG8_SCHED; PG8_LDA(At, 1, 0); PG8_STAGE(PG8_SA(0, 1), a2 + hstepA, voffA);
;             PG8_WAIT_V(8); PG8_WAIT_L(0); PG8_BAR; PG8_MMA(0, 0, At, B0); PG8_MMA(0, 1, At, B1); PG8_BAR; PG8_SCHED;
	s_waitcnt lgkmcnt(0)
	v_mfma_f32_16x16x32_bf16 v[60:63], v[144:147], v[186:189], v[60:63]
	v_mfma_f32_16x16x32_bf16 v[56:59], v[162:165], v[186:189], v[56:59]
	v_mfma_f32_16x16x32_bf16 v[44:47], v[144:147], v[194:197], v[44:47]
	v_mfma_f32_16x16x32_bf16 v[40:43], v[162:165], v[194:197], v[40:43]
	v_mfma_f32_16x16x32_bf16 v[28:31], v[144:147], v[204:207], v[28:31]
	v_mfma_f32_16x16x32_bf16 v[24:27], v[162:165], v[204:207], v[24:27]
	v_mfma_f32_16x16x32_bf16 v[12:15], v[144:147], v[212:215], v[12:15]
	v_mfma_f32_16x16x32_bf16 v[8:11], v[162:165], v[212:215], v[8:11]
	v_mfma_f32_16x16x32_bf16 v[60:63], v[148:151], v[190:193], v[60:63]
	v_mfma_f32_16x16x32_bf16 v[56:59], v[166:169], v[190:193], v[56:59]
	v_mfma_f32_16x16x32_bf16 v[44:47], v[148:151], v[200:203], v[44:47]
	v_mfma_f32_16x16x32_bf16 v[40:43], v[166:169], v[200:203], v[40:43]
	v_mfma_f32_16x16x32_bf16 v[28:31], v[148:151], v[208:211], v[28:31]
	v_mfma_f32_16x16x32_bf16 v[24:27], v[166:169], v[208:211], v[24:27]
	v_mfma_f32_16x16x32_bf16 v[12:15], v[148:151], v[216:219], v[12:15]
	v_mfma_f32_16x16x32_bf16 v[8:11], v[166:169], v[216:219], v[8:11]
	v_mfma_f32_16x16x32_bf16 v[52:55], v[170:173], v[186:189], v[52:55]
	v_mfma_f32_16x16x32_bf16 v[48:51], v[178:181], v[186:189], v[48:51]
	v_mfma_f32_16x16x32_bf16 v[36:39], v[170:173], v[194:197], v[36:39]
	v_mfma_f32_16x16x32_bf16 v[32:35], v[178:181], v[194:197], v[32:35]
	v_mfma_f32_16x16x32_bf16 v[20:23], v[170:173], v[204:207], v[20:23]
	v_mfma_f32_16x16x32_bf16 v[16:19], v[178:181], v[204:207], v[16:19]
	v_mfma_f32_16x16x32_bf16 v[4:7], v[170:173], v[212:215], v[4:7]
	v_mfma_f32_16x16x32_bf16 v[0:3], v[178:181], v[212:215], v[0:3]
	v_mfma_f32_16x16x32_bf16 v[52:55], v[174:177], v[190:193], v[52:55]
	v_mfma_f32_16x16x32_bf16 v[48:51], v[182:185], v[190:193], v[48:51]
	v_mfma_f32_16x16x32_bf16 v[36:39], v[174:177], v[200:203], v[36:39]
	v_mfma_f32_16x16x32_bf16 v[32:35], v[182:185], v[200:203], v[32:35]
	v_mfma_f32_16x16x32_bf16 v[20:23], v[174:177], v[208:211], v[20:23]
	v_mfma_f32_16x16x32_bf16 v[16:19], v[182:185], v[208:211], v[16:19]
	v_mfma_f32_16x16x32_bf16 v[4:7], v[174:177], v[216:219], v[4:7]
	v_mfma_f32_16x16x32_bf16 v[0:3], v[182:185], v[216:219], v[0:3]
	s_barrier
	ds_read_b128 v[144:147], v159
	ds_read_b128 v[148:151], v159 offset:1024
	ds_read_b128 v[162:165], v159 offset:2048
	ds_read_b128 v[166:169], v159 offset:3072
	ds_read_b128 v[170:173], v160
	ds_read_b128 v[174:177], v160 offset:1024
	ds_read_b128 v[178:181], v160 offset:2048
	ds_read_b128 v[182:185], v160 offset:3072
	s_add_u32 s30, s30, 0x40000
	s_addc_u32 s31, s31, 0
	s_mov_b32 m0, s43
	v_lshl_add_u64 v[226:227], s[30:31], 0, v[134:135]
	ds_read_b128 v[186:189], v158 offset:32768
	ds_read_b128 v[190:193], v158 offset:33792
	ds_read_b128 v[194:197], v158 offset:34816
	ds_read_b128 v[200:203], v158 offset:35840
	ds_read_b128 v[204:207], v158 offset:36864
	ds_read_b128 v[208:211], v158 offset:37888
	ds_read_b128 v[212:215], v158 offset:38912
	ds_read_b128 v[216:219], v158 offset:39936
	global_load_lds_dwordx4 v[226:227], off
	v_lshl_add_u64 v[226:227], s[30:31], 0, v[130:131]
	s_mov_b32 m0, s44
	s_nop 0
	global_load_lds_dwordx4 v[226:227], off
	s_waitcnt vmcnt(8)
	s_waitcnt lgkmcnt(0)
	s_barrier
	s_waitcnt lgkmcnt(0)
	v_mfma_f32_16x16x32_bf16 v[124:127], v[144:147], v[186:189], v[124:127]
	v_mfma_f32_16x16x32_bf16 v[120:123], v[162:165], v[186:189], v[120:123]
	v_mfma_f32_16x16x32_bf16 v[108:111], v[144:147], v[194:197], v[108:111]
	v_mfma_f32_16x16x32_bf16 v[104:107], v[162:165], v[194:197], v[104:107]
	v_mfma_f32_16x16x32_bf16 v[92:95], v[144:147], v[204:207], v[92:95]
	v_mfma_f32_16x16x32_bf16 v[88:91], v[162:165], v[204:207], v[88:91]
	v_mfma_f32_16x16x32_bf16 v[76:79], v[144:147], v[212:215], v[76:79]
	v_mfma_f32_16x16x32_bf16 v[72:75], v[162:165], v[212:215], v[72:75]
	v_mfma_f32_16x16x32_bf16 v[124:127], v[148:151], v[190:193], v[124:127]
	v_mfma_f32_16x16x32_bf16 v[120:123], v[166:169], v[190:193], v[120:123]
	v_mfma_f32_16x16x32_bf16 v[108:111], v[148:151], v[200:203], v[108:111]
	v_mfma_f32_16x16x32_bf16 v[104:107], v[166:169], v[200:203], v[104:107]
	v_mfma_f32_16x16x32_bf16 v[92:95], v[148:151], v[208:211], v[92:95]
	v_mfma_f32_16x16x32_bf16 v[88:91], v[166:169], v[208:211], v[88:91]
	v_mfma_f32_16x16x32_bf16 v[76:79], v[148:151], v[216:219], v[76:79]
	v_mfma_f32_16x16x32_bf16 v[72:75], v[166:169], v[216:219], v[72:75]
	v_mfma_f32_16x16x32_bf16 v[116:119], v[170:173], v[186:189], v[116:119]
	v_mfma_f32_16x16x32_bf16 v[112:115], v[178:181], v[186:189], v[112:115]
	v_mfma_f32_16x16x32_bf16 v[100:103], v[170:173], v[194:197], v[100:103]
	v_mfma_f32_16x16x32_bf16 v[96:99], v[178:181], v[194:197], v[96:99]
	v_mfma_f32_16x16x32_bf16 v[84:87], v[170:173], v[204:207], v[84:87]
	v_mfma_f32_16x16x32_bf16 v[80:83], v[178:181], v[204:207], v[80:83]
	v_mfma_f32_16x16x32_bf16 v[68:71], v[170:173], v[212:215], v[68:71]
	v_mfma_f32_16x16x32_bf16 v[64:67], v[178:181], v[212:215], v[64:67]
	v_mfma_f32_16x16x32_bf16 v[116:119], v[174:177], v[190:193], v[116:119]
	v_mfma_f32_16x16x32_bf16 v[112:115], v[182:185], v[190:193], v[112:115]
	v_mfma_f32_16x16x32_bf16 v[100:103], v[174:177], v[200:203], v[100:103]
	v_mfma_f32_16x16x32_bf16 v[96:99], v[182:185], v[200:203], v[96:99]
	v_mfma_f32_16x16x32_bf16 v[84:87], v[174:177], v[208:211], v[84:87]
	v_mfma_f32_16x16x32_bf16 v[80:83], v[182:185], v[208:211], v[80:83]
	v_mfma_f32_16x16x32_bf16 v[68:71], v[174:177], v[216:219], v[68:71]
	v_mfma_f32_16x16x32_bf16 v[64:67], v[182:185], v[216:219], v[64:67]
	s_barrier
; #define PG8_STAGE(bufoff, gbase, voff) do { _Pragma("unroll") for (int _i = 0; _i < 2; ++_i) \
;         __builtin_amdgcn_global_load_lds((const unsigned*)((const char*)(gbase) + (voff)[_i]), (PG8_LAS unsigned*)(lds + (bufoff) + ldsw + _i * 8192), 16, 0, 0); } while (0)
; #define PG8_LDA(dst, b, h) do { _Pragma("unroll") for (int m = 0; m < 4; ++m) _Pragma("unroll") for (int k = 0; k < 2; ++k) dst[m][k] = *(const PG8_LAS bf16x8*)(lds + PG8_SA(b, h) + aoff + m * 2048 + k * 1024); } while (0)
; #define PG8_MMA(ai, bj, At, Bt) do { __builtin_amdgcn_s_setprio(1); _Pragma("unroll") for (int m = 0; m < 4; ++m) _Pragma("unroll") for (int n = 0; n < 2; ++n) _Pragma("unroll") for (int k = 0; k < 2; ++k) \
;         acc[ai][bj][m][n] = __builtin_amdgcn_mfma_f32_16x16x32_bf16(Bt[n][k], At[m][k], acc[ai][bj][m][n], 0, 0, 0); __builtin_amdgcn_s_setprio(0); } while (0)
; #define PG8_WAIT_V(n) asm volatile("s_waitcnt vmcnt(" #n ")" ::: "memory")
; #define PG8_WAIT_L(n) asm volatile("s_waitcnt lgkmcnt(" #n ")" ::: "memory")
; #define PG8_BAR __builtin_amdgcn_s_barrier()
; #define PG8_SCHED __builtin_amdgcn_sched_barrier(0)
; __device__ __forceinline__ float ss_scale(const u64* ss, int row) { return __builtin_amdgcn_rsqf((float)ss[row] * (1.f / 4294967296.f / 1024.f) + EPS); }
; template <class Epi, class Sched, bool ALIGN_EPI = false, bool SP2 = false>
; __device__ __forceinline__ void gemm_phase(PG8_LAS unsigned char* lds, const Gemm g, const Sched& S, const Epi& E, const int tid) {
;     ...
;             PG8_LDA(At, 1, 1); PG8_STAGE(PG8_SB(1, 0), b3, voffB); PG8_STAGE(PG8_SB(1, 1), b3 + hstep, voffB); PG8_STAGE(PG8_SA(1, 0), a3, voffA);
;             PG8_WAIT_V(8); PG8_WAIT_L(0); PG8_BAR; PG8_MMA(1, 0, At, B0); PG8_MMA(1, 1, At, B1); PG8_BAR; PG8_SCHED;
;     __device__ __forceinline__ void operator()(const f32x4 (&acc)[2][2][4][2], const pg8::Unit& u, int wr, int wc, int fr, int fq) const {
;         const int row0 = u.pm * 256 + wr * 64 + fr, col0 = u.pn * 128 + wc * 32 + 8 * fq;
; #pragma unroll
;         for (int ai = 0; ai < 2; ++ai)
; #pragma unroll
;             for (int m = 0; m < 4; ++m) {
;                 const int row = row0 + ai * 128 + m * 16;
;                 float s = ss_scale(ss, row);
;                 if constexpr (NN) s *= __builtin_amdgcn_rsqf(s * s * (float)ssw[row] * (1.f / 4294967296.f / 1024.f) + EPS);
	s_mov_b32 m0, s47
	v_lshl_add_u64 v[152:153], v[152:153], 0, s[12:13]
	s_add_u32 s28, s28, 0x40080
	ds_read_b128 v[186:189], v158 offset:49152
	ds_read_b128 v[190:193], v158 offset:50176
	ds_read_b128 v[194:197], v158 offset:51200
	ds_read_b128 v[200:203], v158 offset:52224
	ds_read_b128 v[204:207], v158 offset:53248
	ds_read_b128 v[208:211], v158 offset:54272
	ds_read_b128 v[212:215], v158 offset:55296
	ds_read_b128 v[216:219], v158 offset:56320
	global_load_lds_dwordx4 v[152:153], off
	v_lshl_add_u64 v[152:153], v[220:221], 0, s[12:13]
	s_mov_b32 m0, s48
	s_addc_u32 s29, s29, 0
	global_load_lds_dwordx4 v[152:153], off
	v_lshl_add_u64 v[152:153], s[28:29], 0, v[132:133]
	s_mov_b32 m0, s51
	s_nop 0
	global_load_lds_dwordx4 v[152:153], off
	v_lshl_add_u64 v[152:153], s[28:29], 0, v[128:129]
	s_mov_b32 m0, s52
	s_nop 0
	global_load_lds_dwordx4 v[152:153], off
	v_lshl_add_u64 v[152:153], v[222:223], 0, s[12:13]
	s_mov_b32 m0, s49
	s_nop 0
	global_load_lds_dwordx4 v[152:153], off
	v_lshl_add_u64 v[152:153], v[224:225], 0, s[12:13]
	s_mov_b32 m0, s50
	s_nop 0
	global_load_lds_dwordx4 v[152:153], off
	s_waitcnt vmcnt(8)
	s_waitcnt lgkmcnt(0)
	s_barrier
	s_waitcnt lgkmcnt(0)
	v_mfma_f32_16x16x32_bf16 v[60:63], v[144:147], v[186:189], v[60:63]
	v_mfma_f32_16x16x32_bf16 v[56:59], v[162:165], v[186:189], v[56:59]
	v_mfma_f32_16x16x32_bf16 v[44:47], v[144:147], v[194:197], v[44:47]
	v_mfma_f32_16x16x32_bf16 v[40:43], v[162:165], v[194:197], v[40:43]
	v_mfma_f32_16x16x32_bf16 v[28:31], v[144:147], v[204:207], v[28:31]
	v_mfma_f32_16x16x32_bf16 v[24:27], v[162:165], v[204:207], v[24:27]
	v_mfma_f32_16x16x32_bf16 v[12:15], v[144:147], v[212:215], v[12:15]
	v_mfma_f32_16x16x32_bf16 v[8:11], v[162:165], v[212:215], v[8:11]
	v_mfma_f32_16x16x32_bf16 v[60:63], v[148:151], v[190:193], v[60:63]
	v_mfma_f32_16x16x32_bf16 v[56:59], v[166:169], v[190:193], v[56:59]
	v_mfma_f32_16x16x32_bf16 v[44:47], v[148:151], v[200:203], v[44:47]
	v_mfma_f32_16x16x32_bf16 v[40:43], v[166:169], v[200:203], v[40:43]
	v_mfma_f32_16x16x32_bf16 v[28:31], v[148:151], v[208:211], v[28:31]
	v_mfma_f32_16x16x32_bf16 v[24:27], v[166:169], v[208:211], v[24:27]
	v_mfma_f32_16x16x32_bf16 v[12:15], v[148:151], v[216:219], v[12:15]
	v_mfma_f32_16x16x32_bf16 v[8:11], v[166:169], v[216:219], v[8:11]
	v_mfma_f32_16x16x32_bf16 v[52:55], v[170:173], v[186:189], v[52:55]
	v_mfma_f32_16x16x32_bf16 v[48:51], v[178:181], v[186:189], v[48:51]
	v_mfma_f32_16x16x32_bf16 v[36:39], v[170:173], v[194:197], v[36:39]
	v_mfma_f32_16x16x32_bf16 v[32:35], v[178:181], v[194:197], v[32:35]
	v_mfma_f32_16x16x32_bf16 v[20:23], v[170:173], v[204:207], v[20:23]
	v_mfma_f32_16x16x32_bf16 v[16:19], v[178:181], v[204:207], v[16:19]
	v_mfma_f32_16x16x32_bf16 v[4:7], v[170:173], v[212:215], v[4:7]
	v_mfma_f32_16x16x32_bf16 v[0:3], v[178:181], v[212:215], v[0:3]
	v_mfma_f32_16x16x32_bf16 v[52:55], v[174:177], v[190:193], v[52:55]
	v_mfma_f32_16x16x32_bf16 v[48:51], v[182:185], v[190:193], v[48:51]
	v_mfma_f32_16x16x32_bf16 v[36:39], v[174:177], v[200:203], v[36:39]
	v_mfma_f32_16x16x32_bf16 v[32:35], v[182:185], v[200:203], v[32:35]
	v_mfma_f32_16x16x32_bf16 v[20:23], v[174:177], v[208:211], v[20:23]
	v_mfma_f32_16x16x32_bf16 v[16:19], v[182:185], v[208:211], v[16:19]
	v_mfma_f32_16x16x32_bf16 v[4:7], v[174:177], v[216:219], v[4:7]
	v_mfma_f32_16x16x32_bf16 v[0:3], v[182:185], v[216:219], v[0:3]
	s_barrier
	s_add_i32 s60, s60, 2
	s_add_u32 s26, s26, 0x100
	s_addc_u32 s27, s27, 0
	s_add_u32 s58, s58, 0x100
	s_addc_u32 s59, s59, 0
	s_cmp_gt_u32 s60, 13
	s_cbranch_scc0 .LBB0_1007
	s_setprio 0
	v_lshl_add_u32 v144, s24, 8, v154
	v_mov_b32_e32 v145, 0
	v_lshl_add_u64 v[150:151], v[144:145], 3, s[8:9]
	global_load_dwordx2 v[176:177], v[150:151], off
	global_load_dwordx2 v[178:179], v[150:151], off offset:128
	global_load_dwordx2 v[180:181], v[150:151], off offset:256
	global_load_dwordx2 v[182:183], v[150:151], off offset:384
	global_load_dwordx2 v[184:185], v[150:151], off offset:1024
	global_load_dwordx2 v[186:187], v[150:151], off offset:1152
	global_load_dwordx2 v[188:189], v[150:151], off offset:1280
	global_load_dwordx2 v[190:191], v[150:151], off offset:1408
	v_lshl_add_u64 v[210:211], v[144:145], 3, s[10:11]
	global_load_dwordx2 v[192:193], v[210:211], off
	global_load_dwordx2 v[194:195], v[210:211], off offset:128
	global_load_dwordx2 v[196:197], v[210:211], off offset:256
	global_load_dwordx2 v[200:201], v[210:211], off offset:384
	global_load_dwordx2 v[202:203], v[210:211], off offset:1024
	global_load_dwordx2 v[204:205], v[210:211], off offset:1152
	global_load_dwordx2 v[206:207], v[210:211], off offset:1280
	global_load_dwordx2 v[208:209], v[210:211], off offset:1408
	v_lshl_or_b32 v148, s55, 7, v155
	v_mul_u32_u24_e32 v146, s54, v144
	v_lshl_add_u32 v146, v148, 1, v146
	v_mov_b32_e32 v147, 0
	v_lshl_add_u64 v[146:147], v[146:147], 0, s[6:7]
	v_mov_b32_e32 v164, 1.0
	v_mov_b32_e32 v165, 1.0
	s_mov_b32 s101, 0
	s_and_b64 vcc, exec, s[14:15]
	s_cbranch_vccz .LBB0_1010
	s_barrier

; #define PG8_STAGE(bufoff, gbase, voff) do { _Pragma("unroll") for (int _i = 0; _i < 2; ++_i) \
;         __builtin_amdgcn_global_load_lds((const unsigned*)((const char*)(gbase) + (voff)[_i]), (PG8_LAS unsigned*)(lds + (bufoff) + ldsw + _i * 8192), 16, 0, 0); } while (0)
; #define PG8_LDA(dst, b, h) do { _Pragma("unroll") for (int m = 0; m < 4; ++m) _Pragma("unroll") for (int k = 0; k < 2; ++k) dst[m][k] = *(const PG8_LAS bf16x8*)(lds + PG8_SA(b, h) + aoff + m * 2048 + k * 1024); } while (0)
; #define PG8_LDB(dst, b, h) do { _Pragma("unroll") for (int n = 0; n < 2; ++n) _Pragma("unroll") for (int k = 0; k < 2; ++k) dst[n][k] = *(const PG8_LAS bf16x8*)(lds + PG8_SB(b, h) + boff + n * 2048 + k * 1024); } while (0)
; #define PG8_MMA(ai, bj, At, Bt) do { __builtin_amdgcn_s_setprio(1); _Pragma("unroll") for (int m = 0; m < 4; ++m) _Pragma("unroll") for (int n = 0; n < 2; ++n) _Pragma("unroll") for (int k = 0; k < 2; ++k) \
;         acc[ai][bj][m][n] = __builtin_amdgcn_mfma_f32_16x16x32_bf16(Bt[n][k], At[m][k], acc[ai][bj][m][n], 0, 0, 0); __builtin_amdgcn_s_setprio(0); } while (0)
; #define PG8_WAIT_V(n) asm volatile("s_waitcnt vmcnt(" #n ")" ::: "memory")
; #define PG8_WAIT_L(n) asm volatile("s_waitcnt lgkmcnt(" #n ")" ::: "memory")
; template <class Epi, class Sched, bool ALIGN_EPI = false, bool SP2 = false>
; __device__ __forceinline__ void gemm_phase(PG8_LAS unsigned char* lds, const Gemm g, const Sched& S, const Epi& E, const int tid) {
;     ...
;             const bool last = (t == nt - 2);
;             const char* a1 = cA + (size_t)(t + 1) * kstep;
;             const char* a2 = last ? nA : cA + (size_t)(t + 2) * kstep; const char* b2 = last ? nB : cB + (size_t)(t + 2) * kstep;
;             const char* a3 = a2 + kstep; const char* b3 = b2 + kstep;
;             if (last && has_next) S.a_ready(nxt);
;             if constexpr (SP2) {
;             PG8_LDB(B0, 0, 0); PG8_LDB(B1, 0, 1); PG8_SCHED; PG8_LDA(At, 0, 0); PG8_STAGE(PG8_SA(1, 1), a1 + hstepA, voffA);
;             PG8_WAIT_V(8); PG8_WAIT_L(0); PG8_BAR; PG8_MMA(0, 0, At, B0); PG8_MMA(0, 1, At, B1); PG8_BAR; PG8_SCHED;
;             PG8_LDA(At, 0, 1); PG8_STAGE(PG8_SB(0, 0), b2, voffB); PG8_STAGE(PG8_SB(0, 1), b2 + hstep, voffB); PG8_STAGE(PG8_SA(0, 0), a2, voffA);
;             PG8_WAIT_V(8); PG8_WAIT_L(0); PG8_BAR; PG8_MMA(1, 0, At, B0); PG8_MMA(1, 1, At, B1); PG8_BAR; PG8_SCHED;
.Lsp_7:
	ds_read_b128 v[80:83], v168
	ds_read_b128 v[84:87], v168 offset:1024
	ds_read_b128 v[88:91], v168 offset:2048
	ds_read_b128 v[92:95], v168 offset:3072
	ds_read_b128 v[160:163], v169
	ds_read_b128 v[176:179], v169 offset:1024
	ds_read_b128 v[180:183], v169 offset:2048
	ds_read_b128 v[184:187], v169 offset:3072
	s_add_u32 s28, s26, 0x100
	s_addc_u32 s29, s27, 0
	s_cmp_eq_u32 s63, 40
	s_cselect_b32 s35, s7, s29
	s_cselect_b32 s34, s6, s28
	s_cselect_b32 s31, s25, s62
	s_cselect_b32 s30, s24, s61
	v_lshl_add_u64 v[164:165], s[26:27], 0, v[152:153]
	s_add_i32 m0, s42, 0xc000
	ds_read_b128 v[188:191], v170
	ds_read_b128 v[192:195], v170 offset:1024
	ds_read_b128 v[200:203], v170 offset:2048
	ds_read_b128 v[204:207], v170 offset:3072
	ds_read_b128 v[208:211], v170 offset:4096
	ds_read_b128 v[212:215], v170 offset:5120
	ds_read_b128 v[216:219], v170 offset:6144
	ds_read_b128 v[220:223], v170 offset:7168
	global_load_lds_dwordx4 v[164:165], off
	v_lshl_add_u64 v[164:165], s[26:27], 0, v[154:155]
	s_add_i32 m0, s42, 0xe000
	s_nop 0
	global_load_lds_dwordx4 v[164:165], off
	s_waitcnt vmcnt(8)
	s_waitcnt lgkmcnt(0)
	s_barrier
	s_waitcnt lgkmcnt(0)
	v_mfma_f32_16x16x32_bf16 v[140:143], v[80:83], v[188:191], v[140:143]
	v_mfma_f32_16x16x32_bf16 v[136:139], v[88:91], v[188:191], v[136:139]
	v_mfma_f32_16x16x32_bf16 v[124:127], v[80:83], v[200:203], v[124:127]
	v_mfma_f32_16x16x32_bf16 v[120:123], v[88:91], v[200:203], v[120:123]
	v_mfma_f32_16x16x32_bf16 v[108:111], v[80:83], v[208:211], v[108:111]
	v_mfma_f32_16x16x32_bf16 v[104:107], v[88:91], v[208:211], v[104:107]
	v_mfma_f32_16x16x32_bf16 v[76:79], v[80:83], v[216:219], v[76:79]
	v_mfma_f32_16x16x32_bf16 v[72:75], v[88:91], v[216:219], v[72:75]
	v_mfma_f32_16x16x32_bf16 v[140:143], v[84:87], v[192:195], v[140:143]
	v_mfma_f32_16x16x32_bf16 v[136:139], v[92:95], v[192:195], v[136:139]
	v_mfma_f32_16x16x32_bf16 v[124:127], v[84:87], v[204:207], v[124:127]
	v_mfma_f32_16x16x32_bf16 v[120:123], v[92:95], v[204:207], v[120:123]
	v_mfma_f32_16x16x32_bf16 v[108:111], v[84:87], v[212:215], v[108:111]
	v_mfma_f32_16x16x32_bf16 v[104:107], v[92:95], v[212:215], v[104:107]
	v_mfma_f32_16x16x32_bf16 v[76:79], v[84:87], v[220:223], v[76:79]
	v_mfma_f32_16x16x32_bf16 v[72:75], v[92:95], v[220:223], v[72:75]
	v_mfma_f32_16x16x32_bf16 v[132:135], v[160:163], v[188:191], v[132:135]
	v_mfma_f32_16x16x32_bf16 v[128:131], v[180:183], v[188:191], v[128:131]
	v_mfma_f32_16x16x32_bf16 v[116:119], v[160:163], v[200:203], v[116:119]
	v_mfma_f32_16x16x32_bf16 v[112:115], v[180:183], v[200:203], v[112:115]
	v_mfma_f32_16x16x32_bf16 v[100:103], v[160:163], v[208:211], v[100:103]
	v_mfma_f32_16x16x32_bf16 v[96:99], v[180:183], v[208:211], v[96:99]
	v_mfma_f32_16x16x32_bf16 v[68:71], v[160:163], v[216:219], v[68:71]
	v_mfma_f32_16x16x32_bf16 v[64:67], v[180:183], v[216:219], v[64:67]
	v_mfma_f32_16x16x32_bf16 v[132:135], v[176:179], v[192:195], v[132:135]
	v_mfma_f32_16x16x32_bf16 v[128:131], v[184:187], v[192:195], v[128:131]
	v_mfma_f32_16x16x32_bf16 v[116:119], v[176:179], v[204:207], v[116:119]
	v_mfma_f32_16x16x32_bf16 v[112:115], v[184:187], v[204:207], v[112:115]
	v_mfma_f32_16x16x32_bf16 v[100:103], v[176:179], v[212:215], v[100:103]
	v_mfma_f32_16x16x32_bf16 v[96:99], v[184:187], v[212:215], v[96:99]
	v_mfma_f32_16x16x32_bf16 v[68:71], v[176:179], v[220:223], v[68:71]
	v_mfma_f32_16x16x32_bf16 v[64:67], v[184:187], v[220:223], v[64:67]
	s_barrier
	s_mov_b32 m0, s38
	v_lshl_add_u64 v[164:165], s[30:31], 0, v[146:147]
	s_add_u32 s26, s30, 0xb0000
	ds_read_b128 v[188:191], v170 offset:16384
	ds_read_b128 v[192:195], v170 offset:17408
	ds_read_b128 v[200:203], v170 offset:18432
	ds_read_b128 v[204:207], v170 offset:19456
	ds_read_b128 v[208:211], v170 offset:20480
	ds_read_b128 v[212:215], v170 offset:21504
	ds_read_b128 v[216:219], v170 offset:22528
	ds_read_b128 v[220:223], v170 offset:23552
	global_load_lds_dwordx4 v[164:165], off
	v_lshl_add_u64 v[196:197], s[30:31], 0, v[150:151]
	s_mov_b32 m0, s39
	s_addc_u32 s27, s31, 0
	global_load_lds_dwordx4 v[196:197], off
	v_lshl_add_u64 v[224:225], s[26:27], 0, v[146:147]
	s_mov_b32 m0, s40
	v_lshl_add_u64 v[226:227], s[34:35], 0, v[148:149]
	global_load_lds_dwordx4 v[224:225], off
	v_lshl_add_u64 v[224:225], s[26:27], 0, v[150:151]
	s_mov_b32 m0, s41
	s_nop 0
	global_load_lds_dwordx4 v[224:225], off
	v_lshl_add_u64 v[224:225], s[34:35], 0, v[144:145]
	s_mov_b32 m0, s42
	s_nop 0
	global_load_lds_dwordx4 v[224:225], off
	s_mov_b32 m0, s43
	s_nop 0
	global_load_lds_dwordx4 v[226:227], off
	s_waitcnt vmcnt(8)
	s_waitcnt lgkmcnt(0)
	s_barrier
; #define PG8_STAGE(bufoff, gbase, voff) do { _Pragma("unroll") for (int _i = 0; _i < 2; ++_i) \
;         __builtin_amdgcn_global_load_lds((const unsigned*)((const char*)(gbase) + (voff)[_i]), (PG8_LAS unsigned*)(lds + (bufoff) + ldsw + _i * 8192), 16, 0, 0); } while (0)
; #define PG8_LDA(dst, b, h) do { _Pragma("unroll") for (int m = 0; m < 4; ++m) _Pragma("unroll") for (int k = 0; k < 2; ++k) dst[m][k] = *(const PG8_LAS bf16x8*)(lds + PG8_SA(b, h) + aoff + m * 2048 + k * 1024); } while (0)
; #define PG8_LDB(dst, b, h) do { _Pragma("unroll") for (int n = 0; n < 2; ++n) _Pragma("unroll") for (int k = 0; k < 2; ++k) dst[n][k] = *(const PG8_LAS bf16x8*)(lds + PG8_SB(b, h) + boff + n * 2048 + k * 1024); } while (0)
; #define PG8_MMA(ai, bj, At, Bt) do { __builtin_amdgcn_s_setprio(1); _Pragma("unroll") for (int m = 0; m < 4; ++m) _Pragma("unroll") for (int n = 0; n < 2; ++n) _Pragma("unroll") for (int k = 0; k < 2; ++k) \
;         acc[ai][bj][m][n] = __builtin_amdgcn_mfma_f32_16x16x32_bf16(Bt[n][k], At[m][k], acc[ai][bj][m][n], 0, 0, 0); __builtin_amdgcn_s_setprio(0); } while (0)
; #define PG8_WAIT_V(n) asm volatile("s_waitcnt vmcnt(" #n ")" ::: "memory")
; #define PG8_WAIT_L(n) asm volatile("s_waitcnt lgkmcnt(" #n ")" ::: "memory")
; #define PG8_BAR __builtin_amdgcn_s_barrier()
; #define PG8_SCHED __builtin_amdgcn_sched_barrier(0)
; template <class Epi, class Sched, bool ALIGN_EPI = false, bool SP2 = false>
; __device__ __forceinline__ void gemm_phase(PG8_LAS unsigned char* lds, const Gemm g, const Sched& S, const Epi& E, const int tid) {
;     ...
;             PG8_WAIT_V(8); PG8_WAIT_L(0); PG8_BAR; PG8_MMA(1, 0, At, B0); PG8_MMA(1, 1, At, B1); PG8_BAR; PG8_SCHED;
;             PG8_LDB(B0, 1, 0); PG8_LDB(B1, 1, 1); PG8_SCHED; PG8_LDA(At, 1, 0); PG8_STAGE(PG8_SA(0, 1), a2 + hstepA, voffA);
;             PG8_WAIT_V(8); PG8_WAIT_L(0); PG8_BAR; PG8_MMA(0, 0, At, B0); PG8_MMA(0, 1, At, B1); PG8_BAR; PG8_SCHED;
	s_waitcnt lgkmcnt(0)
	v_mfma_f32_16x16x32_bf16 v[60:63], v[80:83], v[188:191], v[60:63]
	v_mfma_f32_16x16x32_bf16 v[56:59], v[88:91], v[188:191], v[56:59]
	v_mfma_f32_16x16x32_bf16 v[44:47], v[80:83], v[200:203], v[44:47]
	v_mfma_f32_16x16x32_bf16 v[40:43], v[88:91], v[200:203], v[40:43]
	v_mfma_f32_16x16x32_bf16 v[28:31], v[80:83], v[208:211], v[28:31]
	v_mfma_f32_16x16x32_bf16 v[24:27], v[88:91], v[208:211], v[24:27]
	v_mfma_f32_16x16x32_bf16 v[12:15], v[80:83], v[216:219], v[12:15]
	v_mfma_f32_16x16x32_bf16 v[8:11], v[88:91], v[216:219], v[8:11]
	v_mfma_f32_16x16x32_bf16 v[60:63], v[84:87], v[192:195], v[60:63]
	v_mfma_f32_16x16x32_bf16 v[56:59], v[92:95], v[192:195], v[56:59]
	v_mfma_f32_16x16x32_bf16 v[44:47], v[84:87], v[204:207], v[44:47]
	v_mfma_f32_16x16x32_bf16 v[40:43], v[92:95], v[204:207], v[40:43]
	v_mfma_f32_16x16x32_bf16 v[28:31], v[84:87], v[212:215], v[28:31]
	v_mfma_f32_16x16x32_bf16 v[24:27], v[92:95], v[212:215], v[24:27]
	v_mfma_f32_16x16x32_bf16 v[12:15], v[84:87], v[220:223], v[12:15]
	v_mfma_f32_16x16x32_bf16 v[8:11], v[92:95], v[220:223], v[8:11]
	v_mfma_f32_16x16x32_bf16 v[52:55], v[160:163], v[188:191], v[52:55]
	v_mfma_f32_16x16x32_bf16 v[48:51], v[180:183], v[188:191], v[48:51]
	v_mfma_f32_16x16x32_bf16 v[36:39], v[160:163], v[200:203], v[36:39]
	v_mfma_f32_16x16x32_bf16 v[32:35], v[180:183], v[200:203], v[32:35]
	v_mfma_f32_16x16x32_bf16 v[20:23], v[160:163], v[208:211], v[20:23]
	v_mfma_f32_16x16x32_bf16 v[16:19], v[180:183], v[208:211], v[16:19]
	v_mfma_f32_16x16x32_bf16 v[4:7], v[160:163], v[216:219], v[4:7]
	v_mfma_f32_16x16x32_bf16 v[0:3], v[180:183], v[216:219], v[0:3]
	v_mfma_f32_16x16x32_bf16 v[52:55], v[176:179], v[192:195], v[52:55]
	v_mfma_f32_16x16x32_bf16 v[48:51], v[184:187], v[192:195], v[48:51]
	v_mfma_f32_16x16x32_bf16 v[36:39], v[176:179], v[204:207], v[36:39]
	v_mfma_f32_16x16x32_bf16 v[32:35], v[184:187], v[204:207], v[32:35]
	v_mfma_f32_16x16x32_bf16 v[20:23], v[176:179], v[212:215], v[20:23]
	v_mfma_f32_16x16x32_bf16 v[16:19], v[184:187], v[212:215], v[16:19]
	v_mfma_f32_16x16x32_bf16 v[4:7], v[176:179], v[220:223], v[4:7]
	v_mfma_f32_16x16x32_bf16 v[0:3], v[184:187], v[220:223], v[0:3]
	s_barrier
	ds_read_b128 v[80:83], v171
	ds_read_b128 v[84:87], v171 offset:1024
	ds_read_b128 v[88:91], v171 offset:2048
	ds_read_b128 v[92:95], v171 offset:3072
	ds_read_b128 v[160:163], v172
	ds_read_b128 v[176:179], v172 offset:1024
	ds_read_b128 v[180:183], v172 offset:2048
	ds_read_b128 v[184:187], v172 offset:3072
	s_add_u32 s26, s34, 0xb0000
	s_addc_u32 s27, s35, 0
	s_mov_b32 m0, s44
	v_lshl_add_u64 v[228:229], s[26:27], 0, v[144:145]
	ds_read_b128 v[188:191], v170 offset:32768
	ds_read_b128 v[192:195], v170 offset:33792
	ds_read_b128 v[200:203], v170 offset:34816
	ds_read_b128 v[204:207], v170 offset:35840
	ds_read_b128 v[208:211], v170 offset:36864
	ds_read_b128 v[212:215], v170 offset:37888
	ds_read_b128 v[216:219], v170 offset:38912
	ds_read_b128 v[220:223], v170 offset:39936
	global_load_lds_dwordx4 v[228:229], off
	v_lshl_add_u64 v[228:229], s[26:27], 0, v[148:149]
	s_mov_b32 m0, s45
	s_nop 0
	global_load_lds_dwordx4 v[228:229], off
	s_waitcnt vmcnt(8)
	s_waitcnt lgkmcnt(0)
	s_barrier
	s_waitcnt lgkmcnt(0)
	v_mfma_f32_16x16x32_bf16 v[140:143], v[80:83], v[188:191], v[140:143]
	v_mfma_f32_16x16x32_bf16 v[136:139], v[88:91], v[188:191], v[136:139]
	v_mfma_f32_16x16x32_bf16 v[124:127], v[80:83], v[200:203], v[124:127]
	v_mfma_f32_16x16x32_bf16 v[120:123], v[88:91], v[200:203], v[120:123]
	v_mfma_f32_16x16x32_bf16 v[108:111], v[80:83], v[208:211], v[108:111]
	v_mfma_f32_16x16x32_bf16 v[104:107], v[88:91], v[208:211], v[104:107]
	v_mfma_f32_16x16x32_bf16 v[76:79], v[80:83], v[216:219], v[76:79]
	v_mfma_f32_16x16x32_bf16 v[72:75], v[88:91], v[216:219], v[72:75]
	v_mfma_f32_16x16x32_bf16 v[140:143], v[84:87], v[192:195], v[140:143]
	v_mfma_f32_16x16x32_bf16 v[136:139], v[92:95], v[192:195], v[136:139]
	v_mfma_f32_16x16x32_bf16 v[124:127], v[84:87], v[204:207], v[124:127]
	v_mfma_f32_16x16x32_bf16 v[120:123], v[92:95], v[204:207], v[120:123]
	v_mfma_f32_16x16x32_bf16 v[108:111], v[84:87], v[212:215], v[108:111]
	v_mfma_f32_16x16x32_bf16 v[104:107], v[92:95], v[212:215], v[104:107]
	v_mfma_f32_16x16x32_bf16 v[76:79], v[84:87], v[220:223], v[76:79]
	v_mfma_f32_16x16x32_bf16 v[72:75], v[92:95], v[220:223], v[72:75]
	v_mfma_f32_16x16x32_bf16 v[132:135], v[160:163], v[188:191], v[132:135]
	v_mfma_f32_16x16x32_bf16 v[128:131], v[180:183], v[188:191], v[128:131]
	v_mfma_f32_16x16x32_bf16 v[116:119], v[160:163], v[200:203], v[116:119]
	v_mfma_f32_16x16x32_bf16 v[112:115], v[180:183], v[200:203], v[112:115]
	v_mfma_f32_16x16x32_bf16 v[100:103], v[160:163], v[208:211], v[100:103]
	v_mfma_f32_16x16x32_bf16 v[96:99], v[180:183], v[208:211], v[96:99]
	v_mfma_f32_16x16x32_bf16 v[68:71], v[160:163], v[216:219], v[68:71]
	v_mfma_f32_16x16x32_bf16 v[64:67], v[180:183], v[216:219], v[64:67]
	v_mfma_f32_16x16x32_bf16 v[132:135], v[176:179], v[192:195], v[132:135]
	v_mfma_f32_16x16x32_bf16 v[128:131], v[184:187], v[192:195], v[128:131]
	v_mfma_f32_16x16x32_bf16 v[116:119], v[176:179], v[204:207], v[116:119]
	v_mfma_f32_16x16x32_bf16 v[112:115], v[184:187], v[204:207], v[112:115]
	v_mfma_f32_16x16x32_bf16 v[100:103], v[176:179], v[212:215], v[100:103]
	v_mfma_f32_16x16x32_bf16 v[96:99], v[184:187], v[212:215], v[96:99]
	v_mfma_f32_16x16x32_bf16 v[68:71], v[176:179], v[220:223], v[68:71]
	v_mfma_f32_16x16x32_bf16 v[64:67], v[184:187], v[220:223], v[64:67]
	s_barrier
; #define PG8_STAGE(bufoff, gbase, voff) do { _Pragma("unroll") for (int _i = 0; _i < 2; ++_i) \
;         __builtin_amdgcn_global_load_lds((const unsigned*)((const char*)(gbase) + (voff)[_i]), (PG8_LAS unsigned*)(lds + (bufoff) + ldsw + _i * 8192), 16, 0, 0); } while (0)
; #define PG8_LDA(dst, b, h) do { _Pragma("unroll") for (int m = 0; m < 4; ++m) _Pragma("unroll") for (int k = 0; k < 2; ++k) dst[m][k] = *(const PG8_LAS bf16x8*)(lds + PG8_SA(b, h) + aoff + m * 2048 + k * 1024); } while (0)
; #define PG8_MMA(ai, bj, At, Bt) do { __builtin_amdgcn_s_setprio(1); _Pragma("unroll") for (int m = 0; m < 4; ++m) _Pragma("unroll") for (int n = 0; n < 2; ++n) _Pragma("unroll") for (int k = 0; k < 2; ++k) \
;         acc[ai][bj][m][n] = __builtin_amdgcn_mfma_f32_16x16x32_bf16(Bt[n][k], At[m][k], acc[ai][bj][m][n], 0, 0, 0); __builtin_amdgcn_s_setprio(0); } while (0)
; #define PG8_WAIT_V(n) asm volatile("s_waitcnt vmcnt(" #n ")" ::: "memory")
; #define PG8_WAIT_L(n) asm volatile("s_waitcnt lgkmcnt(" #n ")" ::: "memory")
; #define PG8_BAR __builtin_amdgcn_s_barrier()
; #define PG8_SCHED __builtin_amdgcn_sched_barrier(0)
; template <class Epi, class Sched, bool ALIGN_EPI = false, bool SP2 = false>
; __device__ __forceinline__ void gemm_phase(PG8_LAS unsigned char* lds, const Gemm g, const Sched& S, const Epi& E, const int tid) {
;     ...
;             PG8_LDA(At, 1, 1); PG8_STAGE(PG8_SB(1, 0), b3, voffB); PG8_STAGE(PG8_SB(1, 1), b3 + hstep, voffB); PG8_STAGE(PG8_SA(1, 0), a3, voffA);
;             PG8_WAIT_V(8); PG8_WAIT_L(0); PG8_BAR; PG8_MMA(1, 0, At, B0); PG8_MMA(1, 1, At, B1); PG8_BAR; PG8_SCHED;
;     ...
;         if constexpr (ALIGN_EPI) { if (wr == 0) PG8_BAR; }
;         if constexpr (!Epi::AFTER_DRAIN) { E(acc, cur, wr, wc, fr, fq); S.done(cur); }
	s_mov_b32 m0, s48
	v_lshl_add_u64 v[164:165], v[164:165], 0, s[18:19]
	s_add_u32 s26, s30, 0xb0080
	ds_read_b128 v[188:191], v170 offset:49152
	ds_read_b128 v[192:195], v170 offset:50176
	ds_read_b128 v[200:203], v170 offset:51200
	ds_read_b128 v[204:207], v170 offset:52224
	ds_read_b128 v[208:211], v170 offset:53248
	ds_read_b128 v[212:215], v170 offset:54272
	ds_read_b128 v[216:219], v170 offset:55296
	ds_read_b128 v[220:223], v170 offset:56320
	global_load_lds_dwordx4 v[164:165], off
	v_lshl_add_u64 v[164:165], v[196:197], 0, s[18:19]
	s_mov_b32 m0, s49
	s_addc_u32 s27, s31, 0
	global_load_lds_dwordx4 v[164:165], off
	v_lshl_add_u64 v[164:165], s[26:27], 0, v[146:147]
	s_mov_b32 m0, s52
	s_nop 0
	global_load_lds_dwordx4 v[164:165], off
	v_lshl_add_u64 v[164:165], s[26:27], 0, v[150:151]
	s_mov_b32 m0, s53
	s_nop 0
	global_load_lds_dwordx4 v[164:165], off
	v_lshl_add_u64 v[164:165], v[224:225], 0, s[18:19]
	s_mov_b32 m0, s50
	s_nop 0
	global_load_lds_dwordx4 v[164:165], off
	v_lshl_add_u64 v[164:165], v[226:227], 0, s[18:19]
	s_mov_b32 m0, s51
	s_nop 0
	global_load_lds_dwordx4 v[164:165], off
	s_waitcnt vmcnt(8)
	s_waitcnt lgkmcnt(0)
	s_barrier
	s_waitcnt lgkmcnt(0)
	v_mfma_f32_16x16x32_bf16 v[60:63], v[80:83], v[188:191], v[60:63]
	v_mfma_f32_16x16x32_bf16 v[56:59], v[88:91], v[188:191], v[56:59]
	v_mfma_f32_16x16x32_bf16 v[44:47], v[80:83], v[200:203], v[44:47]
	v_mfma_f32_16x16x32_bf16 v[40:43], v[88:91], v[200:203], v[40:43]
	v_mfma_f32_16x16x32_bf16 v[28:31], v[80:83], v[208:211], v[28:31]
	v_mfma_f32_16x16x32_bf16 v[24:27], v[88:91], v[208:211], v[24:27]
	v_mfma_f32_16x16x32_bf16 v[12:15], v[80:83], v[216:219], v[12:15]
	v_mfma_f32_16x16x32_bf16 v[8:11], v[88:91], v[216:219], v[8:11]
	v_mfma_f32_16x16x32_bf16 v[60:63], v[84:87], v[192:195], v[60:63]
	v_mfma_f32_16x16x32_bf16 v[56:59], v[92:95], v[192:195], v[56:59]
	v_mfma_f32_16x16x32_bf16 v[44:47], v[84:87], v[204:207], v[44:47]
	v_mfma_f32_16x16x32_bf16 v[40:43], v[92:95], v[204:207], v[40:43]
	v_mfma_f32_16x16x32_bf16 v[28:31], v[84:87], v[212:215], v[28:31]
	v_mfma_f32_16x16x32_bf16 v[24:27], v[92:95], v[212:215], v[24:27]
	v_mfma_f32_16x16x32_bf16 v[12:15], v[84:87], v[220:223], v[12:15]
	v_mfma_f32_16x16x32_bf16 v[8:11], v[92:95], v[220:223], v[8:11]
	v_mfma_f32_16x16x32_bf16 v[52:55], v[160:163], v[188:191], v[52:55]
	v_mfma_f32_16x16x32_bf16 v[48:51], v[180:183], v[188:191], v[48:51]
	v_mfma_f32_16x16x32_bf16 v[36:39], v[160:163], v[200:203], v[36:39]
	v_mfma_f32_16x16x32_bf16 v[32:35], v[180:183], v[200:203], v[32:35]
	v_mfma_f32_16x16x32_bf16 v[20:23], v[160:163], v[208:211], v[20:23]
	v_mfma_f32_16x16x32_bf16 v[16:19], v[180:183], v[208:211], v[16:19]
	v_mfma_f32_16x16x32_bf16 v[4:7], v[160:163], v[216:219], v[4:7]
	v_mfma_f32_16x16x32_bf16 v[0:3], v[180:183], v[216:219], v[0:3]
	v_mfma_f32_16x16x32_bf16 v[52:55], v[176:179], v[192:195], v[52:55]
	v_mfma_f32_16x16x32_bf16 v[48:51], v[184:187], v[192:195], v[48:51]
	v_mfma_f32_16x16x32_bf16 v[36:39], v[176:179], v[204:207], v[36:39]
	v_mfma_f32_16x16x32_bf16 v[32:35], v[184:187], v[204:207], v[32:35]
	v_mfma_f32_16x16x32_bf16 v[20:23], v[176:179], v[212:215], v[20:23]
	v_mfma_f32_16x16x32_bf16 v[16:19], v[184:187], v[212:215], v[16:19]
	v_mfma_f32_16x16x32_bf16 v[4:7], v[176:179], v[220:223], v[4:7]
	v_mfma_f32_16x16x32_bf16 v[0:3], v[184:187], v[220:223], v[0:3]
	s_barrier
	s_add_i32 s63, s63, 2
	s_add_u32 s61, s61, 0x100
	s_addc_u32 s62, s62, 0
	s_cmp_gt_u32 s63, 41
	s_mov_b64 s[26:27], s[28:29]
	s_cbranch_scc0 .LBB0_1081
	s_setprio 0
	s_and_b64 vcc, exec, s[20:21]
	s_cbranch_vccnz .LBB0_1085
	s_andn2_b64 vcc, exec, s[22:23]
	s_cbranch_vccz .LBB0_1086
